# rwkv prep: operand records staged in LDS and written as whole 896-byte records per head (no load hoisting)
# speedup vs baseline: 1.0331x; 1.0130x over previous
; __device__ __forceinline__ unsigned cvt_pk_bf16(float lo, float hi) { const f32x2 v = {lo, hi}; return __builtin_bit_cast(unsigned, __builtin_convertvector(v, bf16x2_t)); }
; __device__ __forceinline__ float bflo(unsigned u) { return __uint_as_float(u << 16); }
; __device__ __forceinline__ float bfhi(unsigned u) { return __uint_as_float(u & 0xffff0000u); }
; __device__ __forceinline__ void rwkv_prep_item(const Params& p, const Lt& lt, int l, int item) {
;     const int tid = lt.tid, lane = tid & 63, w = __builtin_amdgcn_readfirstlane(tid >> 6), qi = lane & 15, quad = lane >> 4;
;     const int t = item * 32 + (w >> 2) * 16 + qi, hg = w & 3;
;     const bf16_t* P = (const bf16_t*)(p.ws + WS_P);
;     const bf16_t* pt = P + (size_t)t * INC;
;     const bf16_t* pp = P + (size_t)(t > 0 ? t - 1 : 0) * INC;
;     const float pm = t > 0 ? 1.f : 0.f;
;     const float* mu = p.in[3] + l * 2560;
;     const bf16_t* lora = (const bf16_t*)(p.ws + WS_LORA + l * SZ_LORA);
;     const bf16_t* decT = lora; const bf16_t* aT = lora + 49152; const bf16_t* gT = lora + 98304;
;     bf16x8 fw[2], fa[2], fg[4];
; #pragma unroll
;     for (int ks = 0; ks < 8; ++ks) {
;         const int col = COL_XW + ks * 32 + quad * 8;
;         const u32x4 c4 = *(const u32x4*)(pt + col), q4 = *(const u32x4*)(pp + col);
;         const f32x4 m0 = *(const f32x4*)(mu + col), m1 = *(const f32x4*)(mu + col + 4);
;         float v[8];
; #pragma unroll
;         for (int i = 0; i < 4; ++i) {
;             const float c0 = bflo(c4[i]), c1 = bfhi(c4[i]), p0 = bflo(q4[i]) * pm, p1 = bfhi(q4[i]) * pm;
;             const float mu0 = (i < 2) ? m0[2 * i] : m1[2 * i - 4], mu1 = (i < 2) ? m0[2 * i + 1] : m1[2 * i - 3];
;             v[2 * i] = c0 + (p0 - c0) * mu0; v[2 * i + 1] = c1 + (p1 - c1) * mu1;
;         }
;         if (ks < 2) {
; #pragma unroll
;             for (int i = 0; i < 8; ++i) v[i] = tanhf_(v[i]);
;         } else if (ks >= 4) {
; #pragma unroll
;             for (int i = 0; i < 8; ++i) v[i] = sigmoidf_(v[i]);
;         }
;         u32x4 pk; pk.x = cvt_pk_bf16(v[0], v[1]); pk.y = cvt_pk_bf16(v[2], v[3]); pk.z = cvt_pk_bf16(v[4], v[5]); pk.w = cvt_pk_bf16(v[6], v[7]);
;         const bf16x8 f = __builtin_bit_cast(bf16x8, pk);
;         if (ks < 2) fw[ks] = f; else if (ks < 4) fa[ks - 2] = f; else fg[ks - 4] = f;
;     }
.LBB0_343:
	s_and_b32 s0, s54, 0xfe
	s_ashr_i32 s1, s55, 7
	s_add_i32 s4, s0, s1
	v_and_b32_e32 v210, 63, v245
	v_lshrrev_b32_e32 v211, 6, v245
	v_and_b32_e32 v212, 15, v245
	v_mul_u32_u24_e32 v213, 0x3900, v211
	v_lshl_add_u32 v226, v210, 4, v213
	v_lshrrev_b32_e32 v214, 2, v211
	v_lshlrev_b32_e32 v214, 4, v214
	s_lshl_b32 s98, s4, 5
	v_add_u32_e32 v214, s98, v214
	v_and_b32_e32 v215, 3, v211
	v_mul_u32_u24_e32 v215, 0xa80, v215
	s_movk_i32 s98, 0x2a00
	v_mul_lo_u32 v216, v214, s98
	v_add_u32_e32 v216, v216, v215
	v_lshl_add_u32 v218, v210, 4, v216
	v_mov_b32_e32 v219, 0
	v_readlane_b32 s98, v253, 63
	v_readlane_b32 s99, v254, 0
	s_add_u32 s98, s98, 0x23b00000
	s_addc_u32 s99, s99, 0
	v_lshl_add_u64 v[234:235], s[98:99], 0, v[218:219]
	v_mul_u32_u24_e32 v217, 0x2670, v212
	v_add_u32_e32 v217, v217, v216
	v_sub_u32_e32 v217, v217, v213
	v_add_u32_e32 v230, s98, v217
	v_add_u32_e32 v231, 0x380, v230
	v_add_u32_e32 v232, 0x700, v230
	v_readlane_b32 s0, v253, 52
	v_readlane_b32 s1, v253, 53
	v_mov_b32_e32 v0, v245
	s_and_b64 s[0:1], s[0:1], exec
	s_cselect_b32 s1, s4, s55
	v_readfirstlane_b32 s0, v0
	s_ashr_i32 s4, s0, 4
	v_bfe_u32 v1, v0, 4, 2
	s_lshl_b32 s1, s1, 5
	s_and_b32 s4, s4, -16
	v_and_b32_e32 v180, 15, v0
	s_add_i32 s4, s4, s1
	v_lshlrev_b32_e32 v44, 3, v1
	v_or_b32_e32 v84, s4, v180
	s_waitcnt vmcnt(63) lgkmcnt(0)
	v_mov_b64_e32 v[4:5], s[6:7]
	v_or_b32_e32 v0, 0x900, v44
	v_mad_i64_i32 v[114:115], s[4:5], v84, s76, v[4:5]
	v_lshlrev_b32_e32 v2, 1, v0
	v_lshl_add_u64 v[6:7], v[114:115], 0, v[2:3]
	global_load_dwordx4 v[8:11], v[6:7], off
	v_max_i32_e32 v6, 1, v84
	v_add_u32_e32 v6, -1, v6
	v_mad_u64_u32 v[110:111], s[4:5], v6, s76, v[4:5]
	v_lshl_add_u64 v[4:5], v[110:111], 0, v[2:3]
	global_load_dwordx4 v[12:15], v[4:5], off
	v_lshlrev_b32_e32 v0, 2, v0
	global_load_dwordx4 v[16:19], v0, s[8:9]
	global_load_dwordx4 v[20:23], v0, s[8:9] offset:16
	v_or_b32_e32 v2, 0x920, v44
	v_lshlrev_b32_e32 v0, 2, v2
	v_lshlrev_b32_e32 v2, 1, v2
	v_lshl_add_u64 v[28:29], v[114:115], 0, v[2:3]
	v_lshl_add_u64 v[32:33], v[110:111], 0, v[2:3]
	global_load_dwordx4 v[4:7], v0, s[8:9] offset:16
	global_load_dwordx4 v[24:27], v0, s[8:9]
	s_nop 0
	global_load_dwordx4 v[28:31], v[28:29], off
	s_nop 0
	global_load_dwordx4 v[32:35], v[32:33], off
	v_cmp_lt_i32_e32 vcc, 0, v84
	v_or_b32_e32 v59, 0x980, v44
	s_bfe_u32 s4, s0, 0x20006
	v_cndmask_b32_e64 v0, 0, 1.0, vcc
	s_mul_i32 s5, s4, 0xc0
	v_lshlrev_b32_e32 v112, 4, v1
	v_mov_b32_e32 v113, v3
	v_lshl_add_u64 v[88:89], s[28:29], 0, v[112:113]
	v_lshl_add_u64 v[92:93], s[30:31], 0, v[112:113]
	v_lshlrev_b32_e32 v181, 2, v1
	s_mul_i32 s10, s4, 0xa80
	v_lshl_add_u64 v[94:95], s[34:35], 0, v[112:113]
	s_mov_b32 s57, 0x3f317217
	s_mov_b32 s58, 0x7f800000
	s_mul_i32 s56, s4, 3
	s_waitcnt vmcnt(7)
	v_lshlrev_b32_e32 v2, 16, v8
	v_and_b32_e32 v8, 0xffff0000, v8
	v_lshlrev_b32_e32 v38, 16, v11
	v_and_b32_e32 v39, 0xffff0000, v11
	v_lshlrev_b32_e32 v36, 16, v9
	v_and_b32_e32 v9, 0xffff0000, v9
	s_waitcnt vmcnt(6)
	v_lshlrev_b32_e32 v11, 16, v12
	v_and_b32_e32 v12, 0xffff0000, v12
	v_lshlrev_b32_e32 v40, 16, v13
	v_and_b32_e32 v13, 0xffff0000, v13
	v_fma_f32 v12, v0, v12, -v8
	v_fma_f32 v11, v0, v11, -v2
	v_fma_f32 v13, v0, v13, -v9
	s_waitcnt vmcnt(5)
	v_fmac_f32_e32 v8, v17, v12
	v_fmac_f32_e32 v2, v16, v11
	v_fmac_f32_e32 v9, v19, v13
	v_add_f32_e32 v8, v8, v8
	v_add_f32_e32 v2, v2, v2
	v_add_f32_e32 v9, v9, v9
	v_mul_f32_e32 v8, 0x3fb8aa3b, v8
	v_mul_f32_e32 v2, 0x3fb8aa3b, v2
	v_mul_f32_e32 v9, 0x3fb8aa3b, v9
	v_exp_f32_e32 v8, v8
	v_exp_f32_e32 v2, v2
	v_exp_f32_e32 v9, v9
	v_lshlrev_b32_e32 v37, 16, v10
	v_and_b32_e32 v10, 0xffff0000, v10
	v_lshlrev_b32_e32 v41, 16, v14
	v_and_b32_e32 v14, 0xffff0000, v14
	v_lshlrev_b32_e32 v42, 16, v15
	v_and_b32_e32 v15, 0xffff0000, v15
	v_fma_f32 v40, v0, v40, -v36
	v_fma_f32 v14, v0, v14, -v10
	v_fma_f32 v42, v0, v42, -v38
	v_add_f32_e32 v13, 1.0, v8
	v_fmac_f32_e32 v36, v18, v40
	s_waitcnt vmcnt(4)
	v_fmac_f32_e32 v10, v21, v14
	v_fmac_f32_e32 v38, v22, v42
	v_add_f32_e32 v2, 1.0, v2
	v_add_f32_e32 v14, 1.0, v9
	v_rcp_f32_e32 v9, v13
	v_fma_f32 v13, v0, v15, -v39
	v_add_f32_e32 v11, v36, v36
	v_rcp_f32_e32 v8, v2
	v_add_f32_e32 v2, v38, v38
	v_fmac_f32_e32 v39, v23, v13
	v_add_f32_e32 v10, v10, v10
	v_mul_f32_e32 v11, 0x3fb8aa3b, v11
	v_mul_f32_e32 v2, 0x3fb8aa3b, v2
	v_add_f32_e32 v13, v39, v39
	v_mul_f32_e32 v10, 0x3fb8aa3b, v10
	v_exp_f32_e32 v11, v11
	v_exp_f32_e32 v2, v2
	v_mul_f32_e32 v13, 0x3fb8aa3b, v13
	v_exp_f32_e32 v10, v10
	v_exp_f32_e32 v15, v13
	v_fma_f32 v41, v0, v41, -v37
	v_add_f32_e32 v11, 1.0, v11
	v_add_f32_e32 v2, 1.0, v2
	v_fmac_f32_e32 v37, v20, v41
	v_add_f32_e32 v16, 1.0, v10
	v_rcp_f32_e32 v10, v11
	v_rcp_f32_e32 v11, v14
	v_rcp_f32_e32 v14, v2
	v_add_f32_e32 v2, 1.0, v15
	v_add_f32_e32 v12, v37, v37
	v_rcp_f32_e32 v15, v2
	v_pk_fma_f32 v[8:9], v[8:9], 2.0, 1.0 op_sel_hi:[1,0,0] neg_lo:[1,0,0] neg_hi:[1,0,0]
	s_waitcnt vmcnt(1)
	v_lshlrev_b32_e32 v40, 16, v28
	s_waitcnt vmcnt(0)
; __device__ __forceinline__ unsigned cvt_pk_bf16(float lo, float hi) { const f32x2 v = {lo, hi}; return __builtin_bit_cast(unsigned, __builtin_convertvector(v, bf16x2_t)); }
; __device__ __forceinline__ float bflo(unsigned u) { return __uint_as_float(u << 16); }
; __device__ __forceinline__ float bfhi(unsigned u) { return __uint_as_float(u & 0xffff0000u); }
; __device__ __forceinline__ float sigmoidf_(float x) { return __builtin_amdgcn_rcpf(1.0f + __expf(-x)); }
; __device__ __forceinline__ float tanhf_(float x) { return 1.0f - 2.0f * __builtin_amdgcn_rcpf(1.0f + __expf(2.0f * x)); }
; __device__ __forceinline__ void rwkv_prep_item(const Params& p, const Lt& lt, int l, int item) {
;     ...
;     for (int ks = 0; ks < 8; ++ks) {
;         const int col = COL_XW + ks * 32 + quad * 8;
;         const u32x4 c4 = *(const u32x4*)(pt + col), q4 = *(const u32x4*)(pp + col);
;         const f32x4 m0 = *(const f32x4*)(mu + col), m1 = *(const f32x4*)(mu + col + 4);
;         float v[8];
; #pragma unroll
;         for (int i = 0; i < 4; ++i) {
;             const float c0 = bflo(c4[i]), c1 = bfhi(c4[i]), p0 = bflo(q4[i]) * pm, p1 = bfhi(q4[i]) * pm;
;             const float mu0 = (i < 2) ? m0[2 * i] : m1[2 * i - 4], mu1 = (i < 2) ? m0[2 * i + 1] : m1[2 * i - 3];
;             v[2 * i] = c0 + (p0 - c0) * mu0; v[2 * i + 1] = c1 + (p1 - c1) * mu1;
;         }
;         if (ks < 2) {
; #pragma unroll
;             for (int i = 0; i < 8; ++i) v[i] = tanhf_(v[i]);
;         } else if (ks >= 4) {
; #pragma unroll
;             for (int i = 0; i < 8; ++i) v[i] = sigmoidf_(v[i]);
;         }
;         u32x4 pk; pk.x = cvt_pk_bf16(v[0], v[1]); pk.y = cvt_pk_bf16(v[2], v[3]); pk.z = cvt_pk_bf16(v[4], v[5]); pk.w = cvt_pk_bf16(v[6], v[7]);
;         const bf16x8 f = __builtin_bit_cast(bf16x8, pk);
;         if (ks < 2) fw[ks] = f; else if (ks < 4) fa[ks - 2] = f; else fg[ks - 4] = f;
;     }
	v_lshlrev_b32_e32 v2, 16, v32
	v_mul_f32_e32 v12, 0x3fb8aa3b, v12
	v_cvt_pk_bf16_f32 v20, v8, v9
	v_and_b32_e32 v28, 0xffff0000, v28
	v_and_b32_e32 v8, 0xffff0000, v32
	v_fma_f32 v2, v0, v2, -v40
	v_exp_f32_e32 v12, v12
	v_fmac_f32_e32 v40, v24, v2
	v_fma_f32 v2, v0, v8, -v28
	v_fmac_f32_e32 v28, v25, v2
	v_lshlrev_b32_e32 v25, 16, v29
	v_lshlrev_b32_e32 v2, 16, v33
	v_and_b32_e32 v29, 0xffff0000, v29
	v_and_b32_e32 v8, 0xffff0000, v33
	v_fma_f32 v2, v0, v2, -v25
	v_fmac_f32_e32 v25, v26, v2
	v_fma_f32 v2, v0, v8, -v29
	v_add_f32_e32 v12, 1.0, v12
	v_fmac_f32_e32 v29, v27, v2
	v_lshlrev_b32_e32 v27, 16, v30
	v_lshlrev_b32_e32 v2, 16, v34
	v_rcp_f32_e32 v12, v12
	v_rcp_f32_e32 v13, v16
	v_and_b32_e32 v30, 0xffff0000, v30
	v_and_b32_e32 v8, 0xffff0000, v34
	v_fma_f32 v2, v0, v2, -v27
	v_fmac_f32_e32 v27, v4, v2
	v_fma_f32 v2, v0, v8, -v30
	v_or_b32_e32 v16, 0x940, v44
	v_fmac_f32_e32 v30, v5, v2
	v_lshlrev_b32_e32 v2, 1, v16
	v_pk_fma_f32 v[10:11], v[10:11], 2.0, 1.0 op_sel_hi:[1,0,0] neg_lo:[1,0,0] neg_hi:[1,0,0]
	v_lshl_add_u64 v[4:5], v[114:115], 0, v[2:3]
	v_pk_fma_f32 v[12:13], v[12:13], 2.0, 1.0 op_sel_hi:[1,0,0] neg_lo:[1,0,0] neg_hi:[1,0,0]
	v_pk_fma_f32 v[14:15], v[14:15], 2.0, 1.0 op_sel_hi:[1,0,0] neg_lo:[1,0,0] neg_hi:[1,0,0]
	v_cvt_pk_bf16_f32 v21, v10, v11
	global_load_dwordx4 v[8:11], v[4:5], off
	v_lshl_add_u64 v[4:5], v[110:111], 0, v[2:3]
	v_lshlrev_b32_e32 v2, 2, v16
	v_cvt_pk_bf16_f32 v22, v12, v13
	v_cvt_pk_bf16_f32 v23, v14, v15
	global_load_dwordx4 v[12:15], v[4:5], off
	global_load_dwordx4 v[16:19], v2, s[8:9] offset:16
	global_load_dwordx4 v[36:39], v2, s[8:9]
	v_add_f32_e32 v2, v40, v40
	v_mul_f32_e32 v2, 0x3fb8aa3b, v2
	v_exp_f32_e32 v2, v2
	v_add_f32_e32 v4, v28, v28
	v_mul_f32_e32 v4, 0x3fb8aa3b, v4
	v_exp_f32_e32 v4, v4
	v_add_f32_e32 v2, 1.0, v2
	v_rcp_f32_e32 v24, v2
	v_add_f32_e32 v2, v25, v25
	v_mul_f32_e32 v2, 0x3fb8aa3b, v2
	v_exp_f32_e32 v28, v2
	v_add_f32_e32 v2, v29, v29
	v_mul_f32_e32 v2, 0x3fb8aa3b, v2
	v_or_b32_e32 v25, 0x960, v44
	v_exp_f32_e32 v29, v2
	v_lshlrev_b32_e32 v2, 1, v25
	v_add_f32_e32 v26, 1.0, v4
	v_lshl_add_u64 v[4:5], v[114:115], 0, v[2:3]
	v_lshlrev_b32_e32 v54, 16, v35
	v_and_b32_e32 v55, 0xffff0000, v35
	global_load_dwordx4 v[32:35], v[4:5], off
	v_lshl_add_u64 v[4:5], v[110:111], 0, v[2:3]
	global_load_dwordx4 v[40:43], v[4:5], off
	v_lshlrev_b32_e32 v2, 2, v25
	global_load_dwordx4 v[46:49], v2, s[8:9] offset:16
	global_load_dwordx4 v[50:53], v2, s[8:9]
	v_add_f32_e32 v4, v27, v27
	v_mul_f32_e32 v4, 0x3fb8aa3b, v4
	v_add_f32_e32 v5, v30, v30
	v_exp_f32_e32 v4, v4
	v_mul_f32_e32 v5, 0x3fb8aa3b, v5
	v_exp_f32_e32 v5, v5
	v_add_f32_e32 v2, 1.0, v28
	v_rcp_f32_e32 v25, v26
	v_rcp_f32_e32 v26, v2
	v_add_f32_e32 v2, 1.0, v29
	v_rcp_f32_e32 v27, v2
	v_add_f32_e32 v2, 1.0, v4
	v_lshlrev_b32_e32 v45, 16, v31
	v_rcp_f32_e32 v28, v2
	v_add_f32_e32 v2, 1.0, v5
	v_rcp_f32_e32 v29, v2
	v_fma_f32 v2, v0, v54, -v45
	v_fmac_f32_e32 v45, v6, v2
	v_add_f32_e32 v2, v45, v45
	v_and_b32_e32 v31, 0xffff0000, v31
	v_mul_f32_e32 v2, 0x3fb8aa3b, v2
	v_exp_f32_e32 v45, v2
	v_fma_f32 v2, v0, v55, -v31
	v_fmac_f32_e32 v31, v7, v2
	v_add_f32_e32 v2, v31, v31
	v_mul_f32_e32 v2, 0x3fb8aa3b, v2
	v_exp_f32_e32 v58, v2
	v_lshlrev_b32_e32 v2, 1, v59
	v_lshl_add_u64 v[4:5], v[114:115], 0, v[2:3]
	v_lshl_add_u64 v[30:31], v[110:111], 0, v[2:3]
	global_load_dwordx4 v[4:7], v[4:5], off
	v_add_f32_e32 v2, 1.0, v45
	global_load_dwordx4 v[54:57], v[30:31], off
	v_lshlrev_b32_e32 v31, 2, v59
	v_rcp_f32_e32 v30, v2
	v_add_f32_e32 v2, 1.0, v58
	global_load_dwordx4 v[58:61], v31, s[8:9] offset:16
	global_load_dwordx4 v[62:65], v31, s[8:9]
	v_rcp_f32_e32 v31, v2
	v_pk_fma_f32 v[24:25], v[24:25], 2.0, 1.0 op_sel_hi:[1,0,0] neg_lo:[1,0,0] neg_hi:[1,0,0]
	v_pk_fma_f32 v[26:27], v[26:27], 2.0, 1.0 op_sel_hi:[1,0,0] neg_lo:[1,0,0] neg_hi:[1,0,0]
	v_pk_fma_f32 v[28:29], v[28:29], 2.0, 1.0 op_sel_hi:[1,0,0] neg_lo:[1,0,0] neg_hi:[1,0,0]
	v_pk_fma_f32 v[30:31], v[30:31], 2.0, 1.0 op_sel_hi:[1,0,0] neg_lo:[1,0,0] neg_hi:[1,0,0]
	v_cvt_pk_bf16_f32 v24, v24, v25
	v_cvt_pk_bf16_f32 v25, v26, v27
	v_cvt_pk_bf16_f32 v26, v28, v29
	v_cvt_pk_bf16_f32 v27, v30, v31
	s_waitcnt vmcnt(11)
	v_lshlrev_b32_e32 v28, 16, v8
	v_and_b32_e32 v29, 0xffff0000, v8
	v_lshlrev_b32_e32 v8, 16, v9
	v_and_b32_e32 v9, 0xffff0000, v9
	s_waitcnt vmcnt(10)
	v_lshlrev_b32_e32 v30, 16, v12
	v_and_b32_e32 v31, 0xffff0000, v12
	v_lshlrev_b32_e32 v12, 16, v13
	v_and_b32_e32 v13, 0xffff0000, v13
	v_pk_fma_f32 v[30:31], v[0:1], v[30:31], v[28:29] op_sel_hi:[0,1,1] neg_lo:[0,0,1] neg_hi:[0,0,1]
	v_pk_fma_f32 v[12:13], v[0:1], v[12:13], v[8:9] op_sel_hi:[0,1,1] neg_lo:[0,0,1] neg_hi:[0,0,1]
	s_waitcnt vmcnt(8)
	v_pk_fma_f32 v[28:29], v[36:37], v[30:31], v[28:29]
	v_pk_fma_f32 v[8:9], v[38:39], v[12:13], v[8:9]
	v_lshlrev_b32_e32 v12, 16, v10
	v_and_b32_e32 v13, 0xffff0000, v10
	v_lshlrev_b32_e32 v30, 16, v14
	v_and_b32_e32 v31, 0xffff0000, v14
	v_lshlrev_b32_e32 v10, 16, v11
	v_and_b32_e32 v11, 0xffff0000, v11
	v_lshlrev_b32_e32 v14, 16, v15
	v_and_b32_e32 v15, 0xffff0000, v15
	v_pk_fma_f32 v[14:15], v[0:1], v[14:15], v[10:11] op_sel_hi:[0,1,1] neg_lo:[0,0,1] neg_hi:[0,0,1]
	v_pk_fma_f32 v[30:31], v[0:1], v[30:31], v[12:13] op_sel_hi:[0,1,1] neg_lo:[0,0,1] neg_hi:[0,0,1]
	v_pk_fma_f32 v[10:11], v[18:19], v[14:15], v[10:11]
	v_pk_fma_f32 v[12:13], v[16:17], v[30:31], v[12:13]
	v_cvt_pk_bf16_f32 v28, v28, v29
	v_cvt_pk_bf16_f32 v29, v8, v9
	v_cvt_pk_bf16_f32 v31, v10, v11
	s_waitcnt vmcnt(7)
	v_lshlrev_b32_e32 v8, 16, v32
	v_and_b32_e32 v9, 0xffff0000, v32
	s_waitcnt vmcnt(6)
	v_lshlrev_b32_e32 v10, 16, v40
	v_and_b32_e32 v11, 0xffff0000, v40
	v_pk_fma_f32 v[10:11], v[0:1], v[10:11], v[8:9] op_sel_hi:[0,1,1] neg_lo:[0,0,1] neg_hi:[0,0,1]
	s_waitcnt vmcnt(4)
; __device__ __forceinline__ unsigned cvt_pk_bf16(float lo, float hi) { const f32x2 v = {lo, hi}; return __builtin_bit_cast(unsigned, __builtin_convertvector(v, bf16x2_t)); }
; __device__ __forceinline__ float bflo(unsigned u) { return __uint_as_float(u << 16); }
; __device__ __forceinline__ float bfhi(unsigned u) { return __uint_as_float(u & 0xffff0000u); }
; __device__ __forceinline__ float sigmoidf_(float x) { return __builtin_amdgcn_rcpf(1.0f + __expf(-x)); }
; __device__ __forceinline__ float tanhf_(float x) { return 1.0f - 2.0f * __builtin_amdgcn_rcpf(1.0f + __expf(2.0f * x)); }
; __device__ __forceinline__ void rwkv_prep_item(const Params& p, const Lt& lt, int l, int item) {
;     ...
;     for (int ks = 0; ks < 8; ++ks) {
;         const int col = COL_XW + ks * 32 + quad * 8;
;         const u32x4 c4 = *(const u32x4*)(pt + col), q4 = *(const u32x4*)(pp + col);
;         const f32x4 m0 = *(const f32x4*)(mu + col), m1 = *(const f32x4*)(mu + col + 4);
;         float v[8];
; #pragma unroll
;         for (int i = 0; i < 4; ++i) {
;             const float c0 = bflo(c4[i]), c1 = bfhi(c4[i]), p0 = bflo(q4[i]) * pm, p1 = bfhi(q4[i]) * pm;
;             const float mu0 = (i < 2) ? m0[2 * i] : m1[2 * i - 4], mu1 = (i < 2) ? m0[2 * i + 1] : m1[2 * i - 3];
;             v[2 * i] = c0 + (p0 - c0) * mu0; v[2 * i + 1] = c1 + (p1 - c1) * mu1;
;         }
;         if (ks < 2) {
; #pragma unroll
;             for (int i = 0; i < 8; ++i) v[i] = tanhf_(v[i]);
;         } else if (ks >= 4) {
; #pragma unroll
;             for (int i = 0; i < 8; ++i) v[i] = sigmoidf_(v[i]);
;         }
;         u32x4 pk; pk.x = cvt_pk_bf16(v[0], v[1]); pk.y = cvt_pk_bf16(v[2], v[3]); pk.z = cvt_pk_bf16(v[4], v[5]); pk.w = cvt_pk_bf16(v[6], v[7]);
;         const bf16x8 f = __builtin_bit_cast(bf16x8, pk);
;         if (ks < 2) fw[ks] = f; else if (ks < 4) fa[ks - 2] = f; else fg[ks - 4] = f;
;     }
	v_pk_fma_f32 v[16:17], v[50:51], v[10:11], v[8:9]
	v_lshlrev_b32_e32 v8, 16, v33
	v_and_b32_e32 v9, 0xffff0000, v33
	v_lshlrev_b32_e32 v10, 16, v41
	v_and_b32_e32 v11, 0xffff0000, v41
	v_pk_fma_f32 v[10:11], v[0:1], v[10:11], v[8:9] op_sel_hi:[0,1,1] neg_lo:[0,0,1] neg_hi:[0,0,1]
	v_pk_fma_f32 v[18:19], v[52:53], v[10:11], v[8:9]
	v_lshlrev_b32_e32 v8, 16, v34
	v_and_b32_e32 v9, 0xffff0000, v34
	v_lshlrev_b32_e32 v10, 16, v42
	v_and_b32_e32 v11, 0xffff0000, v42
	v_or_b32_e32 v40, 0x9a0, v44
	v_pk_fma_f32 v[10:11], v[0:1], v[10:11], v[8:9] op_sel_hi:[0,1,1] neg_lo:[0,0,1] neg_hi:[0,0,1]
	v_lshlrev_b32_e32 v2, 1, v40
	v_cvt_pk_bf16_f32 v30, v12, v13
	v_pk_fma_f32 v[36:37], v[46:47], v[10:11], v[8:9]
	v_lshlrev_b32_e32 v32, 16, v35
	v_and_b32_e32 v33, 0xffff0000, v35
	v_lshlrev_b32_e32 v34, 16, v43
	v_and_b32_e32 v35, 0xffff0000, v43
	v_lshl_add_u64 v[8:9], v[114:115], 0, v[2:3]
	v_lshl_add_u64 v[12:13], v[110:111], 0, v[2:3]
	global_load_dwordx4 v[8:11], v[8:9], off
	v_pk_fma_f32 v[34:35], v[0:1], v[34:35], v[32:33] op_sel_hi:[0,1,1] neg_lo:[0,0,1] neg_hi:[0,0,1]
	global_load_dwordx4 v[12:15], v[12:13], off
	v_pk_fma_f32 v[38:39], v[48:49], v[34:35], v[32:33]
	v_cvt_pk_bf16_f32 v34, v36, v37
	v_lshlrev_b32_e32 v36, 2, v40
	v_cvt_pk_bf16_f32 v32, v16, v17
	v_cvt_pk_bf16_f32 v33, v18, v19
	v_cvt_pk_bf16_f32 v35, v38, v39
	global_load_dwordx4 v[16:19], v36, s[8:9] offset:16
	s_nop 0
	global_load_dwordx4 v[36:39], v36, s[8:9]
	s_waitcnt vmcnt(7)
	v_lshlrev_b32_e32 v2, 16, v4
	v_and_b32_e32 v4, 0xffff0000, v4
	s_waitcnt vmcnt(6)
	v_lshlrev_b32_e32 v41, 16, v54
	v_and_b32_e32 v40, 0xffff0000, v54
	v_fma_f32 v41, v0, v41, -v2
	v_fma_f32 v40, v0, v40, -v4
	s_waitcnt vmcnt(4)
	v_fmac_f32_e32 v2, v62, v41
	v_fmac_f32_e32 v4, v63, v40
	v_lshlrev_b32_e32 v40, 16, v5
	v_lshlrev_b32_e32 v41, 16, v55
	v_and_b32_e32 v5, 0xffff0000, v5
	v_and_b32_e32 v42, 0xffff0000, v55
	v_fma_f32 v41, v0, v41, -v40
	v_fmac_f32_e32 v40, v64, v41
	v_fma_f32 v41, v0, v42, -v5
	v_fmac_f32_e32 v5, v65, v41
	v_lshlrev_b32_e32 v41, 16, v6
	v_lshlrev_b32_e32 v42, 16, v56
	v_and_b32_e32 v6, 0xffff0000, v6
	v_and_b32_e32 v43, 0xffff0000, v56
	v_fma_f32 v42, v0, v42, -v41
	v_fmac_f32_e32 v41, v58, v42
	v_fma_f32 v42, v0, v43, -v6
	v_fmac_f32_e32 v6, v59, v42
	v_lshlrev_b32_e32 v42, 16, v7
	v_lshlrev_b32_e32 v43, 16, v57
	v_and_b32_e32 v7, 0xffff0000, v7
	v_and_b32_e32 v45, 0xffff0000, v57
	v_fma_f32 v43, v0, v43, -v42
	v_mul_f32_e32 v2, 0xbfb8aa3b, v2
	v_mul_f32_e32 v4, 0xbfb8aa3b, v4
	v_fmac_f32_e32 v42, v60, v43
	v_fma_f32 v43, v0, v45, -v7
	v_exp_f32_e32 v2, v2
	v_exp_f32_e32 v4, v4
	v_mul_f32_e32 v40, 0xbfb8aa3b, v40
	v_mul_f32_e32 v5, 0xbfb8aa3b, v5
	v_mul_f32_e32 v41, 0xbfb8aa3b, v41
	v_mul_f32_e32 v6, 0xbfb8aa3b, v6
	v_fmac_f32_e32 v7, v61, v43
	v_exp_f32_e32 v40, v40
	v_exp_f32_e32 v5, v5
	v_exp_f32_e32 v41, v41
	v_exp_f32_e32 v6, v6
	v_mul_f32_e32 v42, 0xbfb8aa3b, v42
	v_mul_f32_e32 v7, 0xbfb8aa3b, v7
	v_exp_f32_e32 v42, v42
	v_exp_f32_e32 v7, v7
	v_add_f32_e32 v2, 1.0, v2
	v_add_f32_e32 v4, 1.0, v4
	v_rcp_f32_e32 v2, v2
	v_rcp_f32_e32 v4, v4
	v_add_f32_e32 v40, 1.0, v40
	v_add_f32_e32 v5, 1.0, v5
	v_add_f32_e32 v41, 1.0, v41
	v_add_f32_e32 v6, 1.0, v6
	v_rcp_f32_e32 v40, v40
	v_rcp_f32_e32 v5, v5
	v_rcp_f32_e32 v41, v41
	v_rcp_f32_e32 v6, v6
	v_add_f32_e32 v42, 1.0, v42
	v_add_f32_e32 v7, 1.0, v7
	v_rcp_f32_e32 v42, v42
	v_rcp_f32_e32 v7, v7
	v_or_b32_e32 v45, 0x9c0, v44
	v_cvt_pk_bf16_f32 v4, v2, v4
	v_lshlrev_b32_e32 v2, 1, v45
	v_cvt_pk_bf16_f32 v5, v40, v5
	v_cvt_pk_bf16_f32 v6, v41, v6
	v_lshl_add_u64 v[40:41], v[114:115], 0, v[2:3]
	global_load_dwordx4 v[46:49], v[40:41], off
	v_lshl_add_u64 v[40:41], v[110:111], 0, v[2:3]
	v_lshlrev_b32_e32 v2, 2, v45
	v_cvt_pk_bf16_f32 v7, v42, v7
	s_waitcnt vmcnt(4)
	v_lshlrev_b32_e32 v42, 16, v8
	v_and_b32_e32 v8, 0xffff0000, v8
	s_waitcnt vmcnt(3)
	v_lshlrev_b32_e32 v43, 16, v12
	global_load_dwordx4 v[50:53], v[40:41], off
	global_load_dwordx4 v[54:57], v2, s[8:9] offset:16
	global_load_dwordx4 v[58:61], v2, s[8:9]
	v_and_b32_e32 v2, 0xffff0000, v12
	v_fma_f32 v12, v0, v43, -v42
	v_fma_f32 v2, v0, v2, -v8
	s_waitcnt vmcnt(4)
	v_fmac_f32_e32 v42, v36, v12
	v_fmac_f32_e32 v8, v37, v2
	v_lshlrev_b32_e32 v2, 16, v9
	v_lshlrev_b32_e32 v12, 16, v13
	v_and_b32_e32 v9, 0xffff0000, v9
	v_and_b32_e32 v13, 0xffff0000, v13
	v_fma_f32 v12, v0, v12, -v2
	v_fmac_f32_e32 v2, v38, v12
	v_fma_f32 v12, v0, v13, -v9
	v_mul_f32_e32 v8, 0xbfb8aa3b, v8
	v_fmac_f32_e32 v9, v39, v12
	v_lshlrev_b32_e32 v12, 16, v10
	v_lshlrev_b32_e32 v13, 16, v14
	v_exp_f32_e32 v8, v8
	v_and_b32_e32 v10, 0xffff0000, v10
	v_and_b32_e32 v14, 0xffff0000, v14
	v_fma_f32 v13, v0, v13, -v12
	v_fmac_f32_e32 v12, v16, v13
	v_fma_f32 v13, v0, v14, -v10
	v_fmac_f32_e32 v10, v17, v13
	v_lshlrev_b32_e32 v13, 16, v11
	v_lshlrev_b32_e32 v14, 16, v15
	v_and_b32_e32 v11, 0xffff0000, v11
	v_and_b32_e32 v15, 0xffff0000, v15
	v_fma_f32 v14, v0, v14, -v13
	v_mul_f32_e32 v2, 0xbfb8aa3b, v2
	v_add_f32_e32 v8, 1.0, v8
	v_fmac_f32_e32 v13, v18, v14
	v_fma_f32 v14, v0, v15, -v11
	v_exp_f32_e32 v2, v2
	v_rcp_f32_e32 v15, v8
	v_mul_f32_e32 v8, 0xbfb8aa3b, v9
	v_exp_f32_e32 v8, v8
	v_mul_f32_e32 v9, 0xbfb8aa3b, v12
	v_exp_f32_e32 v9, v9
	v_add_f32_e32 v2, 1.0, v2
	v_rcp_f32_e32 v12, v2
	v_add_f32_e32 v2, 1.0, v8
	v_mul_f32_e32 v8, 0xbfb8aa3b, v10
	v_rcp_f32_e32 v45, v2
	v_add_f32_e32 v2, 1.0, v9
	v_exp_f32_e32 v8, v8
	v_mul_f32_e32 v9, 0xbfb8aa3b, v13
	v_mul_f32_e32 v16, 0xbfb8aa3b, v42
	v_exp_f32_e32 v9, v9
	v_exp_f32_e32 v16, v16
	v_rcp_f32_e32 v10, v2
	v_add_f32_e32 v2, 1.0, v8
	v_fmac_f32_e32 v11, v19, v14
	v_rcp_f32_e32 v13, v2
	v_add_f32_e32 v2, 1.0, v9
	v_add_f32_e32 v14, 1.0, v16
	v_rcp_f32_e32 v66, v2
	v_mul_f32_e32 v2, 0xbfb8aa3b, v11
	v_or_b32_e32 v16, 0x9e0, v44
	v_exp_f32_e32 v11, v2
	v_lshlrev_b32_e32 v2, 1, v16
	v_lshl_add_u64 v[8:9], v[114:115], 0, v[2:3]
	global_load_dwordx4 v[36:39], v[8:9], off
	v_lshl_add_u64 v[8:9], v[110:111], 0, v[2:3]
	global_load_dwordx4 v[40:43], v[8:9], off
	v_lshlrev_b32_e32 v2, 2, v16
	global_load_dwordx4 v[16:19], v2, s[8:9] offset:16
	global_load_dwordx4 v[62:65], v2, s[8:9]
	v_add_f32_e32 v2, 1.0, v11
	v_rcp_f32_e32 v2, v2
	v_rcp_f32_e32 v14, v14
	v_cvt_pk_bf16_f32 v10, v10, v13
	v_cvt_pk_bf16_f32 v9, v12, v45
	v_cvt_pk_bf16_f32 v11, v66, v2
	s_waitcnt vmcnt(7)
; __device__ __forceinline__ void rwkv_prep_item(const Params& p, const Lt& lt, int l, int item) {
;     ...
;         if (ks < 2) {
; #pragma unroll
;             for (int i = 0; i < 8; ++i) v[i] = tanhf_(v[i]);
;         } else if (ks >= 4) {
; #pragma unroll
;             for (int i = 0; i < 8; ++i) v[i] = sigmoidf_(v[i]);
;         }
;         u32x4 pk; pk.x = cvt_pk_bf16(v[0], v[1]); pk.y = cvt_pk_bf16(v[2], v[3]); pk.z = cvt_pk_bf16(v[4], v[5]); pk.w = cvt_pk_bf16(v[6], v[7]);
;         const bf16x8 f = __builtin_bit_cast(bf16x8, pk);
;         if (ks < 2) fw[ks] = f; else if (ks < 4) fa[ks - 2] = f; else fg[ks - 4] = f;
;     }
;     unsigned char* opnd = p.ws + WS_OPND; float* gate = (float*)(p.ws + WS_GATE); float* bonus = (float*)(p.ws + WS_BONUS);
;     const float* w0 = p.in[4] + l * RW; const float* a0 = p.in[6] + l * RW; const float* kkp = p.in[9] + l * RW; const float* kap = p.in[10] + l * RW; const float* rkp = p.in[11] + l * RW;
; #pragma unroll
;     for (int hh = 0; hh < 3; ++hh) {
;         const int h = hg * 3 + hh;
;         f32x4 va[4], vkk[4];
;         float nrm = 0.f, bon = 0.f;
;         unsigned char* ob = opnd + (size_t)t * OPTB + h * OPB;
; #pragma unroll
;         for (int ct = 0; ct < 4; ++ct) {
;             const int crow = h * 64 + ct * 16 + qi;
;             f32x4 aw = {0.f, 0.f, 0.f, 0.f}, aa = aw, ag = aw;
; #pragma unroll
;             for (int ks = 0; ks < 2; ++ks) {
;                 aw = __builtin_amdgcn_mfma_f32_16x16x32_bf16(*(const bf16x8*)(decT + crow * 64 + ks * 32 + quad * 8), fw[ks], aw, 0, 0, 0);
;                 aa = __builtin_amdgcn_mfma_f32_16x16x32_bf16(*(const bf16x8*)(aT + crow * 64 + ks * 32 + quad * 8), fa[ks], aa, 0, 0, 0);
;             }
; #pragma unroll
;             for (int ks = 0; ks < 4; ++ks) ag = __builtin_amdgcn_mfma_f32_16x16x32_bf16(*(const bf16x8*)(gT + crow * 128 + ks * 32 + quad * 8), fg[ks], ag, 0, 0, 0);
;             const int c = h * 64 + ct * 16 + quad * 4;
;             const f32x4 mr = *(const f32x4*)(mu + c), mk = *(const f32x4*)(mu + COL_K + c), mv = *(const f32x4*)(mu + COL_V + c);
;             const f32x4 cr = ld_bf4(pt + c), ck = ld_bf4(pt + COL_K + c), cv = ld_bf4(pt + COL_V + c);
;             const f32x4 qr = ld_bf4(pp + c) * pm, qk = ld_bf4(pp + COL_K + c) * pm, qv = ld_bf4(pp + COL_V + c) * pm;
	v_lshlrev_b32_e32 v2, 16, v46
	v_cvt_pk_bf16_f32 v8, v14, v15
	v_and_b32_e32 v12, 0xffff0000, v46
	s_waitcnt vmcnt(6)
	v_lshlrev_b32_e32 v13, 16, v50
	v_and_b32_e32 v14, 0xffff0000, v50
	v_fma_f32 v13, v0, v13, -v2
	s_waitcnt vmcnt(4)
	v_fmac_f32_e32 v2, v58, v13
	v_fma_f32 v13, v0, v14, -v12
	v_fmac_f32_e32 v12, v59, v13
	v_lshlrev_b32_e32 v13, 16, v47
	v_lshlrev_b32_e32 v15, 16, v51
	v_and_b32_e32 v14, 0xffff0000, v47
	v_and_b32_e32 v45, 0xffff0000, v51
	v_fma_f32 v15, v0, v15, -v13
	v_fmac_f32_e32 v13, v60, v15
	v_fma_f32 v15, v0, v45, -v14
	v_fmac_f32_e32 v14, v61, v15
	v_lshlrev_b32_e32 v15, 16, v48
	v_lshlrev_b32_e32 v46, 16, v52
	v_and_b32_e32 v45, 0xffff0000, v48
	v_and_b32_e32 v47, 0xffff0000, v52
	v_fma_f32 v46, v0, v46, -v15
	v_fmac_f32_e32 v15, v54, v46
	v_fma_f32 v46, v0, v47, -v45
	v_fmac_f32_e32 v45, v55, v46
	v_mul_f32_e32 v2, 0xbfb8aa3b, v2
	v_mul_f32_e32 v12, 0xbfb8aa3b, v12
	v_mul_f32_e32 v13, 0xbfb8aa3b, v13
	v_mul_f32_e32 v14, 0xbfb8aa3b, v14
	v_mul_f32_e32 v15, 0xbfb8aa3b, v15
	v_mul_f32_e32 v45, 0xbfb8aa3b, v45
	v_lshlrev_b32_e32 v46, 16, v49
	v_lshlrev_b32_e32 v48, 16, v53
	v_exp_f32_e32 v2, v2
	v_exp_f32_e32 v12, v12
	v_exp_f32_e32 v13, v13
	v_exp_f32_e32 v14, v14
	v_exp_f32_e32 v15, v15
	v_exp_f32_e32 v45, v45
	v_and_b32_e32 v47, 0xffff0000, v49
	v_and_b32_e32 v49, 0xffff0000, v53
	v_fma_f32 v48, v0, v48, -v46
	v_fmac_f32_e32 v46, v56, v48
	v_fma_f32 v48, v0, v49, -v47
	v_fmac_f32_e32 v47, v57, v48
	v_add_f32_e32 v2, 1.0, v2
	v_add_f32_e32 v12, 1.0, v12
	v_add_f32_e32 v13, 1.0, v13
	v_add_f32_e32 v14, 1.0, v14
	v_add_f32_e32 v15, 1.0, v15
	v_add_f32_e32 v45, 1.0, v45
	v_mul_f32_e32 v46, 0xbfb8aa3b, v46
	v_mul_f32_e32 v47, 0xbfb8aa3b, v47
	v_rcp_f32_e32 v2, v2
	v_rcp_f32_e32 v12, v12
	v_rcp_f32_e32 v13, v13
	v_rcp_f32_e32 v14, v14
	v_rcp_f32_e32 v15, v15
	v_exp_f32_e32 v46, v46
	v_exp_f32_e32 v47, v47
	v_rcp_f32_e32 v45, v45
	v_cvt_pk_bf16_f32 v12, v2, v12
	v_add_f32_e32 v46, 1.0, v46
	v_add_f32_e32 v47, 1.0, v47
	v_cvt_pk_bf16_f32 v13, v13, v14
	v_cvt_pk_bf16_f32 v14, v15, v45
	s_waitcnt vmcnt(3)
	v_lshlrev_b32_e32 v2, 16, v36
	v_and_b32_e32 v45, 0xffff0000, v36
	s_waitcnt vmcnt(2)
	v_lshlrev_b32_e32 v36, 16, v40
	v_rcp_f32_e32 v46, v46
	v_rcp_f32_e32 v47, v47
	v_and_b32_e32 v40, 0xffff0000, v40
	v_fma_f32 v36, v0, v36, -v2
	s_waitcnt vmcnt(0)
	v_fmac_f32_e32 v2, v62, v36
	v_fma_f32 v36, v0, v40, -v45
	v_or_b32_e32 v60, s5, v180
	v_fmac_f32_e32 v45, v63, v36
	v_lshlrev_b32_e32 v58, 16, v37
	v_and_b32_e32 v59, 0xffff0000, v37
	v_lshlrev_b32_e32 v36, 7, v60
	v_mov_b32_e32 v37, v3
	v_lshlrev_b32_e32 v50, 16, v41
	v_and_b32_e32 v54, 0xffff0000, v41
	v_lshl_add_u64 v[40:41], v[88:89], 0, v[36:37]
	v_cvt_pk_bf16_f32 v15, v46, v47
	global_load_dwordx4 v[46:49], v[40:41], off
	v_fma_f32 v50, v0, v50, -v58
	v_lshl_add_u64 v[36:37], v[92:93], 0, v[36:37]
	v_fmac_f32_e32 v58, v64, v50
	global_load_dwordx4 v[50:53], v[36:37], off
	global_load_dwordx4 v[68:71], v[36:37], off offset:64
	v_fma_f32 v54, v0, v54, -v59
	v_fmac_f32_e32 v59, v65, v54
	global_load_dwordx4 v[54:57], v[40:41], off offset:64
	v_or_b32_e32 v36, s5, v181
	v_lshlrev_b32_e32 v64, 1, v36
	v_mov_b32_e32 v65, v3
	v_lshlrev_b32_e32 v61, 16, v38
	v_and_b32_e32 v40, 0xffff0000, v38
	v_lshlrev_b32_e32 v38, 16, v42
	v_lshl_add_u64 v[90:91], v[114:115], 0, v[64:65]
	v_and_b32_e32 v41, 0xffff0000, v42
	v_fma_f32 v38, v0, v38, -v61
	global_load_dwordx2 v[98:99], v[90:91], off
	global_load_dwordx2 v[104:105], v[90:91], off offset:3072
	v_fmac_f32_e32 v61, v16, v38
	v_fma_f32 v16, v0, v41, -v40
	v_lshl_add_u64 v[96:97], v[110:111], 0, v[64:65]
	v_fmac_f32_e32 v40, v17, v16
	v_lshlrev_b32_e32 v16, 16, v39
	global_load_dwordx2 v[106:107], v[96:97], off
	global_load_dwordx2 v[66:67], v[90:91], off offset:1536
	v_and_b32_e32 v17, 0xffff0000, v39
	v_lshlrev_b32_e32 v37, 16, v43
	v_and_b32_e32 v38, 0xffff0000, v43
	v_fma_f32 v37, v0, v37, -v16
	v_fma_f32 v38, v0, v38, -v17
	v_lshlrev_b32_e32 v160, 2, v36
	v_fmac_f32_e32 v17, v19, v38
	v_fmac_f32_e32 v16, v18, v37
	global_load_dwordx4 v[36:39], v160, s[8:9]
	global_load_dwordx4 v[72:75], v160, s[42:43]
	global_load_dwordx2 v[108:109], v[96:97], off offset:1536
	global_load_dwordx2 v[120:121], v[96:97], off offset:3072
	global_load_dwordx4 v[76:79], v160, s[44:45]
	v_mul_f32_e32 v17, 0xbfb8aa3b, v17
	v_exp_f32_e32 v17, v17
	v_mul_f32_e32 v2, 0xbfb8aa3b, v2
	v_mul_f32_e32 v18, 0xbfb8aa3b, v58
	v_mul_f32_e32 v41, 0xbfb8aa3b, v59
	v_add_f32_e32 v17, 1.0, v17
	v_rcp_f32_e32 v19, v17
	v_mul_f32_e32 v17, 0xbfb8aa3b, v45
	v_mul_f32_e32 v42, 0xbfb8aa3b, v61
	v_mul_f32_e32 v40, 0xbfb8aa3b, v40
	v_exp_f32_e32 v2, v2
	v_exp_f32_e32 v17, v17
	v_exp_f32_e32 v18, v18
	v_exp_f32_e32 v41, v41
	v_exp_f32_e32 v42, v42
	v_exp_f32_e32 v40, v40
	v_mul_f32_e32 v16, 0xbfb8aa3b, v16
	v_exp_f32_e32 v16, v16
	v_add_f32_e32 v2, 1.0, v2
	v_add_f32_e32 v17, 1.0, v17
	v_add_f32_e32 v18, 1.0, v18
	v_add_f32_e32 v41, 1.0, v41
	v_add_f32_e32 v42, 1.0, v42
	v_add_f32_e32 v40, 1.0, v40
	v_rcp_f32_e32 v2, v2
	v_rcp_f32_e32 v17, v17
	v_rcp_f32_e32 v18, v18
	v_rcp_f32_e32 v41, v41
	v_rcp_f32_e32 v42, v42
	v_rcp_f32_e32 v40, v40
	v_add_f32_e32 v16, 1.0, v16
	v_rcp_f32_e32 v43, v16
	v_cvt_pk_bf16_f32 v16, v2, v17
	v_cvt_pk_bf16_f32 v17, v18, v41
	v_cvt_pk_bf16_f32 v18, v42, v40
	v_mov_b64_e32 v[40:41], s[36:37]
	v_cvt_pk_bf16_f32 v19, v43, v19
	v_mad_i64_i32 v[118:119], s[0:1], v84, s65, v[40:41]
	s_waitcnt vmcnt(12)
	v_mfma_f32_16x16x32_bf16 v[40:43], v[46:49], v[20:23], 0
	v_lshl_add_u64 v[86:87], v[118:119], 0, s[10:11]
	s_mov_b32 s10, 0xbfb8aa3b
	v_mov_b32_e32 v2, v44
	s_waitcnt vmcnt(11)
; __device__ __forceinline__ float sigmoidf_(float x) { return __builtin_amdgcn_rcpf(1.0f + __expf(-x)); }
; __device__ __forceinline__ f32x4 ld_bf4(const bf16_t* q) { const u32x2 u = *(const u32x2*)q; return (f32x4){bflo(u.x), bfhi(u.x), bflo(u.y), bfhi(u.y)}; }
; __device__ __forceinline__ void rwkv_prep_item(const Params& p, const Lt& lt, int l, int item) {
;     ...
;         for (int ct = 0; ct < 4; ++ct) {
;             const int crow = h * 64 + ct * 16 + qi;
;             f32x4 aw = {0.f, 0.f, 0.f, 0.f}, aa = aw, ag = aw;
; #pragma unroll
;             for (int ks = 0; ks < 2; ++ks) {
;                 aw = __builtin_amdgcn_mfma_f32_16x16x32_bf16(*(const bf16x8*)(decT + crow * 64 + ks * 32 + quad * 8), fw[ks], aw, 0, 0, 0);
;                 aa = __builtin_amdgcn_mfma_f32_16x16x32_bf16(*(const bf16x8*)(aT + crow * 64 + ks * 32 + quad * 8), fa[ks], aa, 0, 0, 0);
;             }
; #pragma unroll
;             for (int ks = 0; ks < 4; ++ks) ag = __builtin_amdgcn_mfma_f32_16x16x32_bf16(*(const bf16x8*)(gT + crow * 128 + ks * 32 + quad * 8), fg[ks], ag, 0, 0, 0);
;             const int c = h * 64 + ct * 16 + quad * 4;
;             const f32x4 mr = *(const f32x4*)(mu + c), mk = *(const f32x4*)(mu + COL_K + c), mv = *(const f32x4*)(mu + COL_V + c);
;             const f32x4 cr = ld_bf4(pt + c), ck = ld_bf4(pt + COL_K + c), cv = ld_bf4(pt + COL_V + c);
;             const f32x4 qr = ld_bf4(pp + c) * pm, qk = ld_bf4(pp + COL_K + c) * pm, qv = ld_bf4(pp + COL_V + c) * pm;
;             const f32x4 r = cr + (qr - cr) * mr, k = ck + (qk - ck) * mk, v = cv + (qv - cv) * mv;
;             const f32x4 w0v = *(const f32x4*)(w0 + c), a0v = *(const f32x4*)(a0 + c), kkv = *(const f32x4*)(kkp + c), kav = *(const f32x4*)(kap + c), rkv = *(const f32x4*)(rkp + c);
;             f32x4 dec, a, kk, k2;
; #pragma unroll
;             for (int j = 0; j < 4; ++j) {
;                 const float z = -(w0v[j] + aw[j]);
;                 const float sp = fmaxf(z, 0.f) + __logf(1.0f + __expf(-fabsf(z)));
;                 dec[j] = __expf(-__expf(-sp - 0.5f));
;                 a[j] = sigmoidf_(a0v[j] + aa[j]);
;                 kk[j] = k[j] * kkv[j];
;                 nrm += kk[j] * kk[j];
;                 k2[j] = k[j] * (1.0f + (a[j] - 1.0f) * kav[j]);
;                 bon += r[j] * k2[j] * rkv[j];
;             }
	v_mfma_f32_16x16x32_bf16 v[80:83], v[50:53], v[28:31], 0
	v_mov_b64_e32 v[44:45], s[38:39]
	s_movk_i32 s0, 0x600
	v_mad_i64_i32 v[116:117], s[0:1], v84, s0, v[44:45]
	s_waitcnt vmcnt(9)
	v_mfma_f32_16x16x32_bf16 v[100:103], v[54:57], v[24:27], v[40:43]
	v_lshlrev_b32_e32 v44, 8, v60
	v_mov_b32_e32 v45, v3
	v_lshl_add_u64 v[44:45], v[94:95], 0, v[44:45]
	v_mfma_f32_16x16x32_bf16 v[80:83], v[68:71], v[32:35], v[80:83]
	s_waitcnt vmcnt(8)
	v_lshlrev_b32_e32 v40, 16, v98
	v_and_b32_e32 v41, 0xffff0000, v98
	v_lshlrev_b32_e32 v42, 16, v99
	v_and_b32_e32 v43, 0xffff0000, v99
	v_xor_b32_e32 v123, 0x80000000, v41
	v_xor_b32_e32 v122, 0x80000000, v40
	s_waitcnt vmcnt(6)
	v_lshlrev_b32_e32 v98, 16, v106
	v_and_b32_e32 v99, 0xffff0000, v106
	v_lshlrev_b32_e32 v68, 16, v104
	v_and_b32_e32 v69, 0xffff0000, v104
	v_lshlrev_b32_e32 v70, 16, v105
	v_and_b32_e32 v71, 0xffff0000, v105
	v_lshlrev_b32_e32 v104, 16, v107
	v_and_b32_e32 v105, 0xffff0000, v107
	v_pk_fma_f32 v[122:123], v[0:1], v[98:99], v[122:123] op_sel_hi:[0,1,1]
	v_xor_b32_e32 v99, 0x80000000, v43
	v_xor_b32_e32 v98, 0x80000000, v42
	v_pk_fma_f32 v[98:99], v[0:1], v[104:105], v[98:99] op_sel_hi:[0,1,1]
	s_waitcnt vmcnt(4)
	v_pk_fma_f32 v[98:99], v[38:39], v[98:99], v[42:43]
	s_waitcnt vmcnt(3)
	v_add_f32_e32 v38, v100, v72
	v_pk_fma_f32 v[128:129], v[36:37], v[122:123], v[40:41]
	v_mul_f32_e64 v36, |v38|, s10
	v_exp_f32_e32 v39, v36
	s_waitcnt vmcnt(1)
	v_lshlrev_b32_e32 v106, 16, v120
	v_and_b32_e32 v107, 0xffff0000, v120
	v_xor_b32_e32 v37, 0x80000000, v69
	v_xor_b32_e32 v36, 0x80000000, v68
	v_pk_fma_f32 v[130:131], v[0:1], v[106:107], v[36:37] op_sel_hi:[0,1,1]
	v_add_f32_e32 v36, 1.0, v39
	v_cmp_gt_f32_e32 vcc, s75, v36
	global_load_dwordx4 v[60:63], v[44:45], off
	global_load_dwordx4 v[52:55], v[44:45], off offset:64
	global_load_dwordx4 v[48:51], v[44:45], off offset:128
	s_nop 0
	global_load_dwordx4 v[44:47], v[44:45], off offset:192
	v_cndmask_b32_e64 v39, 0, 32, vcc
	v_ldexp_f32 v36, v36, v39
	v_log_f32_e32 v39, v36
	v_lshlrev_b32_e32 v120, 16, v121
	v_and_b32_e32 v121, 0xffff0000, v121
	v_xor_b32_e32 v37, 0x80000000, v71
	v_xor_b32_e32 v36, 0x80000000, v70
	v_pk_fma_f32 v[140:141], v[0:1], v[120:121], v[36:37] op_sel_hi:[0,1,1]
	v_mul_f32_e32 v37, 0x3f317217, v39
	v_fma_f32 v37, v39, s57, -v37
	v_fmac_f32_e32 v37, 0x3377d1cf, v39
	v_fmac_f32_e32 v37, 0x3f317217, v39
	v_cmp_lt_f32_e64 s[0:1], |v39|, s58
	v_max_f32_e64 v36, -v38, 0
	v_cndmask_b32_e32 v38, 0, v243, vcc
	v_cndmask_b32_e64 v37, v39, v37, s[0:1]
	v_sub_f32_e32 v37, v37, v38
	v_add_f32_e32 v36, v36, v37
	global_load_dwordx4 v[56:59], v160, s[8:9] offset:3072
	v_sub_f32_e32 v36, -0.5, v36
	v_mul_f32_e32 v36, 0x3fb8aa3b, v36
	v_exp_f32_e32 v72, v36
	global_load_dwordx4 v[36:39], v160, s[46:47]
	global_load_dwordx4 v[104:107], v160, s[48:49]
	global_load_dwordx4 v[122:125], v160, s[52:53]
	global_load_dwordx4 v[40:43], v160, s[50:51]
	v_add_f32_e32 v73, v101, v73
	v_mul_f32_e64 v85, |v73|, s10
	v_exp_f32_e32 v85, v85
	s_waitcnt vmcnt(9)
	v_add_f32_e32 v76, v80, v76
	v_mul_f32_e32 v76, 0xbfb8aa3b, v76
	v_max_f32_e64 v73, -v73, 0
	v_add_f32_e32 v80, 1.0, v85
	v_cmp_gt_f32_e32 vcc, s75, v80
	v_add_f32_e32 v74, v102, v74
	v_exp_f32_e32 v76, v76
	v_cndmask_b32_e64 v85, 0, 32, vcc
	v_ldexp_f32 v80, v80, v85
	v_log_f32_e32 v80, v80
	v_add_f32_e32 v76, 1.0, v76
	v_rcp_f32_e32 v100, v76
	v_add_f32_e32 v76, v81, v77
	v_mul_f32_e32 v85, 0x3f317217, v80
	v_fma_f32 v85, v80, s57, -v85
	v_fmac_f32_e32 v85, 0x3377d1cf, v80
	v_fmac_f32_e32 v85, 0x3f317217, v80
	v_cmp_lt_f32_e64 s[0:1], |v80|, s58
	v_mul_f32_e32 v76, 0xbfb8aa3b, v76
	v_exp_f32_e32 v76, v76
	v_cndmask_b32_e64 v80, v80, v85, s[0:1]
	v_cndmask_b32_e32 v85, 0, v243, vcc
	v_sub_f32_e32 v80, v80, v85
	v_add_f32_e32 v73, v73, v80
	v_mul_f32_e64 v80, |v74|, s10
	v_exp_f32_e32 v80, v80
	v_add_f32_e32 v76, 1.0, v76
	v_add_f32_e32 v75, v103, v75
	v_rcp_f32_e32 v101, v76
	v_add_f32_e32 v77, 1.0, v80
	v_cmp_gt_f32_e32 vcc, s75, v77
	v_mul_f32_e64 v76, |v75|, s10
	v_exp_f32_e32 v76, v76
	v_cndmask_b32_e64 v80, 0, 32, vcc
	v_ldexp_f32 v77, v77, v80
	v_log_f32_e32 v77, v77
	v_add_f32_e32 v76, 1.0, v76
	v_max_f32_e64 v74, -v74, 0
	s_waitcnt vmcnt(8)
	v_mfma_f32_16x16x32_bf16 v[60:63], v[60:63], v[4:7], 0
	v_mul_f32_e32 v80, 0x3f317217, v77
	v_fma_f32 v80, v77, s57, -v80
	v_fmac_f32_e32 v80, 0x3377d1cf, v77
	v_fmac_f32_e32 v80, 0x3f317217, v77
	v_cmp_lt_f32_e64 s[0:1], |v77|, s58
	v_max_f32_e64 v75, -v75, 0
	s_waitcnt vmcnt(7)
	v_mfma_f32_16x16x32_bf16 v[52:55], v[52:55], v[8:11], v[60:63]
	v_cndmask_b32_e64 v77, v77, v80, s[0:1]
	v_cndmask_b32_e32 v80, 0, v243, vcc
	v_sub_f32_e32 v77, v77, v80
	v_cmp_gt_f32_e32 vcc, s75, v76
	v_add_f32_e32 v74, v74, v77
	v_add_f32_e32 v77, v82, v78
	v_cndmask_b32_e64 v78, 0, 32, vcc
	v_ldexp_f32 v76, v76, v78
	v_log_f32_e32 v76, v76
	v_mul_f32_e32 v77, 0xbfb8aa3b, v77
	v_exp_f32_e32 v77, v77
	v_sub_f32_e32 v73, -0.5, v73
	v_mul_f32_e32 v78, 0x3f317217, v76
	v_fma_f32 v78, v76, s57, -v78
	v_fmac_f32_e32 v78, 0x3377d1cf, v76
	v_fmac_f32_e32 v78, 0x3f317217, v76
	v_cmp_lt_f32_e64 s[0:1], |v76|, s58
	v_sub_f32_e32 v74, -0.5, v74
	v_mul_f32_e32 v73, 0x3fb8aa3b, v73
	v_cndmask_b32_e64 v76, v76, v78, s[0:1]
	v_cndmask_b32_e32 v78, 0, v243, vcc
	v_sub_f32_e32 v76, v76, v78
	v_add_f32_e32 v75, v75, v76
	v_add_f32_e32 v76, v83, v79
	v_mul_f32_e32 v76, 0xbfb8aa3b, v76
	v_exp_f32_e32 v76, v76
	v_sub_f32_e32 v75, -0.5, v75
	v_mul_f32_e32 v74, 0x3fb8aa3b, v74
	v_mul_f32_e32 v75, 0x3fb8aa3b, v75
	v_exp_f32_e32 v73, v73
	v_exp_f32_e32 v74, v74
	v_exp_f32_e32 v75, v75
	v_add_f32_e32 v77, 1.0, v77
	v_add_f32_e32 v76, 1.0, v76
	s_waitcnt vmcnt(6)
; __device__ __forceinline__ float sigmoidf_(float x) { return __builtin_amdgcn_rcpf(1.0f + __expf(-x)); }
; __device__ __forceinline__ void st_bf4(unsigned char* q, f32x4 v) { u32x2 w; w.x = cvt_pk_bf16(v[0], v[1]); w.y = cvt_pk_bf16(v[2], v[3]); *(u32x2*)q = w; }
; __device__ __forceinline__ void rwkv_prep_item(const Params& p, const Lt& lt, int l, int item) {
;     ...
;             for (int j = 0; j < 4; ++j) {
;                 const float z = -(w0v[j] + aw[j]);
;                 const float sp = fmaxf(z, 0.f) + __logf(1.0f + __expf(-fabsf(z)));
;                 dec[j] = __expf(-__expf(-sp - 0.5f));
;                 a[j] = sigmoidf_(a0v[j] + aa[j]);
;                 kk[j] = k[j] * kkv[j];
;                 nrm += kk[j] * kk[j];
;                 k2[j] = k[j] * (1.0f + (a[j] - 1.0f) * kav[j]);
;                 bon += r[j] * k2[j] * rkv[j];
;             }
;             va[ct] = a; vkk[ct] = kk;
;             { const int cc = ct * 16 + quad * 4; *(f32x4*)(ob + cc * 4) = dec; st_bf4(ob + 512 + cc * 2, k2); st_bf4(ob + 640 + cc * 2, v); st_bf4(ob + 768 + cc * 2, r); }
;             st_bf4((unsigned char*)((bf16_t*)gate + (size_t)t * RW + c), ag);
;         }
	v_mfma_f32_16x16x32_bf16 v[48:51], v[48:51], v[12:15], v[52:55]
	v_rcp_f32_e32 v120, v77
	v_rcp_f32_e32 v121, v76
	v_lshlrev_b32_e32 v78, 16, v66
	v_and_b32_e32 v79, 0xffff0000, v66
	v_lshlrev_b32_e32 v126, 16, v108
	v_and_b32_e32 v127, 0xffff0000, v108
	v_mul_f32_e32 v72, 0xbfb8aa3b, v72
	v_mul_f32_e32 v73, 0xbfb8aa3b, v73
	v_mul_f32_e32 v74, 0xbfb8aa3b, v74
	v_mul_f32_e32 v75, 0xbfb8aa3b, v75
	v_lshlrev_b32_e32 v76, 16, v67
	v_and_b32_e32 v77, 0xffff0000, v67
	v_xor_b32_e32 v81, 0x80000000, v79
	v_xor_b32_e32 v80, 0x80000000, v78
	v_lshlrev_b32_e32 v108, 16, v109
	v_and_b32_e32 v109, 0xffff0000, v109
	v_exp_f32_e32 v72, v72
	v_exp_f32_e32 v73, v73
	v_exp_f32_e32 v74, v74
	v_exp_f32_e32 v75, v75
	v_xor_b32_e32 v67, 0x80000000, v77
	v_xor_b32_e32 v66, 0x80000000, v76
	v_pk_fma_f32 v[80:81], v[0:1], v[126:127], v[80:81] op_sel_hi:[0,1,1]
	s_waitcnt vmcnt(5)
	v_mfma_f32_16x16x32_bf16 v[44:47], v[44:47], v[16:19], v[48:51]
	v_fma_f32 v66, v0, v108, v66
	v_fma_f32 v67, v0, v109, v67
	s_waitcnt vmcnt(4)
	v_pk_fma_f32 v[138:139], v[56:57], v[80:81], v[78:79]
	v_pk_add_f32 v[56:57], v[100:101], -1.0 op_sel_hi:[1,0]
	v_pk_add_f32 v[52:53], v[120:121], -1.0 op_sel_hi:[1,0]
	s_waitcnt vmcnt(2)
	v_pk_fma_f32 v[56:57], v[104:105], v[56:57], 1.0 op_sel_hi:[1,1,0]
	v_pk_fma_f32 v[132:133], v[58:59], v[66:67], v[76:77]
	v_pk_fma_f32 v[52:53], v[106:107], v[52:53], 1.0 op_sel_hi:[1,1,0]
	s_waitcnt vmcnt(1)
	v_pk_fma_f32 v[48:49], v[124:125], v[140:141], v[70:71]
	v_pk_fma_f32 v[50:51], v[122:123], v[130:131], v[68:69]
	s_or_b32 s0, s5, 16
	v_pk_mul_f32 v[136:137], v[138:139], v[56:57]
	v_pk_mul_f32 v[134:135], v[132:133], v[52:53]
	v_lshl_add_u64 v[52:53], v[86:87], 0, v[112:113]
	v_lshl_add_u64 v[122:123], v[86:87], 0, v[2:3]
	v_cvt_pk_bf16_f32 v50, v50, v51
	v_cvt_pk_bf16_f32 v51, v48, v49
	v_cvt_pk_bf16_f32 v48, v128, v129
	v_cvt_pk_bf16_f32 v49, v98, v99
	v_or_b32_e32 v58, s0, v180
	v_sub_u32_e32 v233, v52, v230
	ds_write_b128 v233, v[72:75]
	v_cvt_pk_bf16_f32 v52, v136, v137
	v_cvt_pk_bf16_f32 v53, v134, v135
	v_sub_u32_e32 v233, v122, v230
	ds_write_b64 v233, v[48:49] offset:768
	v_cvt_pk_bf16_f32 v44, v44, v45
	v_cvt_pk_bf16_f32 v45, v46, v47
	v_lshl_add_u64 v[124:125], v[116:117], 0, v[64:65]
	v_lshlrev_b32_e32 v48, 7, v58
	v_mov_b32_e32 v49, v3
	v_sub_u32_e32 v233, v122, v230
	ds_write_b64 v233, v[52:53] offset:512
	v_sub_u32_e32 v233, v122, v230
	ds_write_b64 v233, v[50:51] offset:640
	global_store_dwordx2 v[124:125], v[44:45], off
	v_lshl_add_u64 v[52:53], v[88:89], 0, v[48:49]
	global_load_dwordx4 v[44:47], v[52:53], off
	v_lshl_add_u64 v[56:57], v[92:93], 0, v[48:49]
	global_load_dwordx4 v[48:51], v[56:57], off
	s_nop 0
	global_load_dwordx4 v[52:55], v[52:53], off offset:64
	s_nop 0
	global_load_dwordx4 v[68:71], v[56:57], off offset:64
	global_load_dwordx2 v[76:77], v[90:91], off offset:32
	global_load_dwordx2 v[78:79], v[90:91], off offset:3104
	global_load_dwordx2 v[126:127], v[96:97], off offset:32
	global_load_dwordx2 v[130:131], v[96:97], off offset:1568
	global_load_dwordx2 v[140:141], v[96:97], off offset:3104
	global_load_dwordx4 v[80:83], v160, s[8:9] offset:64
	global_load_dwordx4 v[102:105], v160, s[42:43] offset:64
	global_load_dwordx4 v[106:109], v160, s[44:45] offset:64
	global_load_dwordx2 v[154:155], v[90:91], off offset:1568
	s_waitcnt vmcnt(12)
	v_mfma_f32_16x16x32_bf16 v[44:47], v[44:47], v[20:23], 0
	v_lshlrev_b32_e32 v56, 8, v58
	v_mov_b32_e32 v57, v3
	v_lshl_add_u64 v[56:57], v[94:95], 0, v[56:57]
	s_waitcnt vmcnt(11)
	v_mfma_f32_16x16x32_bf16 v[48:51], v[48:51], v[28:31], 0
	global_load_dwordx4 v[72:75], v[56:57], off
	global_load_dwordx4 v[64:67], v[56:57], off offset:64
	global_load_dwordx4 v[60:63], v[56:57], off offset:128
	s_nop 0
	global_load_dwordx4 v[56:59], v[56:57], off offset:192
	s_waitcnt vmcnt(9)
	v_lshlrev_b32_e32 v156, 16, v130
	v_and_b32_e32 v157, 0xffff0000, v130
	v_mfma_f32_16x16x32_bf16 v[146:149], v[52:55], v[24:27], v[44:47]
	v_lshlrev_b32_e32 v158, 16, v131
	v_and_b32_e32 v159, 0xffff0000, v131
	s_waitcnt vmcnt(8)
	v_lshlrev_b32_e32 v130, 16, v141
	v_or_b32_e32 v44, s0, v181
	v_lshlrev_b32_e32 v44, 2, v44
	v_mfma_f32_16x16x32_bf16 v[150:153], v[68:71], v[32:35], v[48:51]
	global_load_dwordx4 v[68:71], v160, s[8:9] offset:3136
	global_load_dwordx4 v[52:55], v44, s[52:53]
	v_lshlrev_b32_e32 v44, 16, v76
	v_and_b32_e32 v45, 0xffff0000, v76
	v_lshlrev_b32_e32 v46, 16, v77
	v_and_b32_e32 v47, 0xffff0000, v77
	v_lshlrev_b32_e32 v48, 16, v126
	v_and_b32_e32 v49, 0xffff0000, v126
	v_lshlrev_b32_e32 v50, 16, v127
	v_and_b32_e32 v51, 0xffff0000, v127
	v_lshlrev_b32_e32 v126, 16, v140
	v_and_b32_e32 v127, 0xffff0000, v140
	v_and_b32_e32 v131, 0xffff0000, v141
	v_xor_b32_e32 v141, 0x80000000, v45
	v_xor_b32_e32 v140, 0x80000000, v44
	v_pk_fma_f32 v[48:49], v[0:1], v[48:49], v[140:141] op_sel_hi:[0,1,1]
	v_xor_b32_e32 v141, 0x80000000, v47
	v_xor_b32_e32 v140, 0x80000000, v46
	v_pk_fma_f32 v[50:51], v[0:1], v[50:51], v[140:141] op_sel_hi:[0,1,1]
	s_waitcnt vmcnt(9)
	v_pk_fma_f32 v[142:143], v[82:83], v[50:51], v[46:47]
	s_waitcnt vmcnt(8)
; __device__ __forceinline__ float sigmoidf_(float x) { return __builtin_amdgcn_rcpf(1.0f + __expf(-x)); }
; __device__ __forceinline__ f32x4 ld_bf4(const bf16_t* q) { const u32x2 u = *(const u32x2*)q; return (f32x4){bflo(u.x), bfhi(u.x), bflo(u.y), bfhi(u.y)}; }
; __device__ __forceinline__ void rwkv_prep_item(const Params& p, const Lt& lt, int l, int item) {
;     ...
;         for (int ct = 0; ct < 4; ++ct) {
;             const int crow = h * 64 + ct * 16 + qi;
;             f32x4 aw = {0.f, 0.f, 0.f, 0.f}, aa = aw, ag = aw;
; #pragma unroll
;             for (int ks = 0; ks < 2; ++ks) {
;                 aw = __builtin_amdgcn_mfma_f32_16x16x32_bf16(*(const bf16x8*)(decT + crow * 64 + ks * 32 + quad * 8), fw[ks], aw, 0, 0, 0);
;                 aa = __builtin_amdgcn_mfma_f32_16x16x32_bf16(*(const bf16x8*)(aT + crow * 64 + ks * 32 + quad * 8), fa[ks], aa, 0, 0, 0);
;             }
; #pragma unroll
;             for (int ks = 0; ks < 4; ++ks) ag = __builtin_amdgcn_mfma_f32_16x16x32_bf16(*(const bf16x8*)(gT + crow * 128 + ks * 32 + quad * 8), fg[ks], ag, 0, 0, 0);
;             const int c = h * 64 + ct * 16 + quad * 4;
;             const f32x4 mr = *(const f32x4*)(mu + c), mk = *(const f32x4*)(mu + COL_K + c), mv = *(const f32x4*)(mu + COL_V + c);
;             const f32x4 cr = ld_bf4(pt + c), ck = ld_bf4(pt + COL_K + c), cv = ld_bf4(pt + COL_V + c);
;             const f32x4 qr = ld_bf4(pp + c) * pm, qk = ld_bf4(pp + COL_K + c) * pm, qv = ld_bf4(pp + COL_V + c) * pm;
;             const f32x4 r = cr + (qr - cr) * mr, k = ck + (qk - ck) * mk, v = cv + (qv - cv) * mv;
;             const f32x4 w0v = *(const f32x4*)(w0 + c), a0v = *(const f32x4*)(a0 + c), kkv = *(const f32x4*)(kkp + c), kav = *(const f32x4*)(kap + c), rkv = *(const f32x4*)(rkp + c);
;             f32x4 dec, a, kk, k2;
; #pragma unroll
;             for (int j = 0; j < 4; ++j) {
;                 const float z = -(w0v[j] + aw[j]);
;                 const float sp = fmaxf(z, 0.f) + __logf(1.0f + __expf(-fabsf(z)));
;                 dec[j] = __expf(-__expf(-sp - 0.5f));
;                 a[j] = sigmoidf_(a0v[j] + aa[j]);
;                 kk[j] = k[j] * kkv[j];
;                 nrm += kk[j] * kk[j];
;                 k2[j] = k[j] * (1.0f + (a[j] - 1.0f) * kav[j]);
;                 bon += r[j] * k2[j] * rkv[j];
;             }
	v_add_f32_e32 v46, v146, v102
	v_pk_fma_f32 v[144:145], v[80:81], v[48:49], v[44:45]
	v_mul_f32_e64 v44, |v46|, s10
	v_exp_f32_e32 v47, v44
	v_lshlrev_b32_e32 v76, 16, v78
	v_and_b32_e32 v77, 0xffff0000, v78
	v_xor_b32_e32 v45, 0x80000000, v77
	v_xor_b32_e32 v44, 0x80000000, v76
	v_pk_fma_f32 v[140:141], v[0:1], v[126:127], v[44:45] op_sel_hi:[0,1,1]
	v_add_f32_e32 v44, 1.0, v47
	v_cmp_gt_f32_e32 vcc, s75, v44
	v_lshlrev_b32_e32 v78, 16, v79
	v_and_b32_e32 v79, 0xffff0000, v79
	v_cndmask_b32_e64 v47, 0, 32, vcc
	v_ldexp_f32 v44, v44, v47
	v_log_f32_e32 v47, v44
	v_xor_b32_e32 v45, 0x80000000, v79
	v_xor_b32_e32 v44, 0x80000000, v78
	v_pk_fma_f32 v[162:163], v[0:1], v[130:131], v[44:45] op_sel_hi:[0,1,1]
	v_mul_f32_e32 v45, 0x3f317217, v47
	v_fma_f32 v45, v47, s57, -v45
	v_fmac_f32_e32 v45, 0x3377d1cf, v47
	v_fmac_f32_e32 v45, 0x3f317217, v47
	v_cmp_lt_f32_e64 s[0:1], |v47|, s58
	v_max_f32_e64 v44, -v46, 0
	v_cndmask_b32_e32 v46, 0, v243, vcc
	v_cndmask_b32_e64 v45, v47, v45, s[0:1]
	v_sub_f32_e32 v45, v45, v46
	v_add_f32_e32 v44, v44, v45
	v_sub_f32_e32 v44, -0.5, v44
	v_mul_f32_e32 v44, 0x3fb8aa3b, v44
	v_exp_f32_e32 v85, v44
	global_load_dwordx4 v[48:51], v160, s[46:47] offset:64
	global_load_dwordx4 v[80:83], v160, s[48:49] offset:64
	global_load_dwordx4 v[44:47], v160, s[50:51] offset:64
	v_add_f32_e32 v103, v147, v103
	v_mul_f32_e64 v102, |v103|, s10
	v_exp_f32_e32 v102, v102
	s_waitcnt vmcnt(10)
	v_add_f32_e32 v106, v150, v106
	v_mul_f32_e32 v106, 0xbfb8aa3b, v106
	v_exp_f32_e32 v106, v106
	v_add_f32_e32 v102, 1.0, v102
	v_cmp_gt_f32_e32 vcc, s75, v102
	v_mul_f32_e32 v85, 0xbfb8aa3b, v85
	v_max_f32_e64 v103, -v103, 0
	v_cndmask_b32_e64 v126, 0, 32, vcc
	v_ldexp_f32 v102, v102, v126
	v_log_f32_e32 v126, v102
	v_exp_f32_e32 v102, v85
	v_add_f32_e32 v85, 1.0, v106
	v_add_f32_e32 v104, v148, v104
	v_mul_f32_e32 v106, 0x3f317217, v126
	v_fma_f32 v106, v126, s57, -v106
	v_fmac_f32_e32 v106, 0x3377d1cf, v126
	v_fmac_f32_e32 v106, 0x3f317217, v126
	v_cmp_lt_f32_e64 s[0:1], |v126|, s58
	v_add_f32_e32 v105, v149, v105
	s_waitcnt vmcnt(8)
	v_mfma_f32_16x16x32_bf16 v[72:75], v[72:75], v[4:7], 0
	v_cndmask_b32_e64 v106, v126, v106, s[0:1]
	v_cndmask_b32_e32 v126, 0, v243, vcc
	v_sub_f32_e32 v106, v106, v126
	v_add_f32_e32 v103, v103, v106
	v_mul_f32_e64 v106, |v104|, s10
	v_sub_f32_e32 v103, -0.5, v103
	v_exp_f32_e32 v106, v106
	v_mul_f32_e32 v103, 0x3fb8aa3b, v103
	v_exp_f32_e32 v103, v103
	v_rcp_f32_e32 v126, v85
	v_add_f32_e32 v106, 1.0, v106
	v_cmp_gt_f32_e32 vcc, s75, v106
	v_mul_f32_e32 v85, 0xbfb8aa3b, v103
	v_add_f32_e32 v103, v151, v107
	v_cndmask_b32_e64 v107, 0, 32, vcc
	v_ldexp_f32 v106, v106, v107
	v_log_f32_e32 v106, v106
	v_mul_f32_e32 v103, 0xbfb8aa3b, v103
	v_exp_f32_e32 v107, v103
	v_max_f32_e64 v103, -v104, 0
	v_mul_f32_e32 v104, 0x3f317217, v106
	v_fma_f32 v104, v106, s57, -v104
	v_fmac_f32_e32 v104, 0x3377d1cf, v106
	v_fmac_f32_e32 v104, 0x3f317217, v106
	v_cmp_lt_f32_e64 s[0:1], |v106|, s58
	s_waitcnt vmcnt(7)
	v_mfma_f32_16x16x32_bf16 v[64:67], v[64:67], v[8:11], v[72:75]
	s_waitcnt vmcnt(3)
	v_pk_fma_f32 v[54:55], v[54:55], v[162:163], v[78:79]
	v_cndmask_b32_e64 v104, v106, v104, s[0:1]
	v_cndmask_b32_e32 v106, 0, v243, vcc
	v_sub_f32_e32 v104, v104, v106
	v_add_f32_e32 v103, v103, v104
	v_sub_f32_e32 v103, -0.5, v103
	v_mul_f32_e32 v103, 0x3fb8aa3b, v103
	v_exp_f32_e32 v104, v103
	v_exp_f32_e32 v103, v85
	v_add_f32_e32 v85, 1.0, v107
	v_rcp_f32_e32 v127, v85
	v_mul_f32_e32 v85, 0xbfb8aa3b, v104
	v_mul_f32_e64 v104, |v105|, s10
	v_exp_f32_e32 v104, v104
	v_add_f32_e32 v106, v152, v108
	v_mul_f32_e32 v106, 0xbfb8aa3b, v106
	v_exp_f32_e32 v106, v106
	v_add_f32_e32 v104, 1.0, v104
	v_cmp_gt_f32_e32 vcc, s75, v104
	v_max_f32_e64 v105, -v105, 0
	v_mfma_f32_16x16x32_bf16 v[60:63], v[60:63], v[12:15], v[64:67]
	v_cndmask_b32_e64 v107, 0, 32, vcc
	v_ldexp_f32 v104, v104, v107
	v_log_f32_e32 v107, v104
	v_exp_f32_e32 v104, v85
	v_add_f32_e32 v85, 1.0, v106
	v_rcp_f32_e32 v130, v85
	v_mul_f32_e32 v106, 0x3f317217, v107
	v_fma_f32 v106, v107, s57, -v106
	v_fmac_f32_e32 v106, 0x3377d1cf, v107
	v_fmac_f32_e32 v106, 0x3f317217, v107
	v_cmp_lt_f32_e64 s[0:1], |v107|, s58
	v_lshlrev_b32_e32 v108, 16, v154
	v_xor_b32_e32 v148, 0x80000000, v108
	v_cndmask_b32_e64 v106, v107, v106, s[0:1]
	v_cndmask_b32_e32 v107, 0, v243, vcc
	v_sub_f32_e32 v106, v106, v107
	v_add_f32_e32 v105, v105, v106
	v_sub_f32_e32 v105, -0.5, v105
	v_mul_f32_e32 v105, 0x3fb8aa3b, v105
	v_add_f32_e32 v106, v153, v109
	v_exp_f32_e32 v105, v105
	v_mul_f32_e32 v106, 0xbfb8aa3b, v106
	v_exp_f32_e32 v106, v106
	v_and_b32_e32 v107, 0xffff0000, v155
	v_mul_f32_e32 v85, 0xbfb8aa3b, v105
	v_exp_f32_e32 v105, v85
	v_add_f32_e32 v85, 1.0, v106
	v_rcp_f32_e32 v131, v85
	v_lshlrev_b32_e32 v106, 16, v155
	v_and_b32_e32 v109, 0xffff0000, v154
	v_xor_b32_e32 v147, 0x80000000, v107
	v_xor_b32_e32 v146, 0x80000000, v106
	v_xor_b32_e32 v149, 0x80000000, v109
	v_pk_fma_f32 v[146:147], v[0:1], v[158:159], v[146:147] op_sel_hi:[0,1,1]
	v_pk_fma_f32 v[148:149], v[0:1], v[156:157], v[148:149] op_sel_hi:[0,1,1]
	v_mfma_f32_16x16x32_bf16 v[56:59], v[56:59], v[16:19], v[60:63]
	v_fma_f32 v152, v68, v148, v108
	v_fma_f32 v153, v69, v149, v109
	v_pk_fma_f32 v[148:149], v[70:71], v[146:147], v[106:107]
	v_mov_b32_e32 v107, v3
	v_or_b32_e32 v62, 16, v181
	v_lshlrev_b32_e32 v106, 2, v62
	v_pk_add_f32 v[68:69], v[126:127], -1.0 op_sel_hi:[1,0]
	v_pk_add_f32 v[64:65], v[130:131], -1.0 op_sel_hi:[1,0]
	v_pk_fma_f32 v[52:53], v[52:53], v[140:141], v[76:77]
	v_lshl_add_u64 v[60:61], v[86:87], 0, v[106:107]
	v_lshlrev_b32_e32 v108, 1, v62
	v_mov_b32_e32 v109, v3
	s_waitcnt vmcnt(1)
; __device__ __forceinline__ float sigmoidf_(float x) { return __builtin_amdgcn_rcpf(1.0f + __expf(-x)); }
; __device__ __forceinline__ void st_bf4(unsigned char* q, f32x4 v) { u32x2 w; w.x = cvt_pk_bf16(v[0], v[1]); w.y = cvt_pk_bf16(v[2], v[3]); *(u32x2*)q = w; }
; __device__ __forceinline__ void rwkv_prep_item(const Params& p, const Lt& lt, int l, int item) {
;     ...
;             for (int j = 0; j < 4; ++j) {
;                 const float z = -(w0v[j] + aw[j]);
;                 const float sp = fmaxf(z, 0.f) + __logf(1.0f + __expf(-fabsf(z)));
;                 dec[j] = __expf(-__expf(-sp - 0.5f));
;                 a[j] = sigmoidf_(a0v[j] + aa[j]);
;                 kk[j] = k[j] * kkv[j];
;                 nrm += kk[j] * kk[j];
;                 k2[j] = k[j] * (1.0f + (a[j] - 1.0f) * kav[j]);
;                 bon += r[j] * k2[j] * rkv[j];
;             }
;             va[ct] = a; vkk[ct] = kk;
;             { const int cc = ct * 16 + quad * 4; *(f32x4*)(ob + cc * 4) = dec; st_bf4(ob + 512 + cc * 2, k2); st_bf4(ob + 640 + cc * 2, v); st_bf4(ob + 768 + cc * 2, r); }
;             st_bf4((unsigned char*)((bf16_t*)gate + (size_t)t * RW + c), ag);
;         }
	v_pk_fma_f32 v[68:69], v[80:81], v[68:69], 1.0 op_sel_hi:[1,1,0]
	v_pk_fma_f32 v[64:65], v[82:83], v[64:65], 1.0 op_sel_hi:[1,1,0]
	v_sub_u32_e32 v233, v60, v230
	ds_write_b128 v233, v[102:105]
	v_lshl_add_u64 v[60:61], v[86:87], 0, v[108:109]
	v_cvt_pk_bf16_f32 v52, v52, v53
	v_cvt_pk_bf16_f32 v53, v54, v55
	s_or_b32 s0, s5, 32
	v_pk_mul_f32 v[154:155], v[152:153], v[68:69]
	v_pk_mul_f32 v[150:151], v[148:149], v[64:65]
	v_sub_u32_e32 v233, v60, v230
	ds_write_b64 v233, v[52:53] offset:640
	v_cvt_pk_bf16_f32 v52, v144, v145
	v_cvt_pk_bf16_f32 v53, v142, v143
	v_or_b32_e32 v66, s0, v180
	v_cvt_pk_bf16_f32 v62, v154, v155
	v_cvt_pk_bf16_f32 v63, v150, v151
	v_sub_u32_e32 v233, v60, v230
	ds_write_b64 v233, v[52:53] offset:768
	v_cvt_pk_bf16_f32 v52, v56, v57
	v_cvt_pk_bf16_f32 v53, v58, v59
	v_lshlrev_b32_e32 v56, 7, v66
	v_mov_b32_e32 v57, v3
	v_sub_u32_e32 v233, v60, v230
	ds_write_b64 v233, v[62:63] offset:512
	global_store_dwordx2 v[124:125], v[52:53], off offset:32
	v_lshl_add_u64 v[60:61], v[88:89], 0, v[56:57]
	global_load_dwordx4 v[52:55], v[60:61], off
	v_lshl_add_u64 v[64:65], v[92:93], 0, v[56:57]
	global_load_dwordx4 v[56:59], v[64:65], off
	s_nop 0
	global_load_dwordx4 v[60:63], v[60:61], off offset:64
	s_nop 0
	global_load_dwordx4 v[76:79], v[64:65], off offset:64
	global_load_dwordx2 v[102:103], v[90:91], off offset:64
	global_load_dwordx2 v[104:105], v[90:91], off offset:3136
	global_load_dwordx2 v[140:141], v[96:97], off offset:64
	global_load_dwordx2 v[146:147], v[96:97], off offset:1600
	global_load_dwordx2 v[156:157], v[96:97], off offset:3136
	global_load_dwordx4 v[162:165], v160, s[8:9] offset:128
	global_load_dwordx4 v[166:169], v160, s[42:43] offset:128
	global_load_dwordx4 v[170:173], v160, s[44:45] offset:128
	global_load_dwordx2 v[178:179], v[90:91], off offset:1600
	s_waitcnt vmcnt(12)
	v_mfma_f32_16x16x32_bf16 v[52:55], v[52:55], v[20:23], 0
	v_lshlrev_b32_e32 v64, 8, v66
	v_mov_b32_e32 v65, v3
	v_lshl_add_u64 v[64:65], v[94:95], 0, v[64:65]
	s_waitcnt vmcnt(11)
	v_mfma_f32_16x16x32_bf16 v[56:59], v[56:59], v[28:31], 0
	global_load_dwordx4 v[80:83], v[64:65], off
	global_load_dwordx4 v[72:75], v[64:65], off offset:64
	global_load_dwordx4 v[68:71], v[64:65], off offset:128
	s_nop 0
	global_load_dwordx4 v[64:67], v[64:65], off offset:192
	s_waitcnt vmcnt(9)
	v_lshlrev_b32_e32 v186, 16, v146
	v_and_b32_e32 v187, 0xffff0000, v146
	v_mfma_f32_16x16x32_bf16 v[174:177], v[60:63], v[24:27], v[52:55]
	v_lshlrev_b32_e32 v188, 16, v147
	v_and_b32_e32 v189, 0xffff0000, v147
	s_waitcnt vmcnt(8)
	v_lshlrev_b32_e32 v146, 16, v157
	v_or_b32_e32 v52, s0, v181
	v_lshlrev_b32_e32 v52, 2, v52
	v_mfma_f32_16x16x32_bf16 v[182:185], v[76:79], v[32:35], v[56:59]
	global_load_dwordx4 v[76:79], v160, s[8:9] offset:3200
	global_load_dwordx4 v[60:63], v52, s[52:53]
	v_lshlrev_b32_e32 v52, 16, v102
	v_and_b32_e32 v53, 0xffff0000, v102
	v_lshlrev_b32_e32 v54, 16, v103
	v_and_b32_e32 v55, 0xffff0000, v103
	v_lshlrev_b32_e32 v56, 16, v140
	v_and_b32_e32 v57, 0xffff0000, v140
	v_lshlrev_b32_e32 v58, 16, v141
	v_and_b32_e32 v59, 0xffff0000, v141
	v_lshlrev_b32_e32 v140, 16, v156
	v_and_b32_e32 v141, 0xffff0000, v156
	v_and_b32_e32 v147, 0xffff0000, v157
	v_xor_b32_e32 v157, 0x80000000, v53
	v_xor_b32_e32 v156, 0x80000000, v52
	v_pk_fma_f32 v[56:57], v[0:1], v[56:57], v[156:157] op_sel_hi:[0,1,1]
	v_xor_b32_e32 v157, 0x80000000, v55
	v_xor_b32_e32 v156, 0x80000000, v54
	v_pk_fma_f32 v[58:59], v[0:1], v[58:59], v[156:157] op_sel_hi:[0,1,1]
	s_waitcnt vmcnt(9)
	v_pk_fma_f32 v[156:157], v[164:165], v[58:59], v[54:55]
	s_waitcnt vmcnt(8)
	v_add_f32_e32 v54, v174, v166
	v_pk_fma_f32 v[158:159], v[162:163], v[56:57], v[52:53]
	v_mul_f32_e64 v52, |v54|, s10
	v_exp_f32_e32 v55, v52
	v_lshlrev_b32_e32 v102, 16, v104
	v_and_b32_e32 v103, 0xffff0000, v104
	v_xor_b32_e32 v53, 0x80000000, v103
	v_xor_b32_e32 v52, 0x80000000, v102
	v_pk_fma_f32 v[190:191], v[0:1], v[140:141], v[52:53] op_sel_hi:[0,1,1]
	v_add_f32_e32 v52, 1.0, v55
	v_cmp_gt_f32_e32 vcc, s75, v52
	v_lshlrev_b32_e32 v104, 16, v105
	v_and_b32_e32 v105, 0xffff0000, v105
	v_cndmask_b32_e64 v55, 0, 32, vcc
	v_ldexp_f32 v52, v52, v55
	v_log_f32_e32 v55, v52
	v_xor_b32_e32 v53, 0x80000000, v105
	v_xor_b32_e32 v52, 0x80000000, v104
	v_pk_fma_f32 v[192:193], v[0:1], v[146:147], v[52:53] op_sel_hi:[0,1,1]
	v_mul_f32_e32 v53, 0x3f317217, v55
	v_fma_f32 v53, v55, s57, -v53
	v_fmac_f32_e32 v53, 0x3377d1cf, v55
	v_fmac_f32_e32 v53, 0x3f317217, v55
	v_cmp_lt_f32_e64 s[0:1], |v55|, s58
	v_max_f32_e64 v52, -v54, 0
	v_cndmask_b32_e32 v54, 0, v243, vcc
	v_cndmask_b32_e64 v53, v55, v53, s[0:1]
	v_add_f32_e32 v140, v175, v167
	v_sub_f32_e32 v53, v53, v54
	v_mul_f32_e64 v141, |v140|, s10
	v_add_f32_e32 v52, v52, v53
	v_exp_f32_e32 v141, v141
	v_sub_f32_e32 v52, -0.5, v52
	v_mul_f32_e32 v52, 0x3fb8aa3b, v52
	v_exp_f32_e32 v85, v52
	global_load_dwordx4 v[56:59], v160, s[46:47] offset:128
	global_load_dwordx4 v[162:165], v160, s[48:49] offset:128
	global_load_dwordx4 v[52:55], v160, s[50:51] offset:128
	v_add_f32_e32 v141, 1.0, v141
	v_cmp_gt_f32_e32 vcc, s75, v141
	s_waitcnt vmcnt(10)
	v_add_f32_e32 v146, v182, v170
	v_mul_f32_e32 v146, 0xbfb8aa3b, v146
	v_cndmask_b32_e64 v147, 0, 32, vcc
	v_ldexp_f32 v141, v141, v147
	v_exp_f32_e32 v146, v146
	v_log_f32_e32 v141, v141
	v_mul_f32_e32 v85, 0xbfb8aa3b, v85
	v_exp_f32_e32 v166, v85
	v_add_f32_e32 v85, 1.0, v146
	v_mul_f32_e32 v146, 0x3f317217, v141
	v_fma_f32 v146, v141, s57, -v146
	v_fmac_f32_e32 v146, 0x3377d1cf, v141
	v_fmac_f32_e32 v146, 0x3f317217, v141
	v_cmp_lt_f32_e64 s[0:1], |v141|, s58
	v_max_f32_e64 v140, -v140, 0
	s_waitcnt vmcnt(8)
; __device__ __forceinline__ void rwkv_prep_item(const Params& p, const Lt& lt, int l, int item) {
;     ...
;         for (int ct = 0; ct < 4; ++ct) {
;             const int crow = h * 64 + ct * 16 + qi;
;             f32x4 aw = {0.f, 0.f, 0.f, 0.f}, aa = aw, ag = aw;
; #pragma unroll
;             for (int ks = 0; ks < 2; ++ks) {
;                 aw = __builtin_amdgcn_mfma_f32_16x16x32_bf16(*(const bf16x8*)(decT + crow * 64 + ks * 32 + quad * 8), fw[ks], aw, 0, 0, 0);
;                 aa = __builtin_amdgcn_mfma_f32_16x16x32_bf16(*(const bf16x8*)(aT + crow * 64 + ks * 32 + quad * 8), fa[ks], aa, 0, 0, 0);
;             }
; #pragma unroll
;             for (int ks = 0; ks < 4; ++ks) ag = __builtin_amdgcn_mfma_f32_16x16x32_bf16(*(const bf16x8*)(gT + crow * 128 + ks * 32 + quad * 8), fg[ks], ag, 0, 0, 0);
;             const int c = h * 64 + ct * 16 + quad * 4;
;             const f32x4 mr = *(const f32x4*)(mu + c), mk = *(const f32x4*)(mu + COL_K + c), mv = *(const f32x4*)(mu + COL_V + c);
;             const f32x4 cr = ld_bf4(pt + c), ck = ld_bf4(pt + COL_K + c), cv = ld_bf4(pt + COL_V + c);
;             const f32x4 qr = ld_bf4(pp + c) * pm, qk = ld_bf4(pp + COL_K + c) * pm, qv = ld_bf4(pp + COL_V + c) * pm;
;             const f32x4 r = cr + (qr - cr) * mr, k = ck + (qk - ck) * mk, v = cv + (qv - cv) * mv;
;             const f32x4 w0v = *(const f32x4*)(w0 + c), a0v = *(const f32x4*)(a0 + c), kkv = *(const f32x4*)(kkp + c), kav = *(const f32x4*)(kap + c), rkv = *(const f32x4*)(rkp + c);
;             f32x4 dec, a, kk, k2;
; #pragma unroll
;             for (int j = 0; j < 4; ++j) {
;                 const float z = -(w0v[j] + aw[j]);
;                 const float sp = fmaxf(z, 0.f) + __logf(1.0f + __expf(-fabsf(z)));
;                 dec[j] = __expf(-__expf(-sp - 0.5f));
;                 a[j] = sigmoidf_(a0v[j] + aa[j]);
;                 kk[j] = k[j] * kkv[j];
;                 nrm += kk[j] * kk[j];
;                 k2[j] = k[j] * (1.0f + (a[j] - 1.0f) * kav[j]);
;                 bon += r[j] * k2[j] * rkv[j];
;             }
;             va[ct] = a; vkk[ct] = kk;
;             { const int cc = ct * 16 + quad * 4; *(f32x4*)(ob + cc * 4) = dec; st_bf4(ob + 512 + cc * 2, k2); st_bf4(ob + 640 + cc * 2, v); st_bf4(ob + 768 + cc * 2, r); }
;             st_bf4((unsigned char*)((bf16_t*)gate + (size_t)t * RW + c), ag);
;         }
	v_mfma_f32_16x16x32_bf16 v[80:83], v[80:83], v[4:7], 0
	v_cndmask_b32_e64 v141, v141, v146, s[0:1]
	v_cndmask_b32_e32 v146, 0, v243, vcc
	v_sub_f32_e32 v141, v141, v146
	v_add_f32_e32 v140, v140, v141
	v_sub_f32_e32 v140, -0.5, v140
	v_mul_f32_e32 v140, 0x3fb8aa3b, v140
	v_add_f32_e32 v146, v176, v168
	v_exp_f32_e32 v141, v140
	v_mul_f32_e64 v140, |v146|, s10
	v_exp_f32_e32 v147, v140
	v_max_f32_e64 v146, -v146, 0
	v_rcp_f32_e32 v140, v85
	v_mul_f32_e32 v85, 0xbfb8aa3b, v141
	v_add_f32_e32 v147, 1.0, v147
	v_cmp_gt_f32_e32 vcc, s75, v147
	v_add_f32_e32 v141, v183, v171
	v_mul_f32_e32 v141, 0xbfb8aa3b, v141
	v_cndmask_b32_e64 v161, 0, 32, vcc
	v_ldexp_f32 v147, v147, v161
	v_log_f32_e32 v147, v147
	v_exp_f32_e32 v141, v141
	v_exp_f32_e32 v167, v85
	s_waitcnt vmcnt(7)
	v_mfma_f32_16x16x32_bf16 v[72:75], v[72:75], v[8:11], v[80:83]
	v_mul_f32_e32 v161, 0x3f317217, v147
	v_fma_f32 v161, v147, s57, -v161
	v_fmac_f32_e32 v161, 0x3377d1cf, v147
	v_fmac_f32_e32 v161, 0x3f317217, v147
	v_cmp_lt_f32_e64 s[0:1], |v147|, s58
	v_add_f32_e32 v85, 1.0, v141
	v_rcp_f32_e32 v141, v85
	v_cndmask_b32_e64 v147, v147, v161, s[0:1]
	v_cndmask_b32_e32 v161, 0, v243, vcc
	v_sub_f32_e32 v147, v147, v161
	v_add_f32_e32 v146, v146, v147
	v_sub_f32_e32 v146, -0.5, v146
	v_mul_f32_e32 v146, 0x3fb8aa3b, v146
	v_exp_f32_e32 v146, v146
	v_add_f32_e32 v161, v184, v172
	v_mul_f32_e32 v161, 0xbfb8aa3b, v161
	v_exp_f32_e32 v161, v161
	v_mul_f32_e32 v85, 0xbfb8aa3b, v146
	v_add_f32_e32 v146, v177, v169
	v_mul_f32_e64 v147, |v146|, s10
	v_exp_f32_e32 v147, v147
	v_max_f32_e64 v146, -v146, 0
	s_waitcnt vmcnt(6)
	v_mfma_f32_16x16x32_bf16 v[68:71], v[68:71], v[12:15], v[72:75]
	v_lshlrev_b32_e32 v172, 16, v178
	v_add_f32_e32 v147, 1.0, v147
	v_cmp_gt_f32_e32 vcc, s75, v147
	v_lshlrev_b32_e32 v170, 16, v179
	v_and_b32_e32 v171, 0xffff0000, v179
	v_cndmask_b32_e64 v168, 0, 32, vcc
	v_ldexp_f32 v147, v147, v168
	v_log_f32_e32 v147, v147
	v_exp_f32_e32 v168, v85
	v_add_f32_e32 v85, 1.0, v161
	v_xor_b32_e32 v176, 0x80000000, v172
	v_mul_f32_e32 v161, 0x3f317217, v147
	v_fma_f32 v161, v147, s57, -v161
	v_fmac_f32_e32 v161, 0x3377d1cf, v147
	v_fmac_f32_e32 v161, 0x3f317217, v147
	v_cmp_lt_f32_e64 s[0:1], |v147|, s58
	s_waitcnt vmcnt(5)
	v_mfma_f32_16x16x32_bf16 v[64:67], v[64:67], v[16:19], v[68:71]
	v_xor_b32_e32 v175, 0x80000000, v171
	v_cndmask_b32_e64 v147, v147, v161, s[0:1]
	v_cndmask_b32_e32 v161, 0, v243, vcc
	v_sub_f32_e32 v147, v147, v161
	v_add_f32_e32 v146, v146, v147
	v_sub_f32_e32 v146, -0.5, v146
	v_mul_f32_e32 v146, 0x3fb8aa3b, v146
	v_exp_f32_e32 v147, v146
	v_add_f32_e32 v146, v185, v173
	v_mul_f32_e32 v146, 0xbfb8aa3b, v146
	v_exp_f32_e32 v161, v146
	v_rcp_f32_e32 v146, v85
	v_mul_f32_e32 v85, 0xbfb8aa3b, v147
	v_exp_f32_e32 v169, v85
	v_add_f32_e32 v85, 1.0, v161
	v_rcp_f32_e32 v147, v85
	v_and_b32_e32 v173, 0xffff0000, v178
	v_xor_b32_e32 v177, 0x80000000, v173
	v_or_b32_e32 v70, 32, v181
	v_xor_b32_e32 v174, 0x80000000, v170
	v_pk_fma_f32 v[176:177], v[0:1], v[186:187], v[176:177] op_sel_hi:[0,1,1]
	s_waitcnt vmcnt(3)
	v_pk_fma_f32 v[60:61], v[60:61], v[190:191], v[102:103]
	v_lshlrev_b32_e32 v102, 2, v70
	v_mov_b32_e32 v103, v3
	v_pk_fma_f32 v[174:175], v[0:1], v[188:189], v[174:175] op_sel_hi:[0,1,1]
	v_pk_fma_f32 v[76:77], v[76:77], v[176:177], v[172:173]
	v_pk_add_f32 v[172:173], v[140:141], -1.0 op_sel_hi:[1,0]
	v_pk_add_f32 v[72:73], v[146:147], -1.0 op_sel_hi:[1,0]
	v_pk_fma_f32 v[62:63], v[62:63], v[192:193], v[104:105]
	v_lshl_add_u64 v[68:69], v[86:87], 0, v[102:103]
	v_lshlrev_b32_e32 v104, 1, v70
	v_mov_b32_e32 v105, v3
	s_waitcnt vmcnt(1)
	v_pk_fma_f32 v[80:81], v[162:163], v[172:173], 1.0 op_sel_hi:[1,1,0]
	v_pk_fma_f32 v[170:171], v[78:79], v[174:175], v[170:171]
	v_pk_fma_f32 v[72:73], v[164:165], v[72:73], 1.0 op_sel_hi:[1,1,0]
	v_sub_u32_e32 v233, v68, v230
	ds_write_b128 v233, v[166:169]
	v_lshl_add_u64 v[68:69], v[86:87], 0, v[104:105]
	v_cvt_pk_bf16_f32 v60, v60, v61
	v_cvt_pk_bf16_f32 v61, v62, v63
	s_or_b32 s0, s5, 48
	v_pk_mul_f32 v[162:163], v[76:77], v[80:81]
	v_pk_mul_f32 v[164:165], v[170:171], v[72:73]
	v_sub_u32_e32 v233, v68, v230
	ds_write_b64 v233, v[60:61] offset:640
	v_cvt_pk_bf16_f32 v60, v158, v159
	v_cvt_pk_bf16_f32 v61, v156, v157
	v_or_b32_e32 v161, s0, v180
	v_cvt_pk_bf16_f32 v70, v162, v163
	v_cvt_pk_bf16_f32 v71, v164, v165
	v_sub_u32_e32 v233, v68, v230
	ds_write_b64 v233, v[60:61] offset:768
	v_cvt_pk_bf16_f32 v60, v64, v65
	v_cvt_pk_bf16_f32 v61, v66, v67
	v_lshlrev_b32_e32 v64, 7, v161
	v_mov_b32_e32 v65, v3
	v_sub_u32_e32 v233, v68, v230
	ds_write_b64 v233, v[70:71] offset:512
	global_store_dwordx2 v[124:125], v[60:61], off offset:64
	v_lshl_add_u64 v[68:69], v[88:89], 0, v[64:65]
	global_load_dwordx4 v[60:63], v[68:69], off
	v_lshl_add_u64 v[70:71], v[92:93], 0, v[64:65]
	global_load_dwordx4 v[64:67], v[70:71], off
	global_load_dwordx4 v[72:75], v[68:69], off offset:64
	global_load_dwordx4 v[80:83], v[70:71], off offset:64
	global_load_dwordx2 v[166:167], v[90:91], off offset:96
	global_load_dwordx2 v[168:169], v[90:91], off offset:1632
	global_load_dwordx2 v[172:173], v[90:91], off offset:3168
	global_load_dwordx2 v[174:175], v[96:97], off offset:96
	global_load_dwordx2 v[176:177], v[96:97], off offset:1632
	v_and_b32_e32 v69, 64, v240
	v_xor_b32_e32 v68, 16, v240
	v_add_u32_e32 v69, 64, v69
	v_cmp_lt_i32_e32 vcc, v68, v69
	v_ashrrev_i32_e32 v85, 31, v84
	global_load_dwordx2 v[178:179], v[96:97], off offset:3168
	v_cndmask_b32_e32 v68, v240, v68, vcc
	v_lshlrev_b32_e32 v182, 2, v68
	v_xor_b32_e32 v68, 32, v240
	v_cmp_lt_i32_e32 vcc, v68, v69
	s_waitcnt vmcnt(4)
; __device__ __forceinline__ void rwkv_prep_item(const Params& p, const Lt& lt, int l, int item) {
;     ...
;         for (int ct = 0; ct < 4; ++ct) {
;             const int crow = h * 64 + ct * 16 + qi;
;             f32x4 aw = {0.f, 0.f, 0.f, 0.f}, aa = aw, ag = aw;
; #pragma unroll
;             for (int ks = 0; ks < 2; ++ks) {
;                 aw = __builtin_amdgcn_mfma_f32_16x16x32_bf16(*(const bf16x8*)(decT + crow * 64 + ks * 32 + quad * 8), fw[ks], aw, 0, 0, 0);
;                 aa = __builtin_amdgcn_mfma_f32_16x16x32_bf16(*(const bf16x8*)(aT + crow * 64 + ks * 32 + quad * 8), fa[ks], aa, 0, 0, 0);
;             }
; #pragma unroll
;             for (int ks = 0; ks < 4; ++ks) ag = __builtin_amdgcn_mfma_f32_16x16x32_bf16(*(const bf16x8*)(gT + crow * 128 + ks * 32 + quad * 8), fg[ks], ag, 0, 0, 0);
;             const int c = h * 64 + ct * 16 + quad * 4;
;             const f32x4 mr = *(const f32x4*)(mu + c), mk = *(const f32x4*)(mu + COL_K + c), mv = *(const f32x4*)(mu + COL_V + c);
;             const f32x4 cr = ld_bf4(pt + c), ck = ld_bf4(pt + COL_K + c), cv = ld_bf4(pt + COL_V + c);
;             const f32x4 qr = ld_bf4(pp + c) * pm, qk = ld_bf4(pp + COL_K + c) * pm, qv = ld_bf4(pp + COL_V + c) * pm;
;             const f32x4 r = cr + (qr - cr) * mr, k = ck + (qk - ck) * mk, v = cv + (qv - cv) * mv;
;             const f32x4 w0v = *(const f32x4*)(w0 + c), a0v = *(const f32x4*)(a0 + c), kkv = *(const f32x4*)(kkp + c), kav = *(const f32x4*)(kap + c), rkv = *(const f32x4*)(rkp + c);
;             f32x4 dec, a, kk, k2;
; #pragma unroll
;             for (int j = 0; j < 4; ++j) {
;                 const float z = -(w0v[j] + aw[j]);
;                 const float sp = fmaxf(z, 0.f) + __logf(1.0f + __expf(-fabsf(z)));
;                 dec[j] = __expf(-__expf(-sp - 0.5f));
;                 a[j] = sigmoidf_(a0v[j] + aa[j]);
;                 kk[j] = k[j] * kkv[j];
;                 nrm += kk[j] * kk[j];
;                 k2[j] = k[j] * (1.0f + (a[j] - 1.0f) * kav[j]);
;                 bon += r[j] * k2[j] * rkv[j];
;             }
;             va[ct] = a; vkk[ct] = kk;
;             { const int cc = ct * 16 + quad * 4; *(f32x4*)(ob + cc * 4) = dec; st_bf4(ob + 512 + cc * 2, k2); st_bf4(ob + 640 + cc * 2, v); st_bf4(ob + 768 + cc * 2, r); }
;             st_bf4((unsigned char*)((bf16_t*)gate + (size_t)t * RW + c), ag);
;         }
	v_lshlrev_b32_e32 v204, 16, v168
	v_cndmask_b32_e32 v68, v240, v68, vcc
	v_cmp_eq_u32_e32 vcc, 0, v1
	v_mul_f32_e32 v1, v128, v136
	v_lshlrev_b32_e32 v183, 2, v68
	v_lshlrev_b64 v[68:69], 6, v[84:85]
	v_pk_mul_f32 v[84:85], v[36:37], v[138:139]
	v_fma_f32 v1, v40, v1, 0
	v_mul_f32_e32 v40, v129, v137
	v_pk_mul_f32 v[36:37], v[84:85], v[84:85]
	v_fmac_f32_e32 v1, v41, v40
	v_mul_f32_e32 v40, v98, v134
	v_pk_mul_f32 v[136:137], v[38:39], v[132:133]
	v_fmac_f32_e32 v1, v42, v40
	v_pk_mul_f32 v[38:39], v[136:137], v[136:137]
	v_mul_f32_e32 v40, v99, v135
	v_add_f32_e32 v36, v36, v37
	v_fmac_f32_e32 v1, v43, v40
	v_pk_mul_f32 v[132:133], v[48:49], v[152:153]
	v_mul_f32_e32 v42, v144, v154
	v_add_f32_e32 v36, v38, v36
	v_pk_mul_f32 v[40:41], v[132:133], v[132:133]
	v_fmac_f32_e32 v1, v44, v42
	v_mul_f32_e32 v42, v145, v155
	global_load_dwordx4 v[152:155], v160, s[8:9] offset:192
	v_pk_mul_f32 v[128:129], v[56:57], v[76:77]
	global_load_dwordx4 v[76:79], v160, s[42:43] offset:192
	v_add_f32_e32 v36, v39, v36
	v_fmac_f32_e32 v1, v45, v42
	v_mul_f32_e32 v42, v142, v150
	v_pk_mul_f32 v[134:135], v[50:51], v[148:149]
	v_add_f32_e32 v36, v36, v40
	v_fmac_f32_e32 v1, v46, v42
	v_pk_mul_f32 v[42:43], v[134:135], v[134:135]
	v_mul_f32_e32 v44, v143, v151
	v_add_f32_e32 v36, v41, v36
	v_fmac_f32_e32 v1, v47, v44
	v_mul_f32_e32 v46, v158, v162
	v_add_f32_e32 v36, v42, v36
	v_pk_mul_f32 v[44:45], v[128:129], v[128:129]
	v_fmac_f32_e32 v1, v52, v46
	v_mul_f32_e32 v46, v159, v163
	v_add_f32_e32 v36, v43, v36
	v_fmac_f32_e32 v1, v53, v46
	v_mul_f32_e32 v46, v156, v164
	v_pk_mul_f32 v[138:139], v[58:59], v[170:171]
	v_add_f32_e32 v36, v36, v44
	v_fmac_f32_e32 v1, v54, v46
	v_pk_mul_f32 v[46:47], v[138:139], v[138:139]
	v_add_f32_e32 v36, v45, v36
	v_add_f32_e32 v36, v46, v36
	v_add_f32_e32 v184, v47, v36
	v_mul_f32_e32 v36, v157, v165
	v_fmac_f32_e32 v1, v55, v36
	v_lshlrev_b32_e32 v36, 8, v161
	v_mov_b32_e32 v37, v3
	v_lshl_add_u64 v[36:37], v[94:95], 0, v[36:37]
	v_lshl_add_u64 v[90:91], s[40:41], 0, v[68:69]
	global_load_dwordx4 v[68:71], v160, s[44:45] offset:192
	v_mfma_f32_16x16x32_bf16 v[40:43], v[60:63], v[20:23], 0
	global_load_dwordx4 v[52:55], v[36:37], off
	global_load_dwordx4 v[48:51], v[36:37], off offset:64
	global_load_dwordx4 v[44:47], v[36:37], off offset:128
	s_nop 0
	global_load_dwordx4 v[36:39], v[36:37], off offset:192
	v_lshlrev_b32_e32 v144, 16, v166
	v_and_b32_e32 v145, 0xffff0000, v166
	v_mfma_f32_16x16x32_bf16 v[96:99], v[64:67], v[28:31], 0
	global_load_dwordx4 v[64:67], v160, s[8:9] offset:3264
	global_load_dwordx4 v[56:59], v160, s[46:47] offset:192
	global_load_dwordx4 v[60:63], v160, s[48:49] offset:192
	s_waitcnt vmcnt(12)
	v_lshlrev_b32_e32 v150, 16, v175
	v_and_b32_e32 v151, 0xffff0000, v175
	v_mfma_f32_16x16x32_bf16 v[156:159], v[72:75], v[24:27], v[40:43]
	v_lshlrev_b32_e32 v72, 16, v174
	v_and_b32_e32 v73, 0xffff0000, v174
	v_xor_b32_e32 v75, 0x80000000, v145
	v_xor_b32_e32 v74, 0x80000000, v144
	v_pk_fma_f32 v[174:175], v[0:1], v[72:73], v[74:75] op_sel_hi:[0,1,1]
	global_load_dwordx4 v[72:75], v160, s[50:51] offset:192
	v_or_b32_e32 v40, s0, v181
	v_lshlrev_b32_e32 v142, 16, v167
	v_and_b32_e32 v143, 0xffff0000, v167
	v_xor_b32_e32 v161, 0x80000000, v143
	v_xor_b32_e32 v160, 0x80000000, v142
	v_lshlrev_b32_e32 v164, 16, v169
	v_and_b32_e32 v148, 0xffff0000, v169
	v_pk_fma_f32 v[150:151], v[0:1], v[150:151], v[160:161] op_sel_hi:[0,1,1]
	v_and_b32_e32 v162, 0xffff0000, v168
	s_waitcnt vmcnt(12)
	v_lshlrev_b32_e32 v168, 16, v177
	v_and_b32_e32 v169, 0xffff0000, v177
	v_lshlrev_b32_e32 v40, 2, v40
	global_load_dwordx4 v[40:43], v40, s[52:53]
	v_mfma_f32_16x16x32_bf16 v[80:83], v[80:83], v[32:35], v[96:99]
	v_lshlrev_b32_e32 v166, 16, v176
	v_and_b32_e32 v167, 0xffff0000, v176
	s_waitcnt vmcnt(12)
	v_lshlrev_b32_e32 v170, 16, v178
	v_lshlrev_b32_e32 v96, 16, v172
	v_and_b32_e32 v97, 0xffff0000, v172
	v_lshlrev_b32_e32 v98, 16, v173
	v_and_b32_e32 v99, 0xffff0000, v173
	v_and_b32_e32 v171, 0xffff0000, v178
	v_lshlrev_b32_e32 v172, 16, v179
	v_and_b32_e32 v173, 0xffff0000, v179
	v_xor_b32_e32 v161, 0x80000000, v99
	v_xor_b32_e32 v160, 0x80000000, v98
	v_pk_fma_f32 v[160:161], v[0:1], v[172:173], v[160:161] op_sel_hi:[0,1,1]
	v_mov_b32_e32 v163, v205
	s_waitcnt vmcnt(8)
	v_mfma_f32_16x16x32_bf16 v[52:55], v[52:55], v[4:7], 0
	v_add_f32_e32 v76, v156, v76
	v_mul_f32_e64 v149, |v76|, s10
	v_exp_f32_e32 v149, v149
	v_pk_fma_f32 v[142:143], v[154:155], v[150:151], v[142:143]
	v_xor_b32_e32 v151, 0x80000000, v148
	v_xor_b32_e32 v150, 0x80000000, v164
	v_add_f32_e32 v149, 1.0, v149
	v_cmp_gt_f32_e64 s[0:1], s75, v149
	v_pk_fma_f32 v[144:145], v[152:153], v[174:175], v[144:145]
	v_pk_fma_f32 v[152:153], v[0:1], v[168:169], v[150:151] op_sel_hi:[0,1,1]
	v_cndmask_b32_e64 v156, 0, 32, s[0:1]
	v_ldexp_f32 v149, v149, v156
	v_log_f32_e32 v149, v149
	s_waitcnt vmcnt(2)
; __device__ __forceinline__ float quad_sum(float v) { v += xor16(v); v += xor32(v); return v; }
; __device__ __forceinline__ float sigmoidf_(float x) { return __builtin_amdgcn_rcpf(1.0f + __expf(-x)); }
; __device__ __forceinline__ void st_bf4(unsigned char* q, f32x4 v) { u32x2 w; w.x = cvt_pk_bf16(v[0], v[1]); w.y = cvt_pk_bf16(v[2], v[3]); *(u32x2*)q = w; }
; __device__ __forceinline__ void rwkv_prep_item(const Params& p, const Lt& lt, int l, int item) {
;     ...
;             for (int j = 0; j < 4; ++j) {
;                 const float z = -(w0v[j] + aw[j]);
;                 const float sp = fmaxf(z, 0.f) + __logf(1.0f + __expf(-fabsf(z)));
;                 dec[j] = __expf(-__expf(-sp - 0.5f));
;                 a[j] = sigmoidf_(a0v[j] + aa[j]);
;                 kk[j] = k[j] * kkv[j];
;                 nrm += kk[j] * kk[j];
;                 k2[j] = k[j] * (1.0f + (a[j] - 1.0f) * kav[j]);
;                 bon += r[j] * k2[j] * rkv[j];
;             }
;             va[ct] = a; vkk[ct] = kk;
;             { const int cc = ct * 16 + quad * 4; *(f32x4*)(ob + cc * 4) = dec; st_bf4(ob + 512 + cc * 2, k2); st_bf4(ob + 640 + cc * 2, v); st_bf4(ob + 768 + cc * 2, r); }
;             st_bf4((unsigned char*)((bf16_t*)gate + (size_t)t * RW + c), ag);
;         }
;         nrm = quad_sum(nrm); bon = quad_sum(bon);
;         const float inv = rsqrtf(fmaxf(nrm, 1e-24f));
	v_mov_b32_e32 v169, v60
	v_add_f32_e32 v60, v157, v77
	v_mov_b32_e32 v168, v64
	v_mul_f32_e64 v64, |v60|, s10
	v_exp_f32_e32 v64, v64
	v_mul_f32_e32 v156, 0x3f317217, v149
	v_fma_f32 v156, v149, s57, -v156
	v_fmac_f32_e32 v156, 0x3377d1cf, v149
	v_fmac_f32_e32 v156, 0x3f317217, v149
	v_cmp_lt_f32_e64 s[4:5], |v149|, s58
	v_add_f32_e32 v64, 1.0, v64
	v_add_f32_e32 v68, v80, v68
	v_cndmask_b32_e64 v149, v149, v156, s[4:5]
	v_cndmask_b32_e64 v156, 0, v243, s[0:1]
	v_cmp_gt_f32_e64 s[0:1], s75, v64
	v_mul_f32_e32 v68, 0xbfb8aa3b, v68
	v_exp_f32_e32 v68, v68
	v_cndmask_b32_e64 v77, 0, 32, s[0:1]
	v_ldexp_f32 v64, v64, v77
	v_log_f32_e32 v64, v64
	v_add_f32_e32 v68, 1.0, v68
	v_max_f32_e64 v60, -v60, 0
	v_rcp_f32_e32 v68, v68
	v_mul_f32_e32 v80, 0x3f317217, v64
	v_fma_f32 v80, v64, s57, -v80
	v_fmac_f32_e32 v80, 0x3377d1cf, v64
	v_fmac_f32_e32 v80, 0x3f317217, v64
	v_cmp_lt_f32_e64 s[4:5], |v64|, s58
	v_xor_b32_e32 v151, 0x80000000, v162
	v_xor_b32_e32 v150, 0x80000000, v204
	v_cndmask_b32_e64 v64, v64, v80, s[4:5]
	v_cndmask_b32_e64 v80, 0, v243, s[0:1]
	v_sub_f32_e32 v64, v64, v80
	v_add_f32_e32 v60, v60, v64
	v_add_f32_e32 v64, v81, v69
	v_mul_f32_e32 v64, 0xbfb8aa3b, v64
	v_sub_f32_e32 v60, -0.5, v60
	v_exp_f32_e32 v64, v64
	v_mul_f32_e32 v60, 0x3fb8aa3b, v60
	v_pk_fma_f32 v[154:155], v[0:1], v[166:167], v[150:151] op_sel_hi:[0,1,1]
	v_exp_f32_e32 v60, v60
	v_add_f32_e32 v167, -1.0, v68
	v_mov_b32_e32 v166, v154
	v_sub_f32_e32 v149, v149, v156
	v_pk_fma_f32 v[156:157], v[168:169], v[166:167], v[204:205]
	v_add_f32_e32 v64, 1.0, v64
	v_mul_f32_e32 v56, v56, v156
	v_pk_mul_f32 v[156:157], v[156:157], v[156:157] op_sel:[0,1] op_sel_hi:[1,0]
	v_xor_b32_e32 v151, 0x80000000, v97
	v_xor_b32_e32 v150, 0x80000000, v96
	v_mul_f32_e32 v77, v144, v156
	v_rcp_f32_e32 v69, v64
	v_mul_f32_e32 v60, 0xbfb8aa3b, v60
	v_add_f32_e32 v64, v158, v78
	v_pk_fma_f32 v[150:151], v[0:1], v[170:171], v[150:151] op_sel_hi:[0,1,1]
	s_waitcnt vmcnt(1)
	v_fmac_f32_e32 v1, v72, v77
	v_exp_f32_e32 v77, v60
	v_mov_b32_e32 v60, v65
	v_mul_f32_e64 v65, |v64|, s10
	v_exp_f32_e32 v65, v65
	v_max_f32_e64 v64, -v64, 0
	v_add_f32_e32 v81, -1.0, v69
	v_mov_b32_e32 v80, v155
	v_add_f32_e32 v65, 1.0, v65
	v_cmp_gt_f32_e64 s[0:1], s75, v65
	v_pk_fma_f32 v[60:61], v[60:61], v[80:81], v[162:163]
	v_mov_b32_e32 v81, v62
	v_cndmask_b32_e64 v72, 0, 32, s[0:1]
	v_ldexp_f32 v65, v65, v72
	v_log_f32_e32 v65, v65
	v_mul_f32_e32 v57, v57, v60
	v_pk_mul_f32 v[60:61], v[60:61], v[60:61] op_sel:[0,1] op_sel_hi:[1,0]
	v_max_f32_e64 v76, -v76, 0
	v_mul_f32_e32 v72, 0x3f317217, v65
	v_fma_f32 v72, v65, s57, -v72
	v_fmac_f32_e32 v72, 0x3377d1cf, v65
	v_fmac_f32_e32 v72, 0x3f317217, v65
	v_cmp_lt_f32_e64 s[4:5], |v65|, s58
	v_mul_f32_e32 v61, v145, v60
	v_fmac_f32_e32 v1, v73, v61
	v_cndmask_b32_e64 v65, v65, v72, s[4:5]
	v_cndmask_b32_e64 v72, 0, v243, s[0:1]
	v_sub_f32_e32 v65, v65, v72
	v_add_f32_e32 v64, v64, v65
	v_sub_f32_e32 v64, -0.5, v64
	v_mul_f32_e32 v64, 0x3fb8aa3b, v64
	v_add_f32_e32 v65, v82, v70
	v_exp_f32_e32 v70, v64
	v_mul_f32_e32 v65, 0xbfb8aa3b, v65
	v_exp_f32_e32 v65, v65
	v_add_f32_e32 v76, v76, v149
	v_mul_f32_e32 v61, 0xbfb8aa3b, v70
	v_exp_f32_e32 v78, v61
	v_add_f32_e32 v61, v159, v79
	v_mul_f32_e64 v62, |v61|, s10
	v_exp_f32_e32 v62, v62
	v_add_f32_e32 v64, 1.0, v65
	v_max_f32_e64 v61, -v61, 0
	v_sub_f32_e32 v76, -0.5, v76
	v_add_f32_e32 v62, 1.0, v62
	v_cmp_gt_f32_e64 s[0:1], s75, v62
	v_mfma_f32_16x16x32_bf16 v[48:51], v[48:51], v[8:11], v[52:55]
	v_mul_f32_e32 v76, 0x3fb8aa3b, v76
	v_cndmask_b32_e64 v65, 0, 32, s[0:1]
	v_ldexp_f32 v62, v62, v65
	v_log_f32_e32 v62, v62
	v_exp_f32_e32 v76, v76
	v_rcp_f32_e32 v64, v64
	v_mfma_f32_16x16x32_bf16 v[44:47], v[44:47], v[12:15], v[48:51]
	v_mul_f32_e32 v65, 0x3f317217, v62
	v_fma_f32 v65, v62, s57, -v65
	v_fmac_f32_e32 v65, 0x3377d1cf, v62
	v_fmac_f32_e32 v65, 0x3f317217, v62
	v_cmp_lt_f32_e64 s[4:5], |v62|, s58
	v_mul_f32_e32 v76, 0xbfb8aa3b, v76
	v_exp_f32_e32 v76, v76
	v_cndmask_b32_e64 v62, v62, v65, s[4:5]
	v_cndmask_b32_e64 v65, 0, v243, s[0:1]
	v_sub_f32_e32 v62, v62, v65
	v_add_f32_e32 v61, v61, v62
	v_add_f32_e32 v62, v83, v71
	v_mul_f32_e32 v62, 0xbfb8aa3b, v62
	v_exp_f32_e32 v62, v62
	v_sub_f32_e32 v61, -0.5, v61
	v_mul_f32_e32 v61, 0x3fb8aa3b, v61
	v_exp_f32_e32 v61, v61
	v_add_f32_e32 v62, 1.0, v62
	v_rcp_f32_e32 v65, v62
	v_add_f32_e32 v73, -1.0, v64
	v_mul_f32_e32 v61, 0xbfb8aa3b, v61
	v_mov_b32_e32 v80, v66
	v_mov_b32_e32 v72, v152
	v_mov_b32_e32 v165, v205
	v_exp_f32_e32 v79, v61
	v_fmac_f32_e32 v184, v56, v56
	v_pk_fma_f32 v[72:73], v[80:81], v[72:73], v[164:165]
	v_add_f32_e32 v71, -1.0, v65
	v_mov_b32_e32 v62, v67
	v_mov_b32_e32 v70, v153
	v_mov_b32_e32 v149, v205
	v_mfma_f32_16x16x32_bf16 v[36:39], v[36:39], v[16:19], v[44:47]
	v_fmac_f32_e32 v184, v57, v57
	v_mul_f32_e32 v58, v58, v72
	v_pk_fma_f32 v[52:53], v[62:63], v[70:71], v[148:149]
	v_or_b32_e32 v46, 48, v181
	s_waitcnt vmcnt(0)
	v_pk_fma_f32 v[40:41], v[40:41], v[150:151], v[96:97]
	v_lshlrev_b32_e32 v96, 2, v46
	v_mov_b32_e32 v97, v3
	v_fmac_f32_e32 v184, v58, v58
	v_pk_mul_f32 v[72:73], v[72:73], v[72:73] op_sel:[0,1] op_sel_hi:[1,0]
	v_mul_f32_e32 v59, v59, v52
	v_pk_mul_f32 v[48:49], v[52:53], v[52:53] op_sel:[0,1] op_sel_hi:[1,0]
	v_pk_fma_f32 v[42:43], v[42:43], v[160:161], v[98:99]
	v_lshl_add_u64 v[44:45], v[86:87], 0, v[96:97]
	v_lshlrev_b32_e32 v98, 1, v46
	v_mov_b32_e32 v99, v3
	v_fmac_f32_e32 v184, v59, v59
	v_sub_u32_e32 v233, v44, v230
	ds_write_b128 v233, v[76:79]
	v_lshl_add_u64 v[44:45], v[86:87], 0, v[98:99]
	v_cvt_pk_bf16_f32 v46, v156, v60
	v_cvt_pk_bf16_f32 v47, v72, v48
	v_sub_u32_e32 v233, v44, v230
	ds_write_b64 v233, v[46:47] offset:512
	ds_bpermute_b32 v46, v182, v184
	v_cvt_pk_bf16_f32 v40, v40, v41
	v_cvt_pk_bf16_f32 v41, v42, v43
	v_mul_f32_e32 v66, v142, v72
	v_fmac_f32_e32 v1, v74, v66
	s_waitcnt lgkmcnt(0)
; __device__ __forceinline__ float quad_sum(float v) { v += xor16(v); v += xor32(v); return v; }
; __device__ __forceinline__ float sigmoidf_(float x) { return __builtin_amdgcn_rcpf(1.0f + __expf(-x)); }
; __device__ __forceinline__ void rwkv_prep_item(const Params& p, const Lt& lt, int l, int item) {
;     ...
;             const int c = h * 64 + ct * 16 + quad * 4;
;             const f32x4 mr = *(const f32x4*)(mu + c), mk = *(const f32x4*)(mu + COL_K + c), mv = *(const f32x4*)(mu + COL_V + c);
;             const f32x4 cr = ld_bf4(pt + c), ck = ld_bf4(pt + COL_K + c), cv = ld_bf4(pt + COL_V + c);
;             const f32x4 qr = ld_bf4(pp + c) * pm, qk = ld_bf4(pp + COL_K + c) * pm, qv = ld_bf4(pp + COL_V + c) * pm;
;             const f32x4 r = cr + (qr - cr) * mr, k = ck + (qk - ck) * mk, v = cv + (qv - cv) * mv;
;             const f32x4 w0v = *(const f32x4*)(w0 + c), a0v = *(const f32x4*)(a0 + c), kkv = *(const f32x4*)(kkp + c), kav = *(const f32x4*)(kap + c), rkv = *(const f32x4*)(rkp + c);
;             f32x4 dec, a, kk, k2;
; #pragma unroll
;             for (int j = 0; j < 4; ++j) {
;                 const float z = -(w0v[j] + aw[j]);
;                 const float sp = fmaxf(z, 0.f) + __logf(1.0f + __expf(-fabsf(z)));
;                 dec[j] = __expf(-__expf(-sp - 0.5f));
;                 a[j] = sigmoidf_(a0v[j] + aa[j]);
;                 kk[j] = k[j] * kkv[j];
;                 nrm += kk[j] * kk[j];
;                 k2[j] = k[j] * (1.0f + (a[j] - 1.0f) * kav[j]);
;                 bon += r[j] * k2[j] * rkv[j];
;             }
;             va[ct] = a; vkk[ct] = kk;
;             { const int cc = ct * 16 + quad * 4; *(f32x4*)(ob + cc * 4) = dec; st_bf4(ob + 512 + cc * 2, k2); st_bf4(ob + 640 + cc * 2, v); st_bf4(ob + 768 + cc * 2, r); }
;             st_bf4((unsigned char*)((bf16_t*)gate + (size_t)t * RW + c), ag);
;         }
;         nrm = quad_sum(nrm); bon = quad_sum(bon);
;         const float inv = rsqrtf(fmaxf(nrm, 1e-24f));
; #pragma unroll
;         for (int ct = 0; ct < 4; ++ct) {
;             const int cc = ct * 16 + quad * 4;
;             const f32x4 kkn = vkk[ct] * inv;
;             st_bf4(ob + 256 + cc * 2, -kkn);
;             st_bf4(ob + 384 + cc * 2, kkn * va[ct]);
;         }
;         if (quad == 0) bonus[(size_t)t * 16 + h] = bon;
	v_add_f32_e32 v42, v184, v46
	ds_bpermute_b32 v43, v183, v42
	v_mul_f32_e32 v49, v143, v48
	v_fmac_f32_e32 v1, v75, v49
	v_cvt_pk_bf16_f32 v36, v36, v37
	v_cvt_pk_bf16_f32 v37, v38, v39
	s_waitcnt lgkmcnt(0)
	v_add_f32_e32 v38, v42, v43
	ds_bpermute_b32 v39, v182, v1
	v_max_f32_e32 v38, 0x179abe15, v38
	v_rsq_f32_e32 v38, v38
	v_sub_u32_e32 v233, v44, v230
	ds_write_b64 v233, v[40:41] offset:640
	v_cvt_pk_bf16_f32 v40, v144, v145
	v_cvt_pk_bf16_f32 v41, v142, v143
	v_sub_u32_e32 v233, v44, v230
	ds_write_b64 v233, v[40:41] offset:768
	s_waitcnt lgkmcnt(0)
	v_pk_mul_f32 v[40:41], v[84:85], v[38:39] op_sel_hi:[1,0]
	v_pk_mul_f32 v[42:43], v[136:137], v[38:39] op_sel_hi:[1,0]
	global_store_dwordx2 v[124:125], v[36:37], off offset:96
	v_add_f32_e32 v1, v1, v39
	v_xor_b32_e32 v37, 0x80000000, v43
	v_xor_b32_e32 v39, 0x80000000, v42
	v_xor_b32_e32 v44, 0x80000000, v41
	v_xor_b32_e32 v45, 0x80000000, v40
	v_pk_mul_f32 v[42:43], v[120:121], v[42:43]
	v_pk_mul_f32 v[40:41], v[100:101], v[40:41]
	v_cvt_pk_bf16_f32 v44, v45, v44
	v_cvt_pk_bf16_f32 v40, v40, v41
	v_cvt_pk_bf16_f32 v41, v42, v43
	v_cvt_pk_bf16_f32 v45, v39, v37
	v_sub_u32_e32 v233, v122, v230
	ds_write_b64 v233, v[40:41] offset:384
	v_pk_mul_f32 v[40:41], v[132:133], v[38:39] op_sel_hi:[1,0]
	v_pk_mul_f32 v[42:43], v[134:135], v[38:39] op_sel_hi:[1,0]
	v_sub_u32_e32 v233, v122, v230
	ds_write_b64 v233, v[44:45] offset:256
	v_xor_b32_e32 v37, 0x80000000, v43
	v_xor_b32_e32 v39, 0x80000000, v42
	v_xor_b32_e32 v44, 0x80000000, v41
	v_xor_b32_e32 v45, 0x80000000, v40
	v_pk_mul_f32 v[42:43], v[130:131], v[42:43]
	v_pk_mul_f32 v[40:41], v[126:127], v[40:41]
	v_cvt_pk_bf16_f32 v44, v45, v44
	v_cvt_pk_bf16_f32 v40, v40, v41
	v_cvt_pk_bf16_f32 v41, v42, v43
	v_cvt_pk_bf16_f32 v45, v39, v37
	v_sub_u32_e32 v233, v122, v230
	ds_write_b64 v233, v[40:41] offset:416
	v_pk_mul_f32 v[40:41], v[128:129], v[38:39] op_sel_hi:[1,0]
	v_pk_mul_f32 v[42:43], v[138:139], v[38:39] op_sel_hi:[1,0]
	ds_bpermute_b32 v36, v183, v1
	v_sub_u32_e32 v233, v122, v230
	ds_write_b64 v233, v[44:45] offset:288
	v_xor_b32_e32 v37, 0x80000000, v43
	v_xor_b32_e32 v39, 0x80000000, v42
	v_xor_b32_e32 v44, 0x80000000, v41
	v_xor_b32_e32 v45, 0x80000000, v40
	v_pk_mul_f32 v[42:43], v[146:147], v[42:43]
	v_pk_mul_f32 v[40:41], v[140:141], v[40:41]
	v_cvt_pk_bf16_f32 v44, v45, v44
	v_cvt_pk_bf16_f32 v40, v40, v41
	v_cvt_pk_bf16_f32 v41, v42, v43
	v_cvt_pk_bf16_f32 v45, v39, v37
	v_sub_u32_e32 v233, v122, v230
	ds_write_b64 v233, v[40:41] offset:448
	v_pk_mul_f32 v[40:41], v[56:57], v[38:39] op_sel_hi:[1,0]
	v_pk_mul_f32 v[38:39], v[58:59], v[38:39] op_sel_hi:[1,0]
	v_sub_u32_e32 v233, v122, v230
	ds_write_b64 v233, v[44:45] offset:320
	v_xor_b32_e32 v37, 0x80000000, v39
	v_xor_b32_e32 v43, 0x80000000, v38
	v_xor_b32_e32 v42, 0x80000000, v41
	v_xor_b32_e32 v44, 0x80000000, v40
	v_pk_mul_f32 v[38:39], v[64:65], v[38:39]
	v_pk_mul_f32 v[40:41], v[68:69], v[40:41]
	v_cvt_pk_bf16_f32 v42, v44, v42
	v_cvt_pk_bf16_f32 v43, v43, v37
	v_cvt_pk_bf16_f32 v40, v40, v41
	v_cvt_pk_bf16_f32 v41, v38, v39
	v_sub_u32_e32 v233, v122, v230
	ds_write_b64 v233, v[42:43] offset:352
	v_sub_u32_e32 v233, v122, v230
	ds_write_b64 v233, v[40:41] offset:480
	s_waitcnt lgkmcnt(0)
	s_mov_b32 s98, -1
	s_mov_b32 s99, 0xffffff
	s_mov_b64 exec, s[98:99]
	s_movk_i32 s98, 0
	s_mov_b32 s99, 0
	v_lshl_add_u64 v[228:229], v[234:235], 0, s[98:99]
	s_movk_i32 s98, 0x2a00
	ds_read_b128 v[210:213], v226 offset:0
	ds_read_b128 v[214:217], v226 offset:912
	ds_read_b128 v[218:221], v226 offset:1824
	ds_read_b128 v[222:225], v226 offset:2736
	s_waitcnt lgkmcnt(3)
	global_store_dwordx4 v[228:229], v[210:213], off
	v_lshl_add_u64 v[228:229], v[228:229], 0, s[98:99]
	s_waitcnt lgkmcnt(2)
	global_store_dwordx4 v[228:229], v[214:217], off
	v_lshl_add_u64 v[228:229], v[228:229], 0, s[98:99]
	s_waitcnt lgkmcnt(1)
	global_store_dwordx4 v[228:229], v[218:221], off
	v_lshl_add_u64 v[228:229], v[228:229], 0, s[98:99]
	s_waitcnt lgkmcnt(0)
	global_store_dwordx4 v[228:229], v[222:225], off
	v_lshl_add_u64 v[228:229], v[228:229], 0, s[98:99]
	ds_read_b128 v[210:213], v226 offset:3648
	ds_read_b128 v[214:217], v226 offset:4560
	ds_read_b128 v[218:221], v226 offset:5472
	ds_read_b128 v[222:225], v226 offset:6384
	s_waitcnt lgkmcnt(3)
	global_store_dwordx4 v[228:229], v[210:213], off
	v_lshl_add_u64 v[228:229], v[228:229], 0, s[98:99]
	s_waitcnt lgkmcnt(2)
	global_store_dwordx4 v[228:229], v[214:217], off
	v_lshl_add_u64 v[228:229], v[228:229], 0, s[98:99]
	s_waitcnt lgkmcnt(1)
	global_store_dwordx4 v[228:229], v[218:221], off
	v_lshl_add_u64 v[228:229], v[228:229], 0, s[98:99]
	s_waitcnt lgkmcnt(0)
	global_store_dwordx4 v[228:229], v[222:225], off
	v_lshl_add_u64 v[228:229], v[228:229], 0, s[98:99]
	ds_read_b128 v[210:213], v226 offset:7296
	ds_read_b128 v[214:217], v226 offset:8208
	ds_read_b128 v[218:221], v226 offset:9120
	ds_read_b128 v[222:225], v226 offset:10032
	s_waitcnt lgkmcnt(3)
	global_store_dwordx4 v[228:229], v[210:213], off
	v_lshl_add_u64 v[228:229], v[228:229], 0, s[98:99]
	s_waitcnt lgkmcnt(2)
	global_store_dwordx4 v[228:229], v[214:217], off
	v_lshl_add_u64 v[228:229], v[228:229], 0, s[98:99]
	s_waitcnt lgkmcnt(1)
	global_store_dwordx4 v[228:229], v[218:221], off
	v_lshl_add_u64 v[228:229], v[228:229], 0, s[98:99]
	s_waitcnt lgkmcnt(0)
	global_store_dwordx4 v[228:229], v[222:225], off
	v_lshl_add_u64 v[228:229], v[228:229], 0, s[98:99]
	ds_read_b128 v[210:213], v226 offset:10944
	ds_read_b128 v[214:217], v226 offset:11856
	ds_read_b128 v[218:221], v226 offset:12768
	ds_read_b128 v[222:225], v226 offset:13680
	s_waitcnt lgkmcnt(3)
	global_store_dwordx4 v[228:229], v[210:213], off
	v_lshl_add_u64 v[228:229], v[228:229], 0, s[98:99]
	s_waitcnt lgkmcnt(2)
	global_store_dwordx4 v[228:229], v[214:217], off
	v_lshl_add_u64 v[228:229], v[228:229], 0, s[98:99]
	s_waitcnt lgkmcnt(1)
	global_store_dwordx4 v[228:229], v[218:221], off
	v_lshl_add_u64 v[228:229], v[228:229], 0, s[98:99]
	s_waitcnt lgkmcnt(0)
	global_store_dwordx4 v[228:229], v[222:225], off
	v_lshl_add_u64 v[228:229], v[228:229], 0, s[98:99]
	s_mov_b64 exec, -1
	s_and_saveexec_b64 s[0:1], vcc
	s_cbranch_execz .LBB0_345
	s_lshl_b32 s10, s56, 2
	v_lshl_add_u64 v[38:39], v[90:91], 0, s[10:11]
	s_waitcnt lgkmcnt(0)
	v_add_f32_e32 v1, v1, v36
	global_store_dword v[38:39], v1, off
; __device__ __forceinline__ f32x4 ld_bf4(const bf16_t* q) { const u32x2 u = *(const u32x2*)q; return (f32x4){bflo(u.x), bfhi(u.x), bflo(u.y), bfhi(u.y)}; }
; __device__ __forceinline__ void rwkv_prep_item(const Params& p, const Lt& lt, int l, int item) {
;     ...
;     for (int hh = 0; hh < 3; ++hh) {
;         const int h = hg * 3 + hh;
;         f32x4 va[4], vkk[4];
;         float nrm = 0.f, bon = 0.f;
;         unsigned char* ob = opnd + (size_t)t * OPTB + h * OPB;
; #pragma unroll
;         for (int ct = 0; ct < 4; ++ct) {
;             const int crow = h * 64 + ct * 16 + qi;
;             f32x4 aw = {0.f, 0.f, 0.f, 0.f}, aa = aw, ag = aw;
; #pragma unroll
;             for (int ks = 0; ks < 2; ++ks) {
;                 aw = __builtin_amdgcn_mfma_f32_16x16x32_bf16(*(const bf16x8*)(decT + crow * 64 + ks * 32 + quad * 8), fw[ks], aw, 0, 0, 0);
;                 aa = __builtin_amdgcn_mfma_f32_16x16x32_bf16(*(const bf16x8*)(aT + crow * 64 + ks * 32 + quad * 8), fa[ks], aa, 0, 0, 0);
;             }
; #pragma unroll
;             for (int ks = 0; ks < 4; ++ks) ag = __builtin_amdgcn_mfma_f32_16x16x32_bf16(*(const bf16x8*)(gT + crow * 128 + ks * 32 + quad * 8), fg[ks], ag, 0, 0, 0);
;             const int c = h * 64 + ct * 16 + quad * 4;
;             const f32x4 mr = *(const f32x4*)(mu + c), mk = *(const f32x4*)(mu + COL_K + c), mv = *(const f32x4*)(mu + COL_V + c);
;             const f32x4 cr = ld_bf4(pt + c), ck = ld_bf4(pt + COL_K + c), cv = ld_bf4(pt + COL_V + c);
;             const f32x4 qr = ld_bf4(pp + c) * pm, qk = ld_bf4(pp + COL_K + c) * pm, qv = ld_bf4(pp + COL_V + c) * pm;
;             const f32x4 r = cr + (qr - cr) * mr, k = ck + (qk - ck) * mk, v = cv + (qv - cv) * mv;
;             const f32x4 w0v = *(const f32x4*)(w0 + c), a0v = *(const f32x4*)(a0 + c), kkv = *(const f32x4*)(kkp + c), kav = *(const f32x4*)(kap + c), rkv = *(const f32x4*)(rkp + c);
.LBB0_345:
	s_or_b64 exec, exec, s[0:1]
	s_add_i32 s0, s56, 1
	s_mul_i32 s10, s0, 0x380
	v_lshl_add_u64 v[120:121], v[118:119], 0, s[10:11]
	s_lshl_b32 s10, s0, 6
	v_or_b32_e32 v40, s10, v180
	s_waitcnt lgkmcnt(0)
	v_lshlrev_b32_e32 v36, 7, v40
	v_mov_b32_e32 v37, v3
	v_lshl_add_u64 v[38:39], v[88:89], 0, v[36:37]
	v_lshl_add_u64 v[36:37], v[92:93], 0, v[36:37]
	global_load_dwordx4 v[52:55], v[38:39], off
	global_load_dwordx4 v[56:59], v[36:37], off
	global_load_dwordx4 v[60:63], v[38:39], off offset:64
	global_load_dwordx4 v[68:71], v[36:37], off offset:64
	v_or_b32_e32 v72, s10, v181
	v_lshlrev_b32_e32 v36, 8, v40
	v_mov_b32_e32 v37, v3
	v_lshlrev_b32_e32 v140, 1, v72
	v_mov_b32_e32 v141, v3
	v_lshl_add_u64 v[36:37], v[94:95], 0, v[36:37]
	v_lshlrev_b32_e32 v184, 2, v72
	v_lshl_add_u64 v[134:135], v[114:115], 0, v[140:141]
	global_load_dwordx4 v[48:51], v[36:37], off
	global_load_dwordx4 v[44:47], v[36:37], off offset:64
	global_load_dwordx4 v[40:43], v[36:37], off offset:128
	s_nop 0
	global_load_dwordx4 v[36:39], v[36:37], off offset:192
	v_lshl_add_u64 v[132:133], v[110:111], 0, v[140:141]
	v_mov_b32_e32 v1, v0
	v_mov_b32_e32 v100, v0
	v_mov_b32_e32 v101, v0
	s_mov_b32 s57, 0xbfb8aa3b
	s_mov_b32 s58, 0x3f317217
	s_mov_b32 s59, 0x7f800000
	v_lshl_add_u64 v[140:141], v[116:117], 0, v[140:141]
	s_waitcnt vmcnt(7)
	v_mfma_f32_16x16x32_bf16 v[52:55], v[52:55], v[20:23], 0
	s_waitcnt vmcnt(6)
	v_mfma_f32_16x16x32_bf16 v[56:59], v[56:59], v[28:31], 0
	s_waitcnt vmcnt(5)
	v_mfma_f32_16x16x32_bf16 v[64:67], v[60:63], v[24:27], v[52:55]
	s_waitcnt vmcnt(4)
	v_mfma_f32_16x16x32_bf16 v[56:59], v[68:71], v[32:35], v[56:59]
	global_load_dwordx4 v[68:71], v184, s[8:9]
	global_load_dwordx4 v[60:63], v184, s[8:9] offset:3072
	global_load_dwordx4 v[52:55], v184, s[52:53]
	global_load_dwordx2 v[72:73], v[134:135], off
	global_load_dwordx2 v[126:127], v[134:135], off offset:1536
	global_load_dwordx2 v[76:77], v[134:135], off offset:3072
	s_waitcnt vmcnt(9)
	v_mfma_f32_16x16x32_bf16 v[48:51], v[48:51], v[4:7], 0
	global_load_dwordx2 v[80:81], v[132:133], off offset:1536
	s_waitcnt vmcnt(3)
	v_lshlrev_b32_e32 v74, 16, v72
	s_waitcnt vmcnt(1)
	v_lshlrev_b32_e32 v130, 16, v76
	v_and_b32_e32 v131, 0xffff0000, v76
	v_lshlrev_b32_e32 v142, 16, v77
	v_and_b32_e32 v143, 0xffff0000, v77
	global_load_dwordx2 v[76:77], v[132:133], off
	v_and_b32_e32 v75, 0xffff0000, v72
	v_xor_b32_e32 v85, 0x80000000, v75
	v_xor_b32_e32 v84, 0x80000000, v74
	v_lshlrev_b32_e32 v72, 16, v73
	v_and_b32_e32 v73, 0xffff0000, v73
	v_mfma_f32_16x16x32_bf16 v[44:47], v[44:47], v[8:11], v[48:51]
	s_waitcnt vmcnt(1)
	v_lshlrev_b32_e32 v128, 16, v80
	v_and_b32_e32 v129, 0xffff0000, v80
	v_lshlrev_b32_e32 v136, 16, v81
	v_and_b32_e32 v137, 0xffff0000, v81
	global_load_dwordx2 v[80:81], v[132:133], off offset:3072
	v_mfma_f32_16x16x32_bf16 v[40:43], v[40:43], v[12:15], v[44:47]
	s_waitcnt vmcnt(1)
	v_lshlrev_b32_e32 v78, 16, v76
	v_and_b32_e32 v79, 0xffff0000, v76
	v_pk_fma_f32 v[78:79], v[0:1], v[78:79], v[84:85]
	v_lshlrev_b32_e32 v76, 16, v77
	v_and_b32_e32 v77, 0xffff0000, v77
	v_xor_b32_e32 v85, 0x80000000, v73
	v_xor_b32_e32 v84, 0x80000000, v72
	v_pk_fma_f32 v[146:147], v[68:69], v[78:79], v[74:75]
	v_xor_b32_e32 v69, 0x80000000, v131
	v_xor_b32_e32 v68, 0x80000000, v130
	v_pk_fma_f32 v[76:77], v[100:101], v[76:77], v[84:85]
	v_mfma_f32_16x16x32_bf16 v[36:39], v[36:39], v[16:19], v[40:43]
	v_fma_f32 v144, v70, v76, v72
	v_fma_f32 v145, v71, v77, v73
	v_lshl_add_u64 v[44:45], v[120:121], 0, v[112:113]
	s_waitcnt vmcnt(0)
	v_lshlrev_b32_e32 v82, 16, v80
	v_and_b32_e32 v83, 0xffff0000, v80
	v_lshlrev_b32_e32 v80, 16, v81
	v_and_b32_e32 v81, 0xffff0000, v81
	v_cvt_pk_bf16_f32 v36, v36, v37
	v_cvt_pk_bf16_f32 v37, v38, v39
	v_pk_fma_f32 v[148:149], v[0:1], v[82:83], v[68:69]
	v_xor_b32_e32 v69, 0x80000000, v143
	v_xor_b32_e32 v68, 0x80000000, v142
	v_pk_fma_f32 v[150:151], v[100:101], v[80:81], v[68:69]
	global_load_dwordx4 v[84:87], v184, s[42:43]
	global_load_dwordx4 v[80:83], v184, s[44:45]
	global_load_dwordx4 v[68:71], v184, s[46:47]
	global_load_dwordx4 v[76:79], v184, s[48:49]
	global_load_dwordx4 v[72:75], v184, s[50:51]
	v_pk_fma_f32 v[42:43], v[52:53], v[148:149], v[130:131]
	v_lshl_add_u64 v[130:131], v[120:121], 0, v[2:3]
	v_pk_fma_f32 v[40:41], v[54:55], v[150:151], v[142:143]
	v_cvt_pk_bf16_f32 v42, v42, v43
	v_cvt_pk_bf16_f32 v43, v40, v41
	v_cvt_pk_bf16_f32 v40, v146, v147
	v_cvt_pk_bf16_f32 v41, v144, v145
	v_sub_u32_e32 v233, v130, v231
	ds_write_b64 v233, v[42:43] offset:640
	v_sub_u32_e32 v233, v130, v231
	ds_write_b64 v233, v[40:41] offset:768
	s_waitcnt vmcnt(4)
	v_add_f32_e32 v64, v64, v84
	v_max_f32_e64 v84, -v64, 0
	v_mul_f32_e64 v64, |v64|, s57
	s_waitcnt vmcnt(3)
; __device__ __forceinline__ float sigmoidf_(float x) { return __builtin_amdgcn_rcpf(1.0f + __expf(-x)); }
; __device__ __forceinline__ void st_bf4(unsigned char* q, f32x4 v) { u32x2 w; w.x = cvt_pk_bf16(v[0], v[1]); w.y = cvt_pk_bf16(v[2], v[3]); *(u32x2*)q = w; }
; __device__ __forceinline__ void rwkv_prep_item(const Params& p, const Lt& lt, int l, int item) {
;     ...
; #pragma unroll
;             for (int j = 0; j < 4; ++j) {
;                 const float z = -(w0v[j] + aw[j]);
;                 const float sp = fmaxf(z, 0.f) + __logf(1.0f + __expf(-fabsf(z)));
;                 dec[j] = __expf(-__expf(-sp - 0.5f));
;                 a[j] = sigmoidf_(a0v[j] + aa[j]);
;                 kk[j] = k[j] * kkv[j];
;                 nrm += kk[j] * kk[j];
;                 k2[j] = k[j] * (1.0f + (a[j] - 1.0f) * kav[j]);
;                 bon += r[j] * k2[j] * rkv[j];
;             }
;             va[ct] = a; vkk[ct] = kk;
;             { const int cc = ct * 16 + quad * 4; *(f32x4*)(ob + cc * 4) = dec; st_bf4(ob + 512 + cc * 2, k2); st_bf4(ob + 640 + cc * 2, v); st_bf4(ob + 768 + cc * 2, r); }
;             st_bf4((unsigned char*)((bf16_t*)gate + (size_t)t * RW + c), ag);
	v_add_f32_e32 v56, v56, v80
	v_exp_f32_e32 v64, v64
	v_mul_f32_e32 v56, 0xbfb8aa3b, v56
	v_exp_f32_e32 v56, v56
	v_add_f32_e32 v64, 1.0, v64
	v_cmp_gt_f32_e64 s[0:1], s75, v64
	v_add_f32_e32 v56, 1.0, v56
	s_nop 0
	v_cndmask_b32_e64 v122, 0, 32, s[0:1]
	v_ldexp_f32 v64, v64, v122
	v_log_f32_e32 v64, v64
	s_nop 0
	v_mul_f32_e32 v122, 0x3f317217, v64
	v_cmp_lt_f32_e64 s[4:5], |v64|, s59
	v_fma_f32 v122, v64, s58, -v122
	v_fmac_f32_e32 v122, 0x3377d1cf, v64
	v_fmac_f32_e32 v122, 0x3f317217, v64
	v_cndmask_b32_e64 v64, v64, v122, s[4:5]
	v_cndmask_b32_e64 v122, 0, v243, s[0:1]
	v_sub_f32_e32 v64, v64, v122
	v_rcp_f32_e32 v122, v56
	v_add_f32_e32 v56, v65, v85
	v_max_f32_e64 v65, -v56, 0
	v_mul_f32_e64 v56, |v56|, s57
	v_add_f32_e32 v64, v84, v64
	v_exp_f32_e32 v56, v56
	v_sub_f32_e32 v64, -0.5, v64
	v_mul_f32_e32 v64, 0x3fb8aa3b, v64
	v_exp_f32_e32 v64, v64
	v_add_f32_e32 v56, 1.0, v56
	v_cmp_gt_f32_e64 s[0:1], s75, v56
	v_mul_f32_e32 v64, 0xbfb8aa3b, v64
	s_nop 0
	v_cndmask_b32_e64 v80, 0, 32, s[0:1]
	v_ldexp_f32 v56, v56, v80
	v_exp_f32_e32 v64, v64
	v_log_f32_e32 v56, v56
	s_nop 0
	v_mul_f32_e32 v80, 0x3f317217, v56
	v_cmp_lt_f32_e64 s[4:5], |v56|, s59
	v_fma_f32 v80, v56, s58, -v80
	v_fmac_f32_e32 v80, 0x3377d1cf, v56
	v_fmac_f32_e32 v80, 0x3f317217, v56
	v_cndmask_b32_e64 v56, v56, v80, s[4:5]
	v_cndmask_b32_e64 v80, 0, v243, s[0:1]
	v_sub_f32_e32 v56, v56, v80
	v_add_f32_e32 v56, v65, v56
	v_sub_f32_e32 v56, -0.5, v56
	v_mul_f32_e32 v56, 0x3fb8aa3b, v56
	v_exp_f32_e32 v56, v56
	s_nop 0
	v_mul_f32_e32 v56, 0xbfb8aa3b, v56
	v_exp_f32_e32 v65, v56
	v_add_f32_e32 v56, v57, v81
	v_mul_f32_e32 v56, 0xbfb8aa3b, v56
	v_exp_f32_e32 v56, v56
	s_nop 0
	v_add_f32_e32 v56, 1.0, v56
	v_rcp_f32_e32 v123, v56
	v_add_f32_e32 v56, v66, v86
	v_max_f32_e64 v57, -v56, 0
	v_mul_f32_e64 v56, |v56|, s57
	v_exp_f32_e32 v56, v56
	s_nop 0
	v_add_f32_e32 v56, 1.0, v56
	v_cmp_gt_f32_e64 s[0:1], s75, v56
	s_nop 1
	v_cndmask_b32_e64 v66, 0, 32, s[0:1]
	v_ldexp_f32 v56, v56, v66
	v_log_f32_e32 v56, v56
	s_nop 0
	v_mul_f32_e32 v66, 0x3f317217, v56
	v_cmp_lt_f32_e64 s[4:5], |v56|, s59
	v_fma_f32 v66, v56, s58, -v66
	v_fmac_f32_e32 v66, 0x3377d1cf, v56
	v_fmac_f32_e32 v66, 0x3f317217, v56
	v_cndmask_b32_e64 v56, v56, v66, s[4:5]
	v_cndmask_b32_e64 v66, 0, v243, s[0:1]
	v_sub_f32_e32 v56, v56, v66
	v_add_f32_e32 v56, v57, v56
	v_sub_f32_e32 v56, -0.5, v56
	v_mul_f32_e32 v56, 0x3fb8aa3b, v56
	v_exp_f32_e32 v56, v56
	s_nop 0
	v_mul_f32_e32 v56, 0xbfb8aa3b, v56
	v_exp_f32_e32 v66, v56
	v_add_f32_e32 v56, v58, v82
	v_mul_f32_e32 v56, 0xbfb8aa3b, v56
	v_exp_f32_e32 v56, v56
	s_nop 0
	v_add_f32_e32 v56, 1.0, v56
	v_rcp_f32_e32 v124, v56
	v_add_f32_e32 v56, v67, v87
	v_max_f32_e64 v57, -v56, 0
	v_mul_f32_e64 v56, |v56|, s57
	v_exp_f32_e32 v56, v56
	s_nop 0
	v_add_f32_e32 v56, 1.0, v56
	v_cmp_gt_f32_e64 s[0:1], s75, v56
	s_nop 1
	v_cndmask_b32_e64 v58, 0, 32, s[0:1]
	v_ldexp_f32 v56, v56, v58
	v_log_f32_e32 v56, v56
	s_nop 0
	v_mul_f32_e32 v58, 0x3f317217, v56
	v_cmp_lt_f32_e64 s[4:5], |v56|, s59
	v_fma_f32 v58, v56, s58, -v58
	v_fmac_f32_e32 v58, 0x3377d1cf, v56
	v_fmac_f32_e32 v58, 0x3f317217, v56
	v_cndmask_b32_e64 v56, v56, v58, s[4:5]
	v_cndmask_b32_e64 v58, 0, v243, s[0:1]
	s_or_b32 s0, s10, 16
	v_sub_f32_e32 v56, v56, v58
	v_lshlrev_b32_e32 v58, 16, v126
	v_add_f32_e32 v56, v57, v56
	v_xor_b32_e32 v82, 0x80000000, v58
	v_and_b32_e32 v57, 0xffff0000, v127
	v_sub_f32_e32 v56, -0.5, v56
	v_xor_b32_e32 v81, 0x80000000, v57
	v_mul_f32_e32 v56, 0x3fb8aa3b, v56
	v_exp_f32_e32 v56, v56
	s_nop 0
	v_mul_f32_e32 v56, 0xbfb8aa3b, v56
	v_exp_f32_e32 v67, v56
	v_add_f32_e32 v56, v59, v83
	v_and_b32_e32 v59, 0xffff0000, v126
	v_mul_f32_e32 v56, 0xbfb8aa3b, v56
	v_xor_b32_e32 v83, 0x80000000, v59
	v_exp_f32_e32 v56, v56
	v_pk_fma_f32 v[82:83], v[0:1], v[128:129], v[82:83]
	v_sub_u32_e32 v233, v44, v231
	ds_write_b128 v233, v[64:67]
	v_pk_fma_f32 v[58:59], v[60:61], v[82:83], v[58:59]
	v_pk_add_f32 v[60:61], v[122:123], -1.0 op_sel_hi:[1,0]
	v_add_f32_e32 v56, 1.0, v56
	s_waitcnt vmcnt(1)
	v_pk_fma_f32 v[60:61], v[76:77], v[60:61], 1.0 op_sel_hi:[1,1,0]
	v_rcp_f32_e32 v125, v56
	v_lshlrev_b32_e32 v56, 16, v127
	v_pk_mul_f32 v[126:127], v[68:69], v[58:59]
	v_pk_mul_f32 v[58:59], v[58:59], v[60:61]
	v_xor_b32_e32 v80, 0x80000000, v56
	v_mul_f32_e32 v60, v146, v58
	s_waitcnt vmcnt(0)
	v_fma_f32 v185, v72, v60, 0
	v_mul_f32_e32 v60, v147, v59
	v_pk_fma_f32 v[80:81], v[100:101], v[136:137], v[80:81]
	v_fmac_f32_e32 v185, v73, v60
	v_pk_add_f32 v[60:61], v[124:125], -1.0 op_sel_hi:[1,0]
	v_pk_fma_f32 v[56:57], v[62:63], v[80:81], v[56:57]
	v_pk_fma_f32 v[60:61], v[78:79], v[60:61], 1.0 op_sel_hi:[1,1,0]
	v_cvt_pk_bf16_f32 v44, v58, v59
	v_pk_mul_f32 v[60:61], v[56:57], v[60:61]
	v_pk_mul_f32 v[128:129], v[70:71], v[56:57]
	v_cvt_pk_bf16_f32 v45, v60, v61
	v_sub_u32_e32 v233, v130, v231
	ds_write_b64 v233, v[44:45] offset:512
	v_or_b32_e32 v44, s0, v180
	v_mul_f32_e32 v62, v144, v60
	global_store_dwordx2 v[140:141], v[36:37], off
	v_lshlrev_b32_e32 v36, 7, v44
	v_mov_b32_e32 v37, v3
	v_fmac_f32_e32 v185, v74, v62
	v_mul_f32_e32 v56, v145, v61
	v_lshl_add_u64 v[38:39], v[88:89], 0, v[36:37]
	v_fmac_f32_e32 v185, v75, v56
	v_lshl_add_u64 v[36:37], v[92:93], 0, v[36:37]
	global_load_dwordx4 v[40:43], v[38:39], off
	global_load_dwordx4 v[56:59], v[36:37], off
	global_load_dwordx4 v[60:63], v[38:39], off offset:64
	global_load_dwordx4 v[68:71], v[36:37], off offset:64
	v_lshlrev_b32_e32 v36, 8, v44
	v_mov_b32_e32 v37, v3
	v_lshl_add_u64 v[36:37], v[94:95], 0, v[36:37]
	global_load_dwordx4 v[52:55], v[36:37], off
	global_load_dwordx4 v[48:51], v[36:37], off offset:64
	global_load_dwordx4 v[44:47], v[36:37], off offset:128
	s_nop 0
	global_load_dwordx4 v[36:39], v[36:37], off offset:192
	v_pk_mul_f32 v[136:137], v[126:127], v[126:127]
	v_pk_mul_f32 v[138:139], v[128:129], v[128:129]
	s_waitcnt vmcnt(7)
; __device__ __forceinline__ float sigmoidf_(float x) { return __builtin_amdgcn_rcpf(1.0f + __expf(-x)); }
; __device__ __forceinline__ f32x4 ld_bf4(const bf16_t* q) { const u32x2 u = *(const u32x2*)q; return (f32x4){bflo(u.x), bfhi(u.x), bflo(u.y), bfhi(u.y)}; }
; __device__ __forceinline__ void rwkv_prep_item(const Params& p, const Lt& lt, int l, int item) {
;     ...
;         for (int ct = 0; ct < 4; ++ct) {
;             const int crow = h * 64 + ct * 16 + qi;
;             f32x4 aw = {0.f, 0.f, 0.f, 0.f}, aa = aw, ag = aw;
; #pragma unroll
;             for (int ks = 0; ks < 2; ++ks) {
;                 aw = __builtin_amdgcn_mfma_f32_16x16x32_bf16(*(const bf16x8*)(decT + crow * 64 + ks * 32 + quad * 8), fw[ks], aw, 0, 0, 0);
;                 aa = __builtin_amdgcn_mfma_f32_16x16x32_bf16(*(const bf16x8*)(aT + crow * 64 + ks * 32 + quad * 8), fa[ks], aa, 0, 0, 0);
;             }
; #pragma unroll
;             for (int ks = 0; ks < 4; ++ks) ag = __builtin_amdgcn_mfma_f32_16x16x32_bf16(*(const bf16x8*)(gT + crow * 128 + ks * 32 + quad * 8), fg[ks], ag, 0, 0, 0);
;             const int c = h * 64 + ct * 16 + quad * 4;
;             const f32x4 mr = *(const f32x4*)(mu + c), mk = *(const f32x4*)(mu + COL_K + c), mv = *(const f32x4*)(mu + COL_V + c);
;             const f32x4 cr = ld_bf4(pt + c), ck = ld_bf4(pt + COL_K + c), cv = ld_bf4(pt + COL_V + c);
;             const f32x4 qr = ld_bf4(pp + c) * pm, qk = ld_bf4(pp + COL_K + c) * pm, qv = ld_bf4(pp + COL_V + c) * pm;
;             const f32x4 r = cr + (qr - cr) * mr, k = ck + (qk - ck) * mk, v = cv + (qv - cv) * mv;
;             const f32x4 w0v = *(const f32x4*)(w0 + c), a0v = *(const f32x4*)(a0 + c), kkv = *(const f32x4*)(kkp + c), kav = *(const f32x4*)(kap + c), rkv = *(const f32x4*)(rkp + c);
;             f32x4 dec, a, kk, k2;
; #pragma unroll
;             for (int j = 0; j < 4; ++j) {
;                 const float z = -(w0v[j] + aw[j]);
;                 const float sp = fmaxf(z, 0.f) + __logf(1.0f + __expf(-fabsf(z)));
;                 dec[j] = __expf(-__expf(-sp - 0.5f));
;                 a[j] = sigmoidf_(a0v[j] + aa[j]);
	v_mfma_f32_16x16x32_bf16 v[40:43], v[40:43], v[20:23], 0
	s_waitcnt vmcnt(6)
	v_mfma_f32_16x16x32_bf16 v[56:59], v[56:59], v[28:31], 0
	s_waitcnt vmcnt(5)
	v_mfma_f32_16x16x32_bf16 v[64:67], v[60:63], v[24:27], v[40:43]
	s_nop 3
	v_or_b32_e32 v40, s0, v181
	v_lshlrev_b32_e32 v40, 2, v40
	s_waitcnt vmcnt(4)
	v_mfma_f32_16x16x32_bf16 v[60:63], v[68:71], v[32:35], v[56:59]
	global_load_dwordx4 v[68:71], v184, s[8:9] offset:64
	s_nop 1
	global_load_dwordx4 v[56:59], v184, s[8:9] offset:3136
	s_nop 0
	global_load_dwordx4 v[40:43], v40, s[52:53]
	s_nop 0
	global_load_dwordx2 v[72:73], v[134:135], off offset:32
	global_load_dwordx2 v[146:147], v[134:135], off offset:1568
	global_load_dwordx2 v[76:77], v[134:135], off offset:3104
	s_waitcnt vmcnt(9)
	v_mfma_f32_16x16x32_bf16 v[52:55], v[52:55], v[4:7], 0
	global_load_dwordx2 v[80:81], v[132:133], off offset:1568
	s_waitcnt vmcnt(3)
	v_lshlrev_b32_e32 v74, 16, v72
	s_waitcnt vmcnt(1)
	v_lshlrev_b32_e32 v154, 16, v76
	v_and_b32_e32 v155, 0xffff0000, v76
	v_lshlrev_b32_e32 v156, 16, v77
	v_and_b32_e32 v157, 0xffff0000, v77
	global_load_dwordx2 v[76:77], v[132:133], off offset:32
	v_and_b32_e32 v75, 0xffff0000, v72
	v_xor_b32_e32 v85, 0x80000000, v75
	v_xor_b32_e32 v84, 0x80000000, v74
	v_lshlrev_b32_e32 v72, 16, v73
	v_and_b32_e32 v73, 0xffff0000, v73
	v_mfma_f32_16x16x32_bf16 v[48:51], v[48:51], v[8:11], v[52:55]
	s_waitcnt vmcnt(1)
	v_lshlrev_b32_e32 v148, 16, v80
	v_and_b32_e32 v149, 0xffff0000, v80
	v_lshlrev_b32_e32 v150, 16, v81
	v_and_b32_e32 v151, 0xffff0000, v81
	global_load_dwordx2 v[80:81], v[132:133], off offset:3104
	v_mfma_f32_16x16x32_bf16 v[44:47], v[44:47], v[12:15], v[48:51]
	s_waitcnt vmcnt(1)
	v_lshlrev_b32_e32 v78, 16, v76
	v_and_b32_e32 v79, 0xffff0000, v76
	v_pk_fma_f32 v[78:79], v[0:1], v[78:79], v[84:85]
	v_lshlrev_b32_e32 v76, 16, v77
	v_and_b32_e32 v77, 0xffff0000, v77
	v_xor_b32_e32 v85, 0x80000000, v73
	v_xor_b32_e32 v84, 0x80000000, v72
	v_pk_fma_f32 v[160:161], v[68:69], v[78:79], v[74:75]
	v_xor_b32_e32 v69, 0x80000000, v155
	v_xor_b32_e32 v68, 0x80000000, v154
	v_pk_fma_f32 v[76:77], v[100:101], v[76:77], v[84:85]
	v_mfma_f32_16x16x32_bf16 v[36:39], v[36:39], v[16:19], v[44:47]
	v_fma_f32 v158, v70, v76, v72
	v_fma_f32 v159, v71, v77, v73
	s_waitcnt vmcnt(0)
	v_lshlrev_b32_e32 v82, 16, v80
	v_and_b32_e32 v83, 0xffff0000, v80
	v_lshlrev_b32_e32 v80, 16, v81
	v_and_b32_e32 v81, 0xffff0000, v81
	v_lshl_add_u64 v[44:45], v[120:121], 0, v[106:107]
	v_cvt_pk_bf16_f32 v36, v36, v37
	v_cvt_pk_bf16_f32 v37, v38, v39
	v_pk_fma_f32 v[162:163], v[0:1], v[82:83], v[68:69]
	v_xor_b32_e32 v69, 0x80000000, v157
	v_xor_b32_e32 v68, 0x80000000, v156
	v_pk_fma_f32 v[164:165], v[100:101], v[80:81], v[68:69]
	global_load_dwordx4 v[84:87], v184, s[42:43] offset:64
	global_load_dwordx4 v[80:83], v184, s[44:45] offset:64
	global_load_dwordx4 v[72:75], v184, s[46:47] offset:64
	global_load_dwordx4 v[76:79], v184, s[48:49] offset:64
	global_load_dwordx4 v[68:71], v184, s[50:51] offset:64
	v_pk_fma_f32 v[40:41], v[40:41], v[162:163], v[154:155]
	v_pk_fma_f32 v[42:43], v[42:43], v[164:165], v[156:157]
	v_cvt_pk_bf16_f32 v40, v40, v41
	v_cvt_pk_bf16_f32 v41, v42, v43
	s_waitcnt vmcnt(4)
	v_add_f32_e32 v64, v64, v84
	v_max_f32_e64 v84, -v64, 0
	v_mul_f32_e64 v64, |v64|, s57
	s_waitcnt vmcnt(3)
	v_add_f32_e32 v60, v60, v80
	v_exp_f32_e32 v64, v64
	v_mul_f32_e32 v60, 0xbfb8aa3b, v60
	v_exp_f32_e32 v60, v60
	v_add_f32_e32 v64, 1.0, v64
	v_cmp_gt_f32_e64 s[0:1], s75, v64
	v_add_f32_e32 v60, 1.0, v60
	s_nop 0
	v_cndmask_b32_e64 v142, 0, 32, s[0:1]
	v_ldexp_f32 v64, v64, v142
	v_log_f32_e32 v64, v64
	s_nop 0
	v_mul_f32_e32 v142, 0x3f317217, v64
	v_cmp_lt_f32_e64 s[4:5], |v64|, s59
	v_fma_f32 v142, v64, s58, -v142
	v_fmac_f32_e32 v142, 0x3377d1cf, v64
	v_fmac_f32_e32 v142, 0x3f317217, v64
	v_cndmask_b32_e64 v64, v64, v142, s[4:5]
	v_cndmask_b32_e64 v142, 0, v243, s[0:1]
	v_sub_f32_e32 v64, v64, v142
	v_rcp_f32_e32 v142, v60
	v_add_f32_e32 v60, v65, v85
	v_max_f32_e64 v65, -v60, 0
	v_mul_f32_e64 v60, |v60|, s57
	v_add_f32_e32 v64, v84, v64
	v_exp_f32_e32 v60, v60
	v_sub_f32_e32 v64, -0.5, v64
	v_mul_f32_e32 v64, 0x3fb8aa3b, v64
	v_exp_f32_e32 v64, v64
	v_add_f32_e32 v60, 1.0, v60
	v_cmp_gt_f32_e64 s[0:1], s75, v60
	v_mul_f32_e32 v64, 0xbfb8aa3b, v64
	s_nop 0
	v_cndmask_b32_e64 v80, 0, 32, s[0:1]
	v_ldexp_f32 v60, v60, v80
	v_exp_f32_e32 v64, v64
	v_log_f32_e32 v60, v60
	s_nop 0
	v_mul_f32_e32 v80, 0x3f317217, v60
	v_cmp_lt_f32_e64 s[4:5], |v60|, s59
	v_fma_f32 v80, v60, s58, -v80
	v_fmac_f32_e32 v80, 0x3377d1cf, v60
	v_fmac_f32_e32 v80, 0x3f317217, v60
	v_cndmask_b32_e64 v60, v60, v80, s[4:5]
	v_cndmask_b32_e64 v80, 0, v243, s[0:1]
	v_sub_f32_e32 v60, v60, v80
	v_add_f32_e32 v60, v65, v60
	v_sub_f32_e32 v60, -0.5, v60
	v_mul_f32_e32 v60, 0x3fb8aa3b, v60
	v_exp_f32_e32 v60, v60
	s_nop 0
	v_mul_f32_e32 v60, 0xbfb8aa3b, v60
	v_exp_f32_e32 v65, v60
	v_add_f32_e32 v60, v61, v81
	v_mul_f32_e32 v60, 0xbfb8aa3b, v60
	v_exp_f32_e32 v60, v60
	s_nop 0
	v_add_f32_e32 v60, 1.0, v60
	v_rcp_f32_e32 v143, v60
	v_add_f32_e32 v60, v66, v86
	v_max_f32_e64 v61, -v60, 0
	v_mul_f32_e64 v60, |v60|, s57
	v_exp_f32_e32 v60, v60
	s_nop 0
	v_add_f32_e32 v60, 1.0, v60
	v_cmp_gt_f32_e64 s[0:1], s75, v60
	s_nop 1
	v_cndmask_b32_e64 v66, 0, 32, s[0:1]
	v_ldexp_f32 v60, v60, v66
	v_log_f32_e32 v60, v60
	s_nop 0
	v_mul_f32_e32 v66, 0x3f317217, v60
	v_cmp_lt_f32_e64 s[4:5], |v60|, s59
	v_fma_f32 v66, v60, s58, -v66
	v_fmac_f32_e32 v66, 0x3377d1cf, v60
	v_fmac_f32_e32 v66, 0x3f317217, v60
	v_cndmask_b32_e64 v60, v60, v66, s[4:5]
	v_cndmask_b32_e64 v66, 0, v243, s[0:1]
	v_sub_f32_e32 v60, v60, v66
	v_add_f32_e32 v60, v61, v60
; __device__ __forceinline__ void rwkv_prep_item(const Params& p, const Lt& lt, int l, int item) {
;     ...
;         for (int ct = 0; ct < 4; ++ct) {
;             const int crow = h * 64 + ct * 16 + qi;
;             f32x4 aw = {0.f, 0.f, 0.f, 0.f}, aa = aw, ag = aw;
; #pragma unroll
;             for (int ks = 0; ks < 2; ++ks) {
;                 aw = __builtin_amdgcn_mfma_f32_16x16x32_bf16(*(const bf16x8*)(decT + crow * 64 + ks * 32 + quad * 8), fw[ks], aw, 0, 0, 0);
;                 aa = __builtin_amdgcn_mfma_f32_16x16x32_bf16(*(const bf16x8*)(aT + crow * 64 + ks * 32 + quad * 8), fa[ks], aa, 0, 0, 0);
;             }
; #pragma unroll
;             for (int ks = 0; ks < 4; ++ks) ag = __builtin_amdgcn_mfma_f32_16x16x32_bf16(*(const bf16x8*)(gT + crow * 128 + ks * 32 + quad * 8), fg[ks], ag, 0, 0, 0);
;             const int c = h * 64 + ct * 16 + quad * 4;
;             const f32x4 mr = *(const f32x4*)(mu + c), mk = *(const f32x4*)(mu + COL_K + c), mv = *(const f32x4*)(mu + COL_V + c);
;             const f32x4 cr = ld_bf4(pt + c), ck = ld_bf4(pt + COL_K + c), cv = ld_bf4(pt + COL_V + c);
;             const f32x4 qr = ld_bf4(pp + c) * pm, qk = ld_bf4(pp + COL_K + c) * pm, qv = ld_bf4(pp + COL_V + c) * pm;
;             const f32x4 r = cr + (qr - cr) * mr, k = ck + (qk - ck) * mk, v = cv + (qv - cv) * mv;
;             const f32x4 w0v = *(const f32x4*)(w0 + c), a0v = *(const f32x4*)(a0 + c), kkv = *(const f32x4*)(kkp + c), kav = *(const f32x4*)(kap + c), rkv = *(const f32x4*)(rkp + c);
;             f32x4 dec, a, kk, k2;
; #pragma unroll
;             for (int j = 0; j < 4; ++j) {
;                 const float z = -(w0v[j] + aw[j]);
;                 const float sp = fmaxf(z, 0.f) + __logf(1.0f + __expf(-fabsf(z)));
;                 dec[j] = __expf(-__expf(-sp - 0.5f));
;                 a[j] = sigmoidf_(a0v[j] + aa[j]);
;                 kk[j] = k[j] * kkv[j];
;                 nrm += kk[j] * kk[j];
;                 k2[j] = k[j] * (1.0f + (a[j] - 1.0f) * kav[j]);
;                 bon += r[j] * k2[j] * rkv[j];
;             }
;             va[ct] = a; vkk[ct] = kk;
;             { const int cc = ct * 16 + quad * 4; *(f32x4*)(ob + cc * 4) = dec; st_bf4(ob + 512 + cc * 2, k2); st_bf4(ob + 640 + cc * 2, v); st_bf4(ob + 768 + cc * 2, r); }
;             st_bf4((unsigned char*)((bf16_t*)gate + (size_t)t * RW + c), ag);
	v_sub_f32_e32 v60, -0.5, v60
	v_mul_f32_e32 v60, 0x3fb8aa3b, v60
	v_exp_f32_e32 v60, v60
	s_nop 0
	v_mul_f32_e32 v60, 0xbfb8aa3b, v60
	v_exp_f32_e32 v66, v60
	v_add_f32_e32 v60, v62, v82
	v_mul_f32_e32 v60, 0xbfb8aa3b, v60
	v_exp_f32_e32 v60, v60
	s_nop 0
	v_add_f32_e32 v60, 1.0, v60
	v_rcp_f32_e32 v144, v60
	v_add_f32_e32 v60, v67, v87
	v_max_f32_e64 v61, -v60, 0
	v_mul_f32_e64 v60, |v60|, s57
	v_exp_f32_e32 v60, v60
	s_nop 0
	v_add_f32_e32 v60, 1.0, v60
	v_cmp_gt_f32_e64 s[0:1], s75, v60
	s_nop 1
	v_cndmask_b32_e64 v62, 0, 32, s[0:1]
	v_ldexp_f32 v60, v60, v62
	v_log_f32_e32 v60, v60
	s_nop 0
	v_mul_f32_e32 v62, 0x3f317217, v60
	v_cmp_lt_f32_e64 s[4:5], |v60|, s59
	v_fma_f32 v62, v60, s58, -v62
	v_fmac_f32_e32 v62, 0x3377d1cf, v60
	v_fmac_f32_e32 v62, 0x3f317217, v60
	v_cndmask_b32_e64 v60, v60, v62, s[4:5]
	v_cndmask_b32_e64 v62, 0, v243, s[0:1]
	v_sub_f32_e32 v60, v60, v62
	v_add_f32_e32 v60, v61, v60
	v_sub_f32_e32 v60, -0.5, v60
	v_mul_f32_e32 v60, 0x3fb8aa3b, v60
	v_exp_f32_e32 v60, v60
	v_and_b32_e32 v61, 0xffff0000, v147
	v_lshlrev_b32_e32 v62, 16, v146
	v_xor_b32_e32 v81, 0x80000000, v61
	v_mul_f32_e32 v60, 0xbfb8aa3b, v60
	v_exp_f32_e32 v67, v60
	v_add_f32_e32 v60, v63, v83
	v_mul_f32_e32 v60, 0xbfb8aa3b, v60
	v_exp_f32_e32 v60, v60
	v_and_b32_e32 v63, 0xffff0000, v146
	v_xor_b32_e32 v83, 0x80000000, v63
	v_xor_b32_e32 v82, 0x80000000, v62
	v_add_f32_e32 v60, 1.0, v60
	v_rcp_f32_e32 v145, v60
	v_lshlrev_b32_e32 v60, 16, v147
	v_xor_b32_e32 v80, 0x80000000, v60
	v_pk_fma_f32 v[80:81], v[100:101], v[150:151], v[80:81]
	v_pk_fma_f32 v[82:83], v[0:1], v[148:149], v[82:83]
	v_pk_fma_f32 v[58:59], v[58:59], v[80:81], v[60:61]
	v_pk_fma_f32 v[56:57], v[56:57], v[82:83], v[62:63]
	v_pk_add_f32 v[62:63], v[142:143], -1.0 op_sel_hi:[1,0]
	v_pk_add_f32 v[60:61], v[144:145], -1.0 op_sel_hi:[1,0]
	s_waitcnt vmcnt(1)
	v_pk_fma_f32 v[62:63], v[76:77], v[62:63], 1.0 op_sel_hi:[1,1,0]
	v_pk_fma_f32 v[60:61], v[78:79], v[60:61], 1.0 op_sel_hi:[1,1,0]
	v_pk_mul_f32 v[146:147], v[72:73], v[56:57]
	v_pk_mul_f32 v[56:57], v[56:57], v[62:63]
	v_pk_mul_f32 v[60:61], v[58:59], v[60:61]
	v_sub_u32_e32 v233, v44, v231
	ds_write_b128 v233, v[64:67]
	v_lshl_add_u64 v[44:45], v[120:121], 0, v[108:109]
	v_mul_f32_e32 v62, v160, v56
	v_cvt_pk_bf16_f32 v46, v56, v57
	v_cvt_pk_bf16_f32 v47, v60, v61
	v_sub_u32_e32 v233, v44, v231
	ds_write_b64 v233, v[40:41] offset:640
	v_cvt_pk_bf16_f32 v40, v160, v161
	v_cvt_pk_bf16_f32 v41, v158, v159
	s_or_b32 s0, s10, 32
	s_waitcnt vmcnt(0)
	v_fmac_f32_e32 v185, v68, v62
	v_mul_f32_e32 v62, v161, v57
	v_sub_u32_e32 v233, v44, v231
	ds_write_b64 v233, v[46:47] offset:512
	v_sub_u32_e32 v233, v44, v231
	ds_write_b64 v233, v[40:41] offset:768
	v_or_b32_e32 v44, s0, v180
	v_fmac_f32_e32 v185, v69, v62
	v_mul_f32_e32 v62, v158, v60
	global_store_dwordx2 v[140:141], v[36:37], off offset:32
	v_lshlrev_b32_e32 v36, 7, v44
	v_mov_b32_e32 v37, v3
	v_fmac_f32_e32 v185, v70, v62
	v_pk_mul_f32 v[148:149], v[74:75], v[58:59]
	v_mul_f32_e32 v58, v159, v61
	v_lshl_add_u64 v[38:39], v[88:89], 0, v[36:37]
	v_fmac_f32_e32 v185, v71, v58
	v_lshl_add_u64 v[36:37], v[92:93], 0, v[36:37]
	global_load_dwordx4 v[40:43], v[38:39], off
	global_load_dwordx4 v[56:59], v[36:37], off
	global_load_dwordx4 v[60:63], v[38:39], off offset:64
	global_load_dwordx4 v[68:71], v[36:37], off offset:64
	v_lshlrev_b32_e32 v36, 8, v44
	v_mov_b32_e32 v37, v3
	v_lshl_add_u64 v[36:37], v[94:95], 0, v[36:37]
	global_load_dwordx4 v[52:55], v[36:37], off
	global_load_dwordx4 v[48:51], v[36:37], off offset:64
	global_load_dwordx4 v[44:47], v[36:37], off offset:128
	s_nop 0
	global_load_dwordx4 v[36:39], v[36:37], off offset:192
	v_pk_mul_f32 v[150:151], v[146:147], v[146:147]
	v_pk_mul_f32 v[152:153], v[148:149], v[148:149]
	s_waitcnt vmcnt(7)
	v_mfma_f32_16x16x32_bf16 v[40:43], v[40:43], v[20:23], 0
	s_waitcnt vmcnt(6)
	v_mfma_f32_16x16x32_bf16 v[56:59], v[56:59], v[28:31], 0
	s_waitcnt vmcnt(5)
	v_mfma_f32_16x16x32_bf16 v[64:67], v[60:63], v[24:27], v[40:43]
	s_nop 3
	v_or_b32_e32 v40, s0, v181
	v_lshlrev_b32_e32 v40, 2, v40
	s_waitcnt vmcnt(4)
	v_mfma_f32_16x16x32_bf16 v[60:63], v[68:71], v[32:35], v[56:59]
	global_load_dwordx4 v[68:71], v184, s[8:9] offset:128
	s_nop 1
	global_load_dwordx4 v[56:59], v184, s[8:9] offset:3200
	s_nop 0
	global_load_dwordx4 v[40:43], v40, s[52:53]
	s_nop 0
	global_load_dwordx2 v[72:73], v[134:135], off offset:64
	global_load_dwordx2 v[158:159], v[134:135], off offset:1600
	global_load_dwordx2 v[76:77], v[134:135], off offset:3136
	s_waitcnt vmcnt(9)
	v_mfma_f32_16x16x32_bf16 v[52:55], v[52:55], v[4:7], 0
	global_load_dwordx2 v[80:81], v[132:133], off offset:1600
	s_waitcnt vmcnt(3)
	v_lshlrev_b32_e32 v74, 16, v72
	s_waitcnt vmcnt(1)
	v_lshlrev_b32_e32 v166, 16, v76
	v_and_b32_e32 v167, 0xffff0000, v76
	v_lshlrev_b32_e32 v168, 16, v77
	v_and_b32_e32 v169, 0xffff0000, v77
	global_load_dwordx2 v[76:77], v[132:133], off offset:64
	v_and_b32_e32 v75, 0xffff0000, v72
	v_xor_b32_e32 v85, 0x80000000, v75
	v_xor_b32_e32 v84, 0x80000000, v74
	v_lshlrev_b32_e32 v72, 16, v73
	v_and_b32_e32 v73, 0xffff0000, v73
	v_mfma_f32_16x16x32_bf16 v[48:51], v[48:51], v[8:11], v[52:55]
	s_waitcnt vmcnt(1)
	v_lshlrev_b32_e32 v160, 16, v80
	v_and_b32_e32 v161, 0xffff0000, v80
	v_lshlrev_b32_e32 v162, 16, v81
	v_and_b32_e32 v163, 0xffff0000, v81
	global_load_dwordx2 v[80:81], v[132:133], off offset:3136
	v_mfma_f32_16x16x32_bf16 v[44:47], v[44:47], v[12:15], v[48:51]
	s_waitcnt vmcnt(1)
; __device__ __forceinline__ float sigmoidf_(float x) { return __builtin_amdgcn_rcpf(1.0f + __expf(-x)); }
; __device__ __forceinline__ f32x4 ld_bf4(const bf16_t* q) { const u32x2 u = *(const u32x2*)q; return (f32x4){bflo(u.x), bfhi(u.x), bflo(u.y), bfhi(u.y)}; }
; __device__ __forceinline__ void rwkv_prep_item(const Params& p, const Lt& lt, int l, int item) {
;     ...
;         for (int ct = 0; ct < 4; ++ct) {
;             const int crow = h * 64 + ct * 16 + qi;
;             f32x4 aw = {0.f, 0.f, 0.f, 0.f}, aa = aw, ag = aw;
; #pragma unroll
;             for (int ks = 0; ks < 2; ++ks) {
;                 aw = __builtin_amdgcn_mfma_f32_16x16x32_bf16(*(const bf16x8*)(decT + crow * 64 + ks * 32 + quad * 8), fw[ks], aw, 0, 0, 0);
;                 aa = __builtin_amdgcn_mfma_f32_16x16x32_bf16(*(const bf16x8*)(aT + crow * 64 + ks * 32 + quad * 8), fa[ks], aa, 0, 0, 0);
;             }
; #pragma unroll
;             for (int ks = 0; ks < 4; ++ks) ag = __builtin_amdgcn_mfma_f32_16x16x32_bf16(*(const bf16x8*)(gT + crow * 128 + ks * 32 + quad * 8), fg[ks], ag, 0, 0, 0);
;             const int c = h * 64 + ct * 16 + quad * 4;
;             const f32x4 mr = *(const f32x4*)(mu + c), mk = *(const f32x4*)(mu + COL_K + c), mv = *(const f32x4*)(mu + COL_V + c);
;             const f32x4 cr = ld_bf4(pt + c), ck = ld_bf4(pt + COL_K + c), cv = ld_bf4(pt + COL_V + c);
;             const f32x4 qr = ld_bf4(pp + c) * pm, qk = ld_bf4(pp + COL_K + c) * pm, qv = ld_bf4(pp + COL_V + c) * pm;
;             const f32x4 r = cr + (qr - cr) * mr, k = ck + (qk - ck) * mk, v = cv + (qv - cv) * mv;
;             const f32x4 w0v = *(const f32x4*)(w0 + c), a0v = *(const f32x4*)(a0 + c), kkv = *(const f32x4*)(kkp + c), kav = *(const f32x4*)(kap + c), rkv = *(const f32x4*)(rkp + c);
;             f32x4 dec, a, kk, k2;
; #pragma unroll
;             for (int j = 0; j < 4; ++j) {
;                 const float z = -(w0v[j] + aw[j]);
;                 const float sp = fmaxf(z, 0.f) + __logf(1.0f + __expf(-fabsf(z)));
;                 dec[j] = __expf(-__expf(-sp - 0.5f));
;                 a[j] = sigmoidf_(a0v[j] + aa[j]);
;                 kk[j] = k[j] * kkv[j];
;                 nrm += kk[j] * kk[j];
;                 k2[j] = k[j] * (1.0f + (a[j] - 1.0f) * kav[j]);
;                 bon += r[j] * k2[j] * rkv[j];
;             }
	v_lshlrev_b32_e32 v78, 16, v76
	v_and_b32_e32 v79, 0xffff0000, v76
	v_pk_fma_f32 v[78:79], v[0:1], v[78:79], v[84:85]
	v_lshlrev_b32_e32 v76, 16, v77
	v_and_b32_e32 v77, 0xffff0000, v77
	v_xor_b32_e32 v85, 0x80000000, v73
	v_xor_b32_e32 v84, 0x80000000, v72
	v_pk_fma_f32 v[172:173], v[68:69], v[78:79], v[74:75]
	v_xor_b32_e32 v69, 0x80000000, v167
	v_xor_b32_e32 v68, 0x80000000, v166
	v_pk_fma_f32 v[76:77], v[100:101], v[76:77], v[84:85]
	v_mfma_f32_16x16x32_bf16 v[36:39], v[36:39], v[16:19], v[44:47]
	v_fma_f32 v170, v70, v76, v72
	v_fma_f32 v171, v71, v77, v73
	s_waitcnt vmcnt(0)
	v_lshlrev_b32_e32 v82, 16, v80
	v_and_b32_e32 v83, 0xffff0000, v80
	v_lshlrev_b32_e32 v80, 16, v81
	v_and_b32_e32 v81, 0xffff0000, v81
	v_lshl_add_u64 v[44:45], v[120:121], 0, v[102:103]
	v_cvt_pk_bf16_f32 v36, v36, v37
	v_cvt_pk_bf16_f32 v37, v38, v39
	v_pk_fma_f32 v[174:175], v[0:1], v[82:83], v[68:69]
	v_xor_b32_e32 v69, 0x80000000, v169
	v_xor_b32_e32 v68, 0x80000000, v168
	v_pk_fma_f32 v[176:177], v[100:101], v[80:81], v[68:69]
	global_load_dwordx4 v[84:87], v184, s[42:43] offset:128
	global_load_dwordx4 v[80:83], v184, s[44:45] offset:128
	global_load_dwordx4 v[72:75], v184, s[46:47] offset:128
	global_load_dwordx4 v[76:79], v184, s[48:49] offset:128
	global_load_dwordx4 v[68:71], v184, s[50:51] offset:128
	v_pk_fma_f32 v[40:41], v[40:41], v[174:175], v[166:167]
	v_pk_fma_f32 v[42:43], v[42:43], v[176:177], v[168:169]
	v_cvt_pk_bf16_f32 v40, v40, v41
	v_cvt_pk_bf16_f32 v41, v42, v43
	s_waitcnt vmcnt(4)
	v_add_f32_e32 v64, v64, v84
	v_max_f32_e64 v84, -v64, 0
	v_mul_f32_e64 v64, |v64|, s57
	s_waitcnt vmcnt(3)
	v_add_f32_e32 v60, v60, v80
	v_exp_f32_e32 v64, v64
	v_mul_f32_e32 v60, 0xbfb8aa3b, v60
	v_exp_f32_e32 v60, v60
	v_add_f32_e32 v64, 1.0, v64
	v_cmp_gt_f32_e64 s[0:1], s75, v64
	v_add_f32_e32 v60, 1.0, v60
	s_nop 0
	v_cndmask_b32_e64 v154, 0, 32, s[0:1]
	v_ldexp_f32 v64, v64, v154
	v_log_f32_e32 v64, v64
	s_nop 0
	v_mul_f32_e32 v154, 0x3f317217, v64
	v_cmp_lt_f32_e64 s[4:5], |v64|, s59
	v_fma_f32 v154, v64, s58, -v154
	v_fmac_f32_e32 v154, 0x3377d1cf, v64
	v_fmac_f32_e32 v154, 0x3f317217, v64
	v_cndmask_b32_e64 v64, v64, v154, s[4:5]
	v_cndmask_b32_e64 v154, 0, v243, s[0:1]
	v_sub_f32_e32 v64, v64, v154
	v_rcp_f32_e32 v154, v60
	v_add_f32_e32 v60, v65, v85
	v_max_f32_e64 v65, -v60, 0
	v_mul_f32_e64 v60, |v60|, s57
	v_add_f32_e32 v64, v84, v64
	v_exp_f32_e32 v60, v60
	v_sub_f32_e32 v64, -0.5, v64
	v_mul_f32_e32 v64, 0x3fb8aa3b, v64
	v_exp_f32_e32 v64, v64
	v_add_f32_e32 v60, 1.0, v60
	v_cmp_gt_f32_e64 s[0:1], s75, v60
	v_mul_f32_e32 v64, 0xbfb8aa3b, v64
	s_nop 0
	v_cndmask_b32_e64 v80, 0, 32, s[0:1]
	v_ldexp_f32 v60, v60, v80
	v_exp_f32_e32 v64, v64
	v_log_f32_e32 v60, v60
	s_nop 0
	v_mul_f32_e32 v80, 0x3f317217, v60
	v_fma_f32 v80, v60, s58, -v80
	v_fmac_f32_e32 v80, 0x3377d1cf, v60
	v_fmac_f32_e32 v80, 0x3f317217, v60
	v_cmp_lt_f32_e64 s[4:5], |v60|, s59
	s_nop 1
	v_cndmask_b32_e64 v60, v60, v80, s[4:5]
	v_cndmask_b32_e64 v80, 0, v243, s[0:1]
	v_sub_f32_e32 v60, v60, v80
	v_add_f32_e32 v60, v65, v60
	v_sub_f32_e32 v60, -0.5, v60
	v_mul_f32_e32 v60, 0x3fb8aa3b, v60
	v_exp_f32_e32 v60, v60
	s_nop 0
	v_mul_f32_e32 v60, 0xbfb8aa3b, v60
	v_exp_f32_e32 v65, v60
	v_add_f32_e32 v60, v61, v81
	v_mul_f32_e32 v60, 0xbfb8aa3b, v60
	v_exp_f32_e32 v60, v60
	s_nop 0
	v_add_f32_e32 v60, 1.0, v60
	v_rcp_f32_e32 v155, v60
	v_add_f32_e32 v60, v66, v86
	v_max_f32_e64 v61, -v60, 0
	v_mul_f32_e64 v60, |v60|, s57
	v_exp_f32_e32 v60, v60
	s_nop 0
	v_add_f32_e32 v60, 1.0, v60
	v_cmp_gt_f32_e64 s[0:1], s75, v60
	s_nop 1
	v_cndmask_b32_e64 v66, 0, 32, s[0:1]
	v_ldexp_f32 v60, v60, v66
	v_log_f32_e32 v60, v60
	s_nop 0
	v_mul_f32_e32 v66, 0x3f317217, v60
	v_fma_f32 v66, v60, s58, -v66
	v_fmac_f32_e32 v66, 0x3377d1cf, v60
	v_fmac_f32_e32 v66, 0x3f317217, v60
	v_cmp_lt_f32_e64 s[4:5], |v60|, s59
	s_nop 1
	v_cndmask_b32_e64 v60, v60, v66, s[4:5]
	v_cndmask_b32_e64 v66, 0, v243, s[0:1]
	v_sub_f32_e32 v60, v60, v66
	v_add_f32_e32 v60, v61, v60
	v_sub_f32_e32 v60, -0.5, v60
	v_mul_f32_e32 v60, 0x3fb8aa3b, v60
	v_exp_f32_e32 v60, v60
	s_nop 0
	v_mul_f32_e32 v60, 0xbfb8aa3b, v60
	v_exp_f32_e32 v66, v60
	v_add_f32_e32 v60, v62, v82
	v_mul_f32_e32 v60, 0xbfb8aa3b, v60
	v_exp_f32_e32 v60, v60
	s_nop 0
	v_add_f32_e32 v60, 1.0, v60
	v_rcp_f32_e32 v156, v60
	v_add_f32_e32 v60, v67, v87
	v_max_f32_e64 v61, -v60, 0
	v_mul_f32_e64 v60, |v60|, s57
	v_exp_f32_e32 v60, v60
	s_nop 0
	v_add_f32_e32 v60, 1.0, v60
	v_cmp_gt_f32_e64 s[0:1], s75, v60
	s_nop 1
	v_cndmask_b32_e64 v62, 0, 32, s[0:1]
	v_ldexp_f32 v60, v60, v62
	v_log_f32_e32 v60, v60
	s_nop 0
	v_mul_f32_e32 v62, 0x3f317217, v60
	v_fma_f32 v62, v60, s58, -v62
	v_fmac_f32_e32 v62, 0x3377d1cf, v60
	v_fmac_f32_e32 v62, 0x3f317217, v60
	v_cmp_lt_f32_e64 s[4:5], |v60|, s59
	s_nop 1
	v_cndmask_b32_e64 v60, v60, v62, s[4:5]
	v_cndmask_b32_e64 v62, 0, v243, s[0:1]
	v_sub_f32_e32 v60, v60, v62
	v_add_f32_e32 v60, v61, v60
	v_sub_f32_e32 v60, -0.5, v60
	v_mul_f32_e32 v60, 0x3fb8aa3b, v60
	v_exp_f32_e32 v60, v60
	v_and_b32_e32 v61, 0xffff0000, v159
	v_lshlrev_b32_e32 v62, 16, v158
	v_xor_b32_e32 v81, 0x80000000, v61
	v_mul_f32_e32 v60, 0xbfb8aa3b, v60
	v_exp_f32_e32 v67, v60
	v_add_f32_e32 v60, v63, v83
	v_mul_f32_e32 v60, 0xbfb8aa3b, v60
	v_exp_f32_e32 v60, v60
	v_and_b32_e32 v63, 0xffff0000, v158
	v_xor_b32_e32 v83, 0x80000000, v63
	v_xor_b32_e32 v82, 0x80000000, v62
	v_add_f32_e32 v60, 1.0, v60
	v_rcp_f32_e32 v157, v60
	v_lshlrev_b32_e32 v60, 16, v159
	v_xor_b32_e32 v80, 0x80000000, v60
	v_pk_fma_f32 v[80:81], v[100:101], v[162:163], v[80:81]
	v_pk_fma_f32 v[82:83], v[0:1], v[160:161], v[82:83]
	v_pk_fma_f32 v[58:59], v[58:59], v[80:81], v[60:61]
	v_pk_fma_f32 v[56:57], v[56:57], v[82:83], v[62:63]
	v_pk_add_f32 v[62:63], v[154:155], -1.0 op_sel_hi:[1,0]
	v_pk_add_f32 v[60:61], v[156:157], -1.0 op_sel_hi:[1,0]
	s_waitcnt vmcnt(1)
; __device__ __forceinline__ void rwkv_prep_item(const Params& p, const Lt& lt, int l, int item) {
;     ...
;         for (int ct = 0; ct < 4; ++ct) {
;             const int crow = h * 64 + ct * 16 + qi;
;             f32x4 aw = {0.f, 0.f, 0.f, 0.f}, aa = aw, ag = aw;
; #pragma unroll
;             for (int ks = 0; ks < 2; ++ks) {
;                 aw = __builtin_amdgcn_mfma_f32_16x16x32_bf16(*(const bf16x8*)(decT + crow * 64 + ks * 32 + quad * 8), fw[ks], aw, 0, 0, 0);
;                 aa = __builtin_amdgcn_mfma_f32_16x16x32_bf16(*(const bf16x8*)(aT + crow * 64 + ks * 32 + quad * 8), fa[ks], aa, 0, 0, 0);
;             }
; #pragma unroll
;             for (int ks = 0; ks < 4; ++ks) ag = __builtin_amdgcn_mfma_f32_16x16x32_bf16(*(const bf16x8*)(gT + crow * 128 + ks * 32 + quad * 8), fg[ks], ag, 0, 0, 0);
;             const int c = h * 64 + ct * 16 + quad * 4;
;             const f32x4 mr = *(const f32x4*)(mu + c), mk = *(const f32x4*)(mu + COL_K + c), mv = *(const f32x4*)(mu + COL_V + c);
;             const f32x4 cr = ld_bf4(pt + c), ck = ld_bf4(pt + COL_K + c), cv = ld_bf4(pt + COL_V + c);
;             const f32x4 qr = ld_bf4(pp + c) * pm, qk = ld_bf4(pp + COL_K + c) * pm, qv = ld_bf4(pp + COL_V + c) * pm;
;             const f32x4 r = cr + (qr - cr) * mr, k = ck + (qk - ck) * mk, v = cv + (qv - cv) * mv;
;             const f32x4 w0v = *(const f32x4*)(w0 + c), a0v = *(const f32x4*)(a0 + c), kkv = *(const f32x4*)(kkp + c), kav = *(const f32x4*)(kap + c), rkv = *(const f32x4*)(rkp + c);
;             f32x4 dec, a, kk, k2;
; #pragma unroll
;             for (int j = 0; j < 4; ++j) {
;                 const float z = -(w0v[j] + aw[j]);
;                 const float sp = fmaxf(z, 0.f) + __logf(1.0f + __expf(-fabsf(z)));
;                 dec[j] = __expf(-__expf(-sp - 0.5f));
;                 a[j] = sigmoidf_(a0v[j] + aa[j]);
;                 kk[j] = k[j] * kkv[j];
;                 nrm += kk[j] * kk[j];
;                 k2[j] = k[j] * (1.0f + (a[j] - 1.0f) * kav[j]);
;                 bon += r[j] * k2[j] * rkv[j];
;             }
;             va[ct] = a; vkk[ct] = kk;
;             { const int cc = ct * 16 + quad * 4; *(f32x4*)(ob + cc * 4) = dec; st_bf4(ob + 512 + cc * 2, k2); st_bf4(ob + 640 + cc * 2, v); st_bf4(ob + 768 + cc * 2, r); }
;             st_bf4((unsigned char*)((bf16_t*)gate + (size_t)t * RW + c), ag);
	v_pk_fma_f32 v[62:63], v[76:77], v[62:63], 1.0 op_sel_hi:[1,1,0]
	v_pk_fma_f32 v[60:61], v[78:79], v[60:61], 1.0 op_sel_hi:[1,1,0]
	v_pk_mul_f32 v[158:159], v[72:73], v[56:57]
	v_pk_mul_f32 v[56:57], v[56:57], v[62:63]
	v_pk_mul_f32 v[60:61], v[58:59], v[60:61]
	v_sub_u32_e32 v233, v44, v231
	ds_write_b128 v233, v[64:67]
	v_lshl_add_u64 v[44:45], v[120:121], 0, v[104:105]
	v_mul_f32_e32 v62, v172, v56
	v_cvt_pk_bf16_f32 v46, v56, v57
	v_cvt_pk_bf16_f32 v47, v60, v61
	v_sub_u32_e32 v233, v44, v231
	ds_write_b64 v233, v[40:41] offset:640
	v_cvt_pk_bf16_f32 v40, v172, v173
	v_cvt_pk_bf16_f32 v41, v170, v171
	s_or_b32 s0, s10, 48
	s_waitcnt vmcnt(0)
	v_fmac_f32_e32 v185, v68, v62
	v_mul_f32_e32 v62, v173, v57
	v_sub_u32_e32 v233, v44, v231
	ds_write_b64 v233, v[46:47] offset:512
	v_sub_u32_e32 v233, v44, v231
	ds_write_b64 v233, v[40:41] offset:768
	v_or_b32_e32 v44, s0, v180
	v_fmac_f32_e32 v185, v69, v62
	v_mul_f32_e32 v62, v170, v60
	global_store_dwordx2 v[140:141], v[36:37], off offset:64
	v_lshlrev_b32_e32 v36, 7, v44
	v_mov_b32_e32 v37, v3
	v_fmac_f32_e32 v185, v70, v62
	v_pk_mul_f32 v[160:161], v[74:75], v[58:59]
	v_mul_f32_e32 v58, v171, v61
	v_lshl_add_u64 v[38:39], v[88:89], 0, v[36:37]
	v_fmac_f32_e32 v185, v71, v58
	v_lshl_add_u64 v[36:37], v[92:93], 0, v[36:37]
	global_load_dwordx4 v[40:43], v[38:39], off
	global_load_dwordx4 v[56:59], v[36:37], off
	global_load_dwordx4 v[60:63], v[38:39], off offset:64
	global_load_dwordx4 v[68:71], v[36:37], off offset:64
	v_lshlrev_b32_e32 v36, 8, v44
	v_mov_b32_e32 v37, v3
	v_lshl_add_u64 v[36:37], v[94:95], 0, v[36:37]
	global_load_dwordx4 v[52:55], v[36:37], off
	global_load_dwordx4 v[48:51], v[36:37], off offset:64
	global_load_dwordx4 v[44:47], v[36:37], off offset:128
	s_nop 0
	global_load_dwordx4 v[36:39], v[36:37], off offset:192
	v_pk_mul_f32 v[162:163], v[158:159], v[158:159]
	v_pk_mul_f32 v[164:165], v[160:161], v[160:161]
	s_waitcnt vmcnt(7)
	v_mfma_f32_16x16x32_bf16 v[40:43], v[40:43], v[20:23], 0
	s_waitcnt vmcnt(6)
	v_mfma_f32_16x16x32_bf16 v[56:59], v[56:59], v[28:31], 0
	s_waitcnt vmcnt(5)
	v_mfma_f32_16x16x32_bf16 v[64:67], v[60:63], v[24:27], v[40:43]
	s_nop 3
	v_or_b32_e32 v40, s0, v181
	v_lshlrev_b32_e32 v40, 2, v40
	s_waitcnt vmcnt(4)
	v_mfma_f32_16x16x32_bf16 v[60:63], v[68:71], v[32:35], v[56:59]
	global_load_dwordx4 v[68:71], v184, s[8:9] offset:192
	s_nop 1
	global_load_dwordx4 v[56:59], v184, s[8:9] offset:3264
	s_nop 0
	global_load_dwordx4 v[40:43], v40, s[52:53]
	s_nop 0
	global_load_dwordx2 v[72:73], v[134:135], off offset:96
	global_load_dwordx2 v[174:175], v[134:135], off offset:1632
	global_load_dwordx2 v[76:77], v[134:135], off offset:3168
	s_waitcnt vmcnt(9)
	v_mfma_f32_16x16x32_bf16 v[52:55], v[52:55], v[4:7], 0
	global_load_dwordx2 v[80:81], v[132:133], off offset:1632
	s_waitcnt vmcnt(3)
	v_lshlrev_b32_e32 v74, 16, v72
	s_waitcnt vmcnt(1)
	v_lshlrev_b32_e32 v134, 16, v76
	v_and_b32_e32 v135, 0xffff0000, v76
	v_lshlrev_b32_e32 v166, 16, v77
	v_and_b32_e32 v167, 0xffff0000, v77
	global_load_dwordx2 v[76:77], v[132:133], off offset:96
	v_and_b32_e32 v75, 0xffff0000, v72
	v_xor_b32_e32 v85, 0x80000000, v75
	v_xor_b32_e32 v84, 0x80000000, v74
	v_lshlrev_b32_e32 v72, 16, v73
	v_and_b32_e32 v73, 0xffff0000, v73
	v_mfma_f32_16x16x32_bf16 v[48:51], v[48:51], v[8:11], v[52:55]
	s_waitcnt vmcnt(1)
	v_lshlrev_b32_e32 v176, 16, v80
	v_and_b32_e32 v177, 0xffff0000, v80
	v_lshlrev_b32_e32 v178, 16, v81
	v_and_b32_e32 v179, 0xffff0000, v81
	global_load_dwordx2 v[80:81], v[132:133], off offset:3168
	v_mfma_f32_16x16x32_bf16 v[44:47], v[44:47], v[12:15], v[48:51]
	s_waitcnt vmcnt(1)
	v_lshlrev_b32_e32 v78, 16, v76
	v_and_b32_e32 v79, 0xffff0000, v76
	v_pk_fma_f32 v[78:79], v[0:1], v[78:79], v[84:85]
	v_lshlrev_b32_e32 v76, 16, v77
	v_and_b32_e32 v77, 0xffff0000, v77
	v_xor_b32_e32 v85, 0x80000000, v73
	v_xor_b32_e32 v84, 0x80000000, v72
	v_pk_fma_f32 v[168:169], v[68:69], v[78:79], v[74:75]
	v_xor_b32_e32 v69, 0x80000000, v135
	v_xor_b32_e32 v68, 0x80000000, v134
	v_pk_fma_f32 v[76:77], v[100:101], v[76:77], v[84:85]
	v_mfma_f32_16x16x32_bf16 v[36:39], v[36:39], v[16:19], v[44:47]
	v_fma_f32 v132, v70, v76, v72
	v_fma_f32 v133, v71, v77, v73
	s_waitcnt vmcnt(0)
	v_lshlrev_b32_e32 v82, 16, v80
	v_and_b32_e32 v83, 0xffff0000, v80
	v_lshlrev_b32_e32 v80, 16, v81
	v_and_b32_e32 v81, 0xffff0000, v81
	v_pk_fma_f32 v[170:171], v[0:1], v[82:83], v[68:69]
	v_xor_b32_e32 v69, 0x80000000, v167
	v_xor_b32_e32 v68, 0x80000000, v166
	v_pk_fma_f32 v[172:173], v[100:101], v[80:81], v[68:69]
	global_load_dwordx4 v[76:79], v184, s[42:43] offset:192
	global_load_dwordx4 v[84:87], v184, s[44:45] offset:192
	global_load_dwordx4 v[72:75], v184, s[46:47] offset:192
	global_load_dwordx4 v[80:83], v184, s[48:49] offset:192
	global_load_dwordx4 v[68:71], v184, s[50:51] offset:192
	v_pk_fma_f32 v[42:43], v[42:43], v[172:173], v[166:167]
	v_pk_fma_f32 v[40:41], v[40:41], v[170:171], v[134:135]
	v_lshl_add_u64 v[44:45], v[120:121], 0, v[96:97]
	v_cvt_pk_bf16_f32 v40, v40, v41
	v_cvt_pk_bf16_f32 v41, v42, v43
	v_cvt_pk_bf16_f32 v36, v36, v37
	v_cvt_pk_bf16_f32 v37, v38, v39
	s_waitcnt vmcnt(4)
	v_add_f32_e32 v64, v64, v76
	v_max_f32_e64 v76, -v64, 0
	v_mul_f32_e64 v64, |v64|, s57
	v_exp_f32_e32 v64, v64
	v_add_f32_e32 v65, v65, v77
	v_add_f32_e32 v66, v66, v78
	v_add_f32_e32 v67, v67, v79
	v_add_f32_e32 v64, 1.0, v64
	v_cmp_gt_f32_e64 s[0:1], s75, v64
	s_waitcnt vmcnt(3)
; __device__ __forceinline__ float quad_sum(float v) { v += xor16(v); v += xor32(v); return v; }
; __device__ __forceinline__ float sigmoidf_(float x) { return __builtin_amdgcn_rcpf(1.0f + __expf(-x)); }
; __device__ __forceinline__ void st_bf4(unsigned char* q, f32x4 v) { u32x2 w; w.x = cvt_pk_bf16(v[0], v[1]); w.y = cvt_pk_bf16(v[2], v[3]); *(u32x2*)q = w; }
; __device__ __forceinline__ void rwkv_prep_item(const Params& p, const Lt& lt, int l, int item) {
;     ...
; #pragma unroll
;             for (int j = 0; j < 4; ++j) {
;                 const float z = -(w0v[j] + aw[j]);
;                 const float sp = fmaxf(z, 0.f) + __logf(1.0f + __expf(-fabsf(z)));
;                 dec[j] = __expf(-__expf(-sp - 0.5f));
;                 a[j] = sigmoidf_(a0v[j] + aa[j]);
;                 kk[j] = k[j] * kkv[j];
;                 nrm += kk[j] * kk[j];
;                 k2[j] = k[j] * (1.0f + (a[j] - 1.0f) * kav[j]);
;                 bon += r[j] * k2[j] * rkv[j];
;             }
;             va[ct] = a; vkk[ct] = kk;
;             { const int cc = ct * 16 + quad * 4; *(f32x4*)(ob + cc * 4) = dec; st_bf4(ob + 512 + cc * 2, k2); st_bf4(ob + 640 + cc * 2, v); st_bf4(ob + 768 + cc * 2, r); }
;             st_bf4((unsigned char*)((bf16_t*)gate + (size_t)t * RW + c), ag);
;         }
;         nrm = quad_sum(nrm); bon = quad_sum(bon);
	v_add_f32_e32 v60, v60, v84
	v_add_f32_e32 v61, v61, v85
	v_cndmask_b32_e64 v184, 0, 32, s[0:1]
	v_ldexp_f32 v64, v64, v184
	v_log_f32_e32 v64, v64
	v_mul_f32_e32 v60, 0xbfb8aa3b, v60
	v_mul_f32_e32 v61, 0xbfb8aa3b, v61
	v_exp_f32_e32 v60, v60
	v_mul_f32_e32 v184, 0x3f317217, v64
	v_fma_f32 v184, v64, s58, -v184
	v_fmac_f32_e32 v184, 0x3377d1cf, v64
	v_fmac_f32_e32 v184, 0x3f317217, v64
	v_cmp_lt_f32_e64 s[4:5], |v64|, s59
	v_exp_f32_e32 v61, v61
	v_add_f32_e32 v62, v62, v86
	v_cndmask_b32_e64 v64, v64, v184, s[4:5]
	v_cndmask_b32_e64 v184, 0, v243, s[0:1]
	v_sub_f32_e32 v64, v64, v184
	v_add_f32_e32 v64, v76, v64
	v_max_f32_e64 v76, -v65, 0
	v_mul_f32_e64 v65, |v65|, s57
	v_exp_f32_e32 v65, v65
	v_add_f32_e32 v63, v63, v87
	v_add_f32_e32 v60, 1.0, v60
	v_add_f32_e32 v61, 1.0, v61
	v_add_f32_e32 v65, 1.0, v65
	v_cmp_gt_f32_e64 s[0:1], s75, v65
	v_mul_f32_e32 v62, 0xbfb8aa3b, v62
	v_mul_f32_e32 v63, 0xbfb8aa3b, v63
	v_cndmask_b32_e64 v77, 0, 32, s[0:1]
	v_ldexp_f32 v65, v65, v77
	v_log_f32_e32 v65, v65
	v_rcp_f32_e32 v60, v60
	v_rcp_f32_e32 v61, v61
	v_exp_f32_e32 v62, v62
	v_mul_f32_e32 v77, 0x3f317217, v65
	v_fma_f32 v77, v65, s58, -v77
	v_fmac_f32_e32 v77, 0x3377d1cf, v65
	v_fmac_f32_e32 v77, 0x3f317217, v65
	v_cmp_lt_f32_e64 s[4:5], |v65|, s59
	v_exp_f32_e32 v63, v63
	v_lshlrev_b32_e32 v78, 16, v174
	v_cndmask_b32_e64 v65, v65, v77, s[4:5]
	v_cndmask_b32_e64 v77, 0, v243, s[0:1]
	v_sub_f32_e32 v65, v65, v77
	v_add_f32_e32 v65, v76, v65
	v_max_f32_e64 v76, -v66, 0
	v_mul_f32_e64 v66, |v66|, s57
	v_exp_f32_e32 v66, v66
	v_and_b32_e32 v79, 0xffff0000, v174
	v_xor_b32_e32 v87, 0x80000000, v79
	v_xor_b32_e32 v86, 0x80000000, v78
	v_add_f32_e32 v66, 1.0, v66
	v_cmp_gt_f32_e64 s[0:1], s75, v66
	v_pk_fma_f32 v[86:87], v[0:1], v[176:177], v[86:87]
	v_add_f32_e32 v62, 1.0, v62
	v_cndmask_b32_e64 v77, 0, 32, s[0:1]
	v_ldexp_f32 v66, v66, v77
	v_log_f32_e32 v66, v66
	v_add_f32_e32 v63, 1.0, v63
	v_pk_fma_f32 v[78:79], v[56:57], v[86:87], v[78:79]
	v_pk_add_f32 v[86:87], v[60:61], -1.0 op_sel_hi:[1,0]
	v_mul_f32_e32 v77, 0x3f317217, v66
	v_fma_f32 v77, v66, s58, -v77
	v_fmac_f32_e32 v77, 0x3377d1cf, v66
	v_fmac_f32_e32 v77, 0x3f317217, v66
	v_cmp_lt_f32_e64 s[4:5], |v66|, s59
	v_rcp_f32_e32 v62, v62
	v_rcp_f32_e32 v63, v63
	v_cndmask_b32_e64 v66, v66, v77, s[4:5]
	v_cndmask_b32_e64 v77, 0, v243, s[0:1]
	v_sub_f32_e32 v66, v66, v77
	v_add_f32_e32 v66, v76, v66
	v_max_f32_e64 v76, -v67, 0
	v_mul_f32_e64 v67, |v67|, s57
	v_exp_f32_e32 v67, v67
	s_waitcnt vmcnt(1)
	v_pk_fma_f32 v[80:81], v[80:81], v[86:87], 1.0 op_sel_hi:[1,1,0]
	v_pk_mul_f32 v[56:57], v[72:73], v[78:79]
	v_pk_mul_f32 v[78:79], v[78:79], v[80:81]
	v_add_f32_e32 v67, 1.0, v67
	v_cmp_gt_f32_e64 s[0:1], s75, v67
	v_mul_f32_e32 v80, v168, v78
	s_waitcnt vmcnt(0)
	v_fmac_f32_e32 v185, v68, v80
	v_cndmask_b32_e64 v77, 0, 32, s[0:1]
	v_ldexp_f32 v67, v67, v77
	v_log_f32_e32 v67, v67
	v_mul_f32_e32 v68, v169, v79
	v_fmac_f32_e32 v185, v69, v68
	v_pk_add_f32 v[68:69], v[62:63], -1.0 op_sel_hi:[1,0]
	v_mul_f32_e32 v77, 0x3f317217, v67
	v_fma_f32 v77, v67, s58, -v77
	v_fmac_f32_e32 v77, 0x3377d1cf, v67
	v_fmac_f32_e32 v77, 0x3f317217, v67
	v_cmp_lt_f32_e64 s[4:5], |v67|, s59
	v_pk_fma_f32 v[68:69], v[82:83], v[68:69], 1.0 op_sel_hi:[1,1,0]
	v_sub_f32_e32 v64, -0.5, v64
	v_cndmask_b32_e64 v67, v67, v77, s[4:5]
	v_cndmask_b32_e64 v77, 0, v243, s[0:1]
	v_sub_f32_e32 v67, v67, v77
	v_add_f32_e32 v67, v76, v67
	v_lshlrev_b32_e32 v76, 16, v175
	v_and_b32_e32 v77, 0xffff0000, v175
	v_xor_b32_e32 v85, 0x80000000, v77
	v_xor_b32_e32 v84, 0x80000000, v76
	v_pk_fma_f32 v[84:85], v[100:101], v[178:179], v[84:85]
	v_sub_f32_e32 v65, -0.5, v65
	v_pk_fma_f32 v[58:59], v[58:59], v[84:85], v[76:77]
	v_sub_f32_e32 v66, -0.5, v66
	v_pk_mul_f32 v[68:69], v[58:59], v[68:69]
	v_sub_f32_e32 v67, -0.5, v67
	v_mul_f32_e32 v76, v132, v68
	v_fmac_f32_e32 v185, v70, v76
	v_add_f32_e32 v70, v136, v137
	v_add_f32_e32 v70, v138, v70
	v_add_f32_e32 v70, v139, v70
	v_mul_f32_e32 v64, 0x3fb8aa3b, v64
	v_mul_f32_e32 v65, 0x3fb8aa3b, v65
	v_mul_f32_e32 v66, 0x3fb8aa3b, v66
	v_mul_f32_e32 v67, 0x3fb8aa3b, v67
	v_add_f32_e32 v70, v70, v150
	v_exp_f32_e32 v64, v64
	v_exp_f32_e32 v65, v65
	v_exp_f32_e32 v66, v66
	v_exp_f32_e32 v67, v67
	v_add_f32_e32 v70, v151, v70
	v_add_f32_e32 v70, v152, v70
	v_add_f32_e32 v70, v153, v70
	v_add_f32_e32 v70, v70, v162
	v_mul_f32_e32 v64, 0xbfb8aa3b, v64
	v_mul_f32_e32 v65, 0xbfb8aa3b, v65
	v_mul_f32_e32 v66, 0xbfb8aa3b, v66
	v_mul_f32_e32 v67, 0xbfb8aa3b, v67
	v_add_f32_e32 v70, v163, v70
	v_exp_f32_e32 v64, v64
	v_exp_f32_e32 v65, v65
	v_exp_f32_e32 v66, v66
	v_exp_f32_e32 v67, v67
	v_add_f32_e32 v70, v164, v70
	v_pk_mul_f32 v[72:73], v[56:57], v[56:57]
	v_add_f32_e32 v70, v165, v70
	v_pk_mul_f32 v[58:59], v[74:75], v[58:59]
	v_add_f32_e32 v70, v70, v72
	v_pk_mul_f32 v[74:75], v[58:59], v[58:59]
	v_add_f32_e32 v70, v73, v70
	v_add_f32_e32 v70, v74, v70
	v_sub_u32_e32 v233, v44, v231
	ds_write_b128 v233, v[64:67]
	v_lshl_add_u64 v[44:45], v[120:121], 0, v[98:99]
	v_add_f32_e32 v70, v75, v70
	v_cvt_pk_bf16_f32 v46, v78, v79
	v_cvt_pk_bf16_f32 v47, v68, v69
	v_sub_u32_e32 v233, v44, v231
	ds_write_b64 v233, v[40:41] offset:640
	v_cvt_pk_bf16_f32 v40, v168, v169
	v_cvt_pk_bf16_f32 v41, v132, v133
	v_sub_u32_e32 v233, v44, v231
	ds_write_b64 v233, v[46:47] offset:512
	v_sub_u32_e32 v233, v44, v231
	ds_write_b64 v233, v[40:41] offset:768
	global_store_dwordx2 v[140:141], v[36:37], off offset:96
	ds_bpermute_b32 v36, v182, v70
	v_mul_f32_e32 v72, v133, v69
	v_fmac_f32_e32 v185, v71, v72
	s_waitcnt lgkmcnt(0)
	v_add_f32_e32 v36, v70, v36
	ds_bpermute_b32 v37, v183, v36
	s_waitcnt lgkmcnt(0)
; __device__ __forceinline__ float quad_sum(float v) { v += xor16(v); v += xor32(v); return v; }
; __device__ __forceinline__ void st_bf4(unsigned char* q, f32x4 v) { u32x2 w; w.x = cvt_pk_bf16(v[0], v[1]); w.y = cvt_pk_bf16(v[2], v[3]); *(u32x2*)q = w; }
; __device__ __forceinline__ void rwkv_prep_item(const Params& p, const Lt& lt, int l, int item) {
;     ...
;         nrm = quad_sum(nrm); bon = quad_sum(bon);
;         const float inv = rsqrtf(fmaxf(nrm, 1e-24f));
; #pragma unroll
;         for (int ct = 0; ct < 4; ++ct) {
;             const int cc = ct * 16 + quad * 4;
;             const f32x4 kkn = vkk[ct] * inv;
;             st_bf4(ob + 256 + cc * 2, -kkn);
;             st_bf4(ob + 384 + cc * 2, kkn * va[ct]);
;         }
;         if (quad == 0) bonus[(size_t)t * 16 + h] = bon;
	v_add_f32_e32 v38, v36, v37
	v_max_f32_e32 v38, 0x179abe15, v38
	v_rsq_f32_e32 v38, v38
	ds_bpermute_b32 v36, v182, v185
	v_pk_mul_f32 v[40:41], v[126:127], v[38:39] op_sel_hi:[1,0]
	v_pk_mul_f32 v[42:43], v[128:129], v[38:39] op_sel_hi:[1,0]
	v_xor_b32_e32 v44, 0x80000000, v41
	v_xor_b32_e32 v39, 0x80000000, v43
	v_xor_b32_e32 v45, 0x80000000, v42
	v_xor_b32_e32 v46, 0x80000000, v40
	v_pk_mul_f32 v[42:43], v[124:125], v[42:43]
	v_pk_mul_f32 v[40:41], v[122:123], v[40:41]
	v_cvt_pk_bf16_f32 v44, v46, v44
	v_cvt_pk_bf16_f32 v40, v40, v41
	v_cvt_pk_bf16_f32 v41, v42, v43
	v_cvt_pk_bf16_f32 v45, v45, v39
	v_sub_u32_e32 v233, v130, v231
	ds_write_b64 v233, v[40:41] offset:384
	v_pk_mul_f32 v[40:41], v[146:147], v[38:39] op_sel_hi:[1,0]
	v_pk_mul_f32 v[42:43], v[148:149], v[38:39] op_sel_hi:[1,0]
	v_sub_u32_e32 v233, v130, v231
	ds_write_b64 v233, v[44:45] offset:256
	v_xor_b32_e32 v39, 0x80000000, v43
	v_xor_b32_e32 v45, 0x80000000, v42
	v_xor_b32_e32 v44, 0x80000000, v41
	v_xor_b32_e32 v46, 0x80000000, v40
	v_pk_mul_f32 v[42:43], v[144:145], v[42:43]
	v_pk_mul_f32 v[40:41], v[142:143], v[40:41]
	s_waitcnt lgkmcnt(0)
	v_add_f32_e32 v36, v185, v36
	v_cvt_pk_bf16_f32 v40, v40, v41
	v_cvt_pk_bf16_f32 v41, v42, v43
	v_cvt_pk_bf16_f32 v44, v46, v44
	v_cvt_pk_bf16_f32 v45, v45, v39
	v_sub_u32_e32 v233, v130, v231
	ds_write_b64 v233, v[40:41] offset:416
	v_pk_mul_f32 v[40:41], v[158:159], v[38:39] op_sel_hi:[1,0]
	v_pk_mul_f32 v[42:43], v[160:161], v[38:39] op_sel_hi:[1,0]
	ds_bpermute_b32 v37, v183, v36
	v_sub_u32_e32 v233, v130, v231
	ds_write_b64 v233, v[44:45] offset:288
	v_xor_b32_e32 v39, 0x80000000, v43
	v_xor_b32_e32 v45, 0x80000000, v42
	v_xor_b32_e32 v44, 0x80000000, v41
	v_xor_b32_e32 v46, 0x80000000, v40
	v_pk_mul_f32 v[42:43], v[156:157], v[42:43]
	v_pk_mul_f32 v[40:41], v[154:155], v[40:41]
	v_cvt_pk_bf16_f32 v44, v46, v44
	v_cvt_pk_bf16_f32 v40, v40, v41
	v_cvt_pk_bf16_f32 v41, v42, v43
	v_cvt_pk_bf16_f32 v45, v45, v39
	v_sub_u32_e32 v233, v130, v231
	ds_write_b64 v233, v[40:41] offset:448
	v_pk_mul_f32 v[40:41], v[56:57], v[38:39] op_sel_hi:[1,0]
	v_pk_mul_f32 v[38:39], v[58:59], v[38:39] op_sel_hi:[1,0]
	v_sub_u32_e32 v233, v130, v231
	ds_write_b64 v233, v[44:45] offset:320
	v_xor_b32_e32 v43, 0x80000000, v39
	v_xor_b32_e32 v44, 0x80000000, v38
	v_xor_b32_e32 v42, 0x80000000, v41
	v_xor_b32_e32 v45, 0x80000000, v40
	v_pk_mul_f32 v[38:39], v[62:63], v[38:39]
	v_pk_mul_f32 v[40:41], v[60:61], v[40:41]
	v_cvt_pk_bf16_f32 v42, v45, v42
	v_cvt_pk_bf16_f32 v43, v44, v43
	v_cvt_pk_bf16_f32 v40, v40, v41
	v_cvt_pk_bf16_f32 v41, v38, v39
	v_sub_u32_e32 v233, v130, v231
	ds_write_b64 v233, v[42:43] offset:352
	v_sub_u32_e32 v233, v130, v231
	ds_write_b64 v233, v[40:41] offset:480
	s_waitcnt lgkmcnt(0)
	s_mov_b32 s98, -1
	s_mov_b32 s99, 0xffffff
	s_mov_b64 exec, s[98:99]
	s_movk_i32 s98, 896
	s_mov_b32 s99, 0
	v_lshl_add_u64 v[228:229], v[234:235], 0, s[98:99]
	s_movk_i32 s98, 0x2a00
	ds_read_b128 v[210:213], v226 offset:0
	ds_read_b128 v[214:217], v226 offset:912
	ds_read_b128 v[218:221], v226 offset:1824
	ds_read_b128 v[222:225], v226 offset:2736
	s_waitcnt lgkmcnt(3)
	global_store_dwordx4 v[228:229], v[210:213], off
	v_lshl_add_u64 v[228:229], v[228:229], 0, s[98:99]
	s_waitcnt lgkmcnt(2)
	global_store_dwordx4 v[228:229], v[214:217], off
	v_lshl_add_u64 v[228:229], v[228:229], 0, s[98:99]
	s_waitcnt lgkmcnt(1)
	global_store_dwordx4 v[228:229], v[218:221], off
	v_lshl_add_u64 v[228:229], v[228:229], 0, s[98:99]
	s_waitcnt lgkmcnt(0)
	global_store_dwordx4 v[228:229], v[222:225], off
	v_lshl_add_u64 v[228:229], v[228:229], 0, s[98:99]
	ds_read_b128 v[210:213], v226 offset:3648
	ds_read_b128 v[214:217], v226 offset:4560
	ds_read_b128 v[218:221], v226 offset:5472
	ds_read_b128 v[222:225], v226 offset:6384
	s_waitcnt lgkmcnt(3)
	global_store_dwordx4 v[228:229], v[210:213], off
	v_lshl_add_u64 v[228:229], v[228:229], 0, s[98:99]
	s_waitcnt lgkmcnt(2)
	global_store_dwordx4 v[228:229], v[214:217], off
	v_lshl_add_u64 v[228:229], v[228:229], 0, s[98:99]
	s_waitcnt lgkmcnt(1)
	global_store_dwordx4 v[228:229], v[218:221], off
	v_lshl_add_u64 v[228:229], v[228:229], 0, s[98:99]
	s_waitcnt lgkmcnt(0)
	global_store_dwordx4 v[228:229], v[222:225], off
	v_lshl_add_u64 v[228:229], v[228:229], 0, s[98:99]
	ds_read_b128 v[210:213], v226 offset:7296
	ds_read_b128 v[214:217], v226 offset:8208
	ds_read_b128 v[218:221], v226 offset:9120
	ds_read_b128 v[222:225], v226 offset:10032
	s_waitcnt lgkmcnt(3)
	global_store_dwordx4 v[228:229], v[210:213], off
	v_lshl_add_u64 v[228:229], v[228:229], 0, s[98:99]
	s_waitcnt lgkmcnt(2)
	global_store_dwordx4 v[228:229], v[214:217], off
	v_lshl_add_u64 v[228:229], v[228:229], 0, s[98:99]
	s_waitcnt lgkmcnt(1)
	global_store_dwordx4 v[228:229], v[218:221], off
	v_lshl_add_u64 v[228:229], v[228:229], 0, s[98:99]
	s_waitcnt lgkmcnt(0)
	global_store_dwordx4 v[228:229], v[222:225], off
	v_lshl_add_u64 v[228:229], v[228:229], 0, s[98:99]
	ds_read_b128 v[210:213], v226 offset:10944
	ds_read_b128 v[214:217], v226 offset:11856
	ds_read_b128 v[218:221], v226 offset:12768
	ds_read_b128 v[222:225], v226 offset:13680
	s_waitcnt lgkmcnt(3)
	global_store_dwordx4 v[228:229], v[210:213], off
	v_lshl_add_u64 v[228:229], v[228:229], 0, s[98:99]
	s_waitcnt lgkmcnt(2)
	global_store_dwordx4 v[228:229], v[214:217], off
	v_lshl_add_u64 v[228:229], v[228:229], 0, s[98:99]
	s_waitcnt lgkmcnt(1)
	global_store_dwordx4 v[228:229], v[218:221], off
	v_lshl_add_u64 v[228:229], v[228:229], 0, s[98:99]
	s_waitcnt lgkmcnt(0)
	global_store_dwordx4 v[228:229], v[222:225], off
	v_lshl_add_u64 v[228:229], v[228:229], 0, s[98:99]
	s_mov_b64 exec, -1
	s_and_saveexec_b64 s[0:1], vcc
	s_cbranch_execz .LBB0_347
	s_lshl_b32 s10, s56, 2
	v_lshl_add_u64 v[38:39], v[90:91], 0, s[10:11]
	s_waitcnt lgkmcnt(0)
	v_add_f32_e32 v36, v36, v37
	global_store_dword v[38:39], v36, off offset:4
; __device__ __forceinline__ void rwkv_prep_item(const Params& p, const Lt& lt, int l, int item) {
;     ...
;     for (int hh = 0; hh < 3; ++hh) {
;         const int h = hg * 3 + hh;
;         f32x4 va[4], vkk[4];
;         float nrm = 0.f, bon = 0.f;
;         unsigned char* ob = opnd + (size_t)t * OPTB + h * OPB;
; #pragma unroll
;         for (int ct = 0; ct < 4; ++ct) {
;             const int crow = h * 64 + ct * 16 + qi;
;             f32x4 aw = {0.f, 0.f, 0.f, 0.f}, aa = aw, ag = aw;
; #pragma unroll
;             for (int ks = 0; ks < 2; ++ks) {
;                 aw = __builtin_amdgcn_mfma_f32_16x16x32_bf16(*(const bf16x8*)(decT + crow * 64 + ks * 32 + quad * 8), fw[ks], aw, 0, 0, 0);
;                 aa = __builtin_amdgcn_mfma_f32_16x16x32_bf16(*(const bf16x8*)(aT + crow * 64 + ks * 32 + quad * 8), fa[ks], aa, 0, 0, 0);
;             }
; #pragma unroll
;             for (int ks = 0; ks < 4; ++ks) ag = __builtin_amdgcn_mfma_f32_16x16x32_bf16(*(const bf16x8*)(gT + crow * 128 + ks * 32 + quad * 8), fg[ks], ag, 0, 0, 0);
;             const int c = h * 64 + ct * 16 + quad * 4;
;             const f32x4 mr = *(const f32x4*)(mu + c), mk = *(const f32x4*)(mu + COL_K + c), mv = *(const f32x4*)(mu + COL_V + c);
;             const f32x4 cr = ld_bf4(pt + c), ck = ld_bf4(pt + COL_K + c), cv = ld_bf4(pt + COL_V + c);
;             const f32x4 qr = ld_bf4(pp + c) * pm, qk = ld_bf4(pp + COL_K + c) * pm, qv = ld_bf4(pp + COL_V + c) * pm;
;             const f32x4 r = cr + (qr - cr) * mr, k = ck + (qk - ck) * mk, v = cv + (qv - cv) * mv;
;             const f32x4 w0v = *(const f32x4*)(w0 + c), a0v = *(const f32x4*)(a0 + c), kkv = *(const f32x4*)(kkp + c), kav = *(const f32x4*)(kap + c), rkv = *(const f32x4*)(rkp + c);
;             f32x4 dec, a, kk, k2;
; #pragma unroll
;             for (int j = 0; j < 4; ++j) {
;                 const float z = -(w0v[j] + aw[j]);
;                 const float sp = fmaxf(z, 0.f) + __logf(1.0f + __expf(-fabsf(z)));
;                 dec[j] = __expf(-__expf(-sp - 0.5f));
;                 a[j] = sigmoidf_(a0v[j] + aa[j]);
;                 kk[j] = k[j] * kkv[j];
;                 nrm += kk[j] * kk[j];
;                 k2[j] = k[j] * (1.0f + (a[j] - 1.0f) * kav[j]);
;                 bon += r[j] * k2[j] * rkv[j];
;             }
;             va[ct] = a; vkk[ct] = kk;
.LBB0_347:
	s_or_b64 exec, exec, s[0:1]
	s_add_i32 s0, s56, 2
	s_mul_i32 s10, s0, 0x380
	v_lshl_add_u64 v[118:119], v[118:119], 0, s[10:11]
	s_lshl_b32 s10, s0, 6
	v_or_b32_e32 v40, s10, v180
	v_lshlrev_b32_e32 v36, 7, v40
	s_waitcnt lgkmcnt(0)
	v_mov_b32_e32 v37, v3
	v_lshl_add_u64 v[38:39], v[88:89], 0, v[36:37]
	v_lshl_add_u64 v[36:37], v[92:93], 0, v[36:37]
	global_load_dwordx4 v[52:55], v[38:39], off
	global_load_dwordx4 v[56:59], v[36:37], off
	global_load_dwordx4 v[60:63], v[38:39], off offset:64
	global_load_dwordx4 v[68:71], v[36:37], off offset:64
	v_or_b32_e32 v72, s10, v181
	v_lshlrev_b32_e32 v36, 8, v40
	v_mov_b32_e32 v37, v3
	v_lshlrev_b32_e32 v132, 1, v72
	v_mov_b32_e32 v133, v3
	v_lshl_add_u64 v[36:37], v[94:95], 0, v[36:37]
	v_lshlrev_b32_e32 v158, 2, v72
	v_lshl_add_u64 v[126:127], v[114:115], 0, v[132:133]
	global_load_dwordx4 v[48:51], v[36:37], off
	global_load_dwordx4 v[44:47], v[36:37], off offset:64
	global_load_dwordx4 v[40:43], v[36:37], off offset:128
	s_nop 0
	global_load_dwordx4 v[36:39], v[36:37], off offset:192
	v_lshl_add_u64 v[124:125], v[110:111], 0, v[132:133]
	v_lshl_add_u64 v[116:117], v[116:117], 0, v[132:133]
	s_waitcnt vmcnt(7)
	v_mfma_f32_16x16x32_bf16 v[52:55], v[52:55], v[20:23], 0
	s_waitcnt vmcnt(6)
	v_mfma_f32_16x16x32_bf16 v[56:59], v[56:59], v[28:31], 0
	s_waitcnt vmcnt(5)
	v_mfma_f32_16x16x32_bf16 v[64:67], v[60:63], v[24:27], v[52:55]
	s_waitcnt vmcnt(4)
	v_mfma_f32_16x16x32_bf16 v[56:59], v[68:71], v[32:35], v[56:59]
	global_load_dwordx4 v[68:71], v158, s[8:9]
	global_load_dwordx4 v[60:63], v158, s[8:9] offset:3072
	global_load_dwordx4 v[52:55], v158, s[52:53]
	global_load_dwordx2 v[72:73], v[126:127], off
	global_load_dwordx2 v[120:121], v[126:127], off offset:1536
	global_load_dwordx2 v[76:77], v[126:127], off offset:3072
	s_waitcnt vmcnt(9)
	v_mfma_f32_16x16x32_bf16 v[48:51], v[48:51], v[4:7], 0
	global_load_dwordx2 v[80:81], v[124:125], off offset:1536
	s_waitcnt vmcnt(3)
	v_lshlrev_b32_e32 v74, 16, v72
	s_waitcnt vmcnt(1)
	v_lshlrev_b32_e32 v134, 16, v76
	v_and_b32_e32 v135, 0xffff0000, v76
	v_lshlrev_b32_e32 v136, 16, v77
	v_and_b32_e32 v137, 0xffff0000, v77
	global_load_dwordx2 v[76:77], v[124:125], off
	v_and_b32_e32 v75, 0xffff0000, v72
	v_xor_b32_e32 v85, 0x80000000, v75
	v_xor_b32_e32 v84, 0x80000000, v74
	v_lshlrev_b32_e32 v72, 16, v73
	v_and_b32_e32 v73, 0xffff0000, v73
	v_mfma_f32_16x16x32_bf16 v[44:47], v[44:47], v[8:11], v[48:51]
	s_waitcnt vmcnt(1)
	v_lshlrev_b32_e32 v122, 16, v80
	v_and_b32_e32 v123, 0xffff0000, v80
	v_lshlrev_b32_e32 v128, 16, v81
	v_and_b32_e32 v129, 0xffff0000, v81
	global_load_dwordx2 v[80:81], v[124:125], off offset:3072
	v_mfma_f32_16x16x32_bf16 v[40:43], v[40:43], v[12:15], v[44:47]
	s_waitcnt vmcnt(1)
	v_lshlrev_b32_e32 v78, 16, v76
	v_and_b32_e32 v79, 0xffff0000, v76
	v_pk_fma_f32 v[78:79], v[0:1], v[78:79], v[84:85]
	v_lshlrev_b32_e32 v76, 16, v77
	v_and_b32_e32 v77, 0xffff0000, v77
	v_xor_b32_e32 v85, 0x80000000, v73
	v_xor_b32_e32 v84, 0x80000000, v72
	v_pk_fma_f32 v[140:141], v[68:69], v[78:79], v[74:75]
	v_xor_b32_e32 v69, 0x80000000, v135
	v_xor_b32_e32 v68, 0x80000000, v134
	v_pk_fma_f32 v[76:77], v[100:101], v[76:77], v[84:85]
	v_mfma_f32_16x16x32_bf16 v[36:39], v[36:39], v[16:19], v[40:43]
	v_fma_f32 v138, v70, v76, v72
	v_fma_f32 v139, v71, v77, v73
	v_lshl_add_u64 v[44:45], v[118:119], 0, v[112:113]
	v_lshl_add_u64 v[112:113], v[118:119], 0, v[2:3]
	s_waitcnt vmcnt(0)
	v_lshlrev_b32_e32 v82, 16, v80
	v_and_b32_e32 v83, 0xffff0000, v80
	v_lshlrev_b32_e32 v80, 16, v81
	v_and_b32_e32 v81, 0xffff0000, v81
	v_cvt_pk_bf16_f32 v36, v36, v37
	v_cvt_pk_bf16_f32 v37, v38, v39
	v_pk_fma_f32 v[142:143], v[0:1], v[82:83], v[68:69]
	v_xor_b32_e32 v69, 0x80000000, v137
	v_xor_b32_e32 v68, 0x80000000, v136
	v_pk_fma_f32 v[144:145], v[100:101], v[80:81], v[68:69]
	global_load_dwordx4 v[84:87], v158, s[42:43]
	global_load_dwordx4 v[80:83], v158, s[44:45]
	global_load_dwordx4 v[68:71], v158, s[46:47]
	global_load_dwordx4 v[76:79], v158, s[48:49]
	global_load_dwordx4 v[72:75], v158, s[50:51]
	v_pk_fma_f32 v[42:43], v[52:53], v[142:143], v[134:135]
	v_pk_fma_f32 v[40:41], v[54:55], v[144:145], v[136:137]
	v_cvt_pk_bf16_f32 v42, v42, v43
	v_cvt_pk_bf16_f32 v43, v40, v41
	v_cvt_pk_bf16_f32 v40, v140, v141
	v_cvt_pk_bf16_f32 v41, v138, v139
	v_sub_u32_e32 v233, v112, v232
	ds_write_b64 v233, v[42:43] offset:640
	v_sub_u32_e32 v233, v112, v232
	ds_write_b64 v233, v[40:41] offset:768
	s_waitcnt vmcnt(4)
	v_add_f32_e32 v64, v64, v84
	v_max_f32_e64 v84, -v64, 0
	v_mul_f32_e64 v64, |v64|, s57
	s_waitcnt vmcnt(3)
; __device__ __forceinline__ float sigmoidf_(float x) { return __builtin_amdgcn_rcpf(1.0f + __expf(-x)); }
; __device__ __forceinline__ void st_bf4(unsigned char* q, f32x4 v) { u32x2 w; w.x = cvt_pk_bf16(v[0], v[1]); w.y = cvt_pk_bf16(v[2], v[3]); *(u32x2*)q = w; }
; __device__ __forceinline__ void rwkv_prep_item(const Params& p, const Lt& lt, int l, int item) {
;     ...
; #pragma unroll
;             for (int j = 0; j < 4; ++j) {
;                 const float z = -(w0v[j] + aw[j]);
;                 const float sp = fmaxf(z, 0.f) + __logf(1.0f + __expf(-fabsf(z)));
;                 dec[j] = __expf(-__expf(-sp - 0.5f));
;                 a[j] = sigmoidf_(a0v[j] + aa[j]);
;                 kk[j] = k[j] * kkv[j];
;                 nrm += kk[j] * kk[j];
;                 k2[j] = k[j] * (1.0f + (a[j] - 1.0f) * kav[j]);
;                 bon += r[j] * k2[j] * rkv[j];
;             }
;             va[ct] = a; vkk[ct] = kk;
;             { const int cc = ct * 16 + quad * 4; *(f32x4*)(ob + cc * 4) = dec; st_bf4(ob + 512 + cc * 2, k2); st_bf4(ob + 640 + cc * 2, v); st_bf4(ob + 768 + cc * 2, r); }
;             st_bf4((unsigned char*)((bf16_t*)gate + (size_t)t * RW + c), ag);
	v_add_f32_e32 v56, v56, v80
	v_exp_f32_e32 v64, v64
	v_mul_f32_e32 v56, 0xbfb8aa3b, v56
	v_exp_f32_e32 v56, v56
	v_add_f32_e32 v64, 1.0, v64
	v_cmp_gt_f32_e64 s[0:1], s75, v64
	v_add_f32_e32 v56, 1.0, v56
	s_nop 0
	v_cndmask_b32_e64 v110, 0, 32, s[0:1]
	v_ldexp_f32 v64, v64, v110
	v_log_f32_e32 v64, v64
	s_nop 0
	v_mul_f32_e32 v110, 0x3f317217, v64
	v_cmp_lt_f32_e64 s[4:5], |v64|, s59
	v_fma_f32 v110, v64, s58, -v110
	v_fmac_f32_e32 v110, 0x3377d1cf, v64
	v_fmac_f32_e32 v110, 0x3f317217, v64
	v_cndmask_b32_e64 v64, v64, v110, s[4:5]
	v_cndmask_b32_e64 v110, 0, v243, s[0:1]
	v_sub_f32_e32 v64, v64, v110
	v_rcp_f32_e32 v110, v56
	v_add_f32_e32 v56, v65, v85
	v_max_f32_e64 v65, -v56, 0
	v_mul_f32_e64 v56, |v56|, s57
	v_add_f32_e32 v64, v84, v64
	v_exp_f32_e32 v56, v56
	v_sub_f32_e32 v64, -0.5, v64
	v_mul_f32_e32 v64, 0x3fb8aa3b, v64
	v_exp_f32_e32 v64, v64
	v_add_f32_e32 v56, 1.0, v56
	v_cmp_gt_f32_e64 s[0:1], s75, v56
	v_mul_f32_e32 v64, 0xbfb8aa3b, v64
	s_nop 0
	v_cndmask_b32_e64 v80, 0, 32, s[0:1]
	v_ldexp_f32 v56, v56, v80
	v_exp_f32_e32 v64, v64
	v_log_f32_e32 v56, v56
	s_nop 0
	v_mul_f32_e32 v80, 0x3f317217, v56
	v_cmp_lt_f32_e64 s[4:5], |v56|, s59
	v_fma_f32 v80, v56, s58, -v80
	v_fmac_f32_e32 v80, 0x3377d1cf, v56
	v_fmac_f32_e32 v80, 0x3f317217, v56
	v_cndmask_b32_e64 v56, v56, v80, s[4:5]
	v_cndmask_b32_e64 v80, 0, v243, s[0:1]
	v_sub_f32_e32 v56, v56, v80
	v_add_f32_e32 v56, v65, v56
	v_sub_f32_e32 v56, -0.5, v56
	v_mul_f32_e32 v56, 0x3fb8aa3b, v56
	v_exp_f32_e32 v56, v56
	s_nop 0
	v_mul_f32_e32 v56, 0xbfb8aa3b, v56
	v_exp_f32_e32 v65, v56
	v_add_f32_e32 v56, v57, v81
	v_mul_f32_e32 v56, 0xbfb8aa3b, v56
	v_exp_f32_e32 v56, v56
	s_nop 0
	v_add_f32_e32 v56, 1.0, v56
	v_rcp_f32_e32 v111, v56
	v_add_f32_e32 v56, v66, v86
	v_max_f32_e64 v57, -v56, 0
	v_mul_f32_e64 v56, |v56|, s57
	v_exp_f32_e32 v56, v56
	s_nop 0
	v_add_f32_e32 v56, 1.0, v56
	v_cmp_gt_f32_e64 s[0:1], s75, v56
	s_nop 1
	v_cndmask_b32_e64 v66, 0, 32, s[0:1]
	v_ldexp_f32 v56, v56, v66
	v_log_f32_e32 v56, v56
	s_nop 0
	v_mul_f32_e32 v66, 0x3f317217, v56
	v_cmp_lt_f32_e64 s[4:5], |v56|, s59
	v_fma_f32 v66, v56, s58, -v66
	v_fmac_f32_e32 v66, 0x3377d1cf, v56
	v_fmac_f32_e32 v66, 0x3f317217, v56
	v_cndmask_b32_e64 v56, v56, v66, s[4:5]
	v_cndmask_b32_e64 v66, 0, v243, s[0:1]
	v_sub_f32_e32 v56, v56, v66
	v_add_f32_e32 v56, v57, v56
	v_sub_f32_e32 v56, -0.5, v56
	v_mul_f32_e32 v56, 0x3fb8aa3b, v56
	v_exp_f32_e32 v56, v56
	s_nop 0
	v_mul_f32_e32 v56, 0xbfb8aa3b, v56
	v_exp_f32_e32 v66, v56
	v_add_f32_e32 v56, v58, v82
	v_mul_f32_e32 v56, 0xbfb8aa3b, v56
	v_exp_f32_e32 v56, v56
	s_nop 0
	v_add_f32_e32 v56, 1.0, v56
	v_rcp_f32_e32 v114, v56
	v_add_f32_e32 v56, v67, v87
	v_max_f32_e64 v57, -v56, 0
	v_mul_f32_e64 v56, |v56|, s57
	v_exp_f32_e32 v56, v56
	s_nop 0
	v_add_f32_e32 v56, 1.0, v56
	v_cmp_gt_f32_e64 s[0:1], s75, v56
	s_nop 1
	v_cndmask_b32_e64 v58, 0, 32, s[0:1]
	v_ldexp_f32 v56, v56, v58
	v_log_f32_e32 v56, v56
	s_nop 0
	v_mul_f32_e32 v58, 0x3f317217, v56
	v_cmp_lt_f32_e64 s[4:5], |v56|, s59
	v_fma_f32 v58, v56, s58, -v58
	v_fmac_f32_e32 v58, 0x3377d1cf, v56
	v_fmac_f32_e32 v58, 0x3f317217, v56
	v_cndmask_b32_e64 v56, v56, v58, s[4:5]
	v_cndmask_b32_e64 v58, 0, v243, s[0:1]
	s_or_b32 s0, s10, 16
	v_sub_f32_e32 v56, v56, v58
	v_lshlrev_b32_e32 v58, 16, v120
	v_add_f32_e32 v56, v57, v56
	v_xor_b32_e32 v82, 0x80000000, v58
	v_and_b32_e32 v57, 0xffff0000, v121
	v_sub_f32_e32 v56, -0.5, v56
	v_xor_b32_e32 v81, 0x80000000, v57
	v_mul_f32_e32 v56, 0x3fb8aa3b, v56
	v_exp_f32_e32 v56, v56
	s_nop 0
	v_mul_f32_e32 v56, 0xbfb8aa3b, v56
	v_exp_f32_e32 v67, v56
	v_add_f32_e32 v56, v59, v83
	v_and_b32_e32 v59, 0xffff0000, v120
	v_mul_f32_e32 v56, 0xbfb8aa3b, v56
	v_xor_b32_e32 v83, 0x80000000, v59
	v_exp_f32_e32 v56, v56
	v_pk_fma_f32 v[82:83], v[0:1], v[122:123], v[82:83]
	v_sub_u32_e32 v233, v44, v232
	ds_write_b128 v233, v[64:67]
	v_pk_fma_f32 v[58:59], v[60:61], v[82:83], v[58:59]
	v_pk_add_f32 v[60:61], v[110:111], -1.0 op_sel_hi:[1,0]
	v_add_f32_e32 v56, 1.0, v56
	s_waitcnt vmcnt(1)
	v_pk_fma_f32 v[60:61], v[76:77], v[60:61], 1.0 op_sel_hi:[1,1,0]
	v_rcp_f32_e32 v115, v56
	v_lshlrev_b32_e32 v56, 16, v121
	v_pk_mul_f32 v[120:121], v[68:69], v[58:59]
	v_pk_mul_f32 v[58:59], v[58:59], v[60:61]
	v_xor_b32_e32 v80, 0x80000000, v56
	v_mul_f32_e32 v60, v140, v58
	s_waitcnt vmcnt(0)
	v_fma_f32 v159, v72, v60, 0
	v_mul_f32_e32 v60, v141, v59
	v_pk_fma_f32 v[80:81], v[100:101], v[128:129], v[80:81]
	v_fmac_f32_e32 v159, v73, v60
	v_pk_add_f32 v[60:61], v[114:115], -1.0 op_sel_hi:[1,0]
	v_pk_fma_f32 v[56:57], v[62:63], v[80:81], v[56:57]
	v_pk_fma_f32 v[60:61], v[78:79], v[60:61], 1.0 op_sel_hi:[1,1,0]
	v_cvt_pk_bf16_f32 v44, v58, v59
	v_pk_mul_f32 v[60:61], v[56:57], v[60:61]
	v_pk_mul_f32 v[122:123], v[70:71], v[56:57]
	v_cvt_pk_bf16_f32 v45, v60, v61
	v_sub_u32_e32 v233, v112, v232
	ds_write_b64 v233, v[44:45] offset:512
	v_or_b32_e32 v44, s0, v180
	v_mul_f32_e32 v62, v138, v60
	v_lshlrev_b32_e32 v2, 7, v44
	v_fmac_f32_e32 v159, v74, v62
	v_mul_f32_e32 v56, v139, v61
	global_store_dwordx2 v[116:117], v[36:37], off
	v_lshl_add_u64 v[36:37], v[88:89], 0, v[2:3]
	v_fmac_f32_e32 v159, v75, v56
	v_lshl_add_u64 v[38:39], v[92:93], 0, v[2:3]
	global_load_dwordx4 v[40:43], v[36:37], off
	global_load_dwordx4 v[56:59], v[38:39], off
	global_load_dwordx4 v[60:63], v[36:37], off offset:64
	global_load_dwordx4 v[68:71], v[38:39], off offset:64
	v_lshlrev_b32_e32 v2, 8, v44
	v_lshl_add_u64 v[36:37], v[94:95], 0, v[2:3]
	v_or_b32_e32 v2, s0, v181
	v_lshlrev_b32_e32 v2, 2, v2
	global_load_dwordx4 v[52:55], v[36:37], off
	global_load_dwordx4 v[48:51], v[36:37], off offset:64
	global_load_dwordx4 v[44:47], v[36:37], off offset:128
	s_nop 0
	global_load_dwordx4 v[36:39], v[36:37], off offset:192
	v_pk_mul_f32 v[128:129], v[120:121], v[120:121]
	v_pk_mul_f32 v[130:131], v[122:123], v[122:123]
	s_waitcnt vmcnt(7)
; __device__ __forceinline__ float sigmoidf_(float x) { return __builtin_amdgcn_rcpf(1.0f + __expf(-x)); }
; __device__ __forceinline__ f32x4 ld_bf4(const bf16_t* q) { const u32x2 u = *(const u32x2*)q; return (f32x4){bflo(u.x), bfhi(u.x), bflo(u.y), bfhi(u.y)}; }
; __device__ __forceinline__ void rwkv_prep_item(const Params& p, const Lt& lt, int l, int item) {
;     ...
;         for (int ct = 0; ct < 4; ++ct) {
;             const int crow = h * 64 + ct * 16 + qi;
;             f32x4 aw = {0.f, 0.f, 0.f, 0.f}, aa = aw, ag = aw;
; #pragma unroll
;             for (int ks = 0; ks < 2; ++ks) {
;                 aw = __builtin_amdgcn_mfma_f32_16x16x32_bf16(*(const bf16x8*)(decT + crow * 64 + ks * 32 + quad * 8), fw[ks], aw, 0, 0, 0);
;                 aa = __builtin_amdgcn_mfma_f32_16x16x32_bf16(*(const bf16x8*)(aT + crow * 64 + ks * 32 + quad * 8), fa[ks], aa, 0, 0, 0);
;             }
; #pragma unroll
;             for (int ks = 0; ks < 4; ++ks) ag = __builtin_amdgcn_mfma_f32_16x16x32_bf16(*(const bf16x8*)(gT + crow * 128 + ks * 32 + quad * 8), fg[ks], ag, 0, 0, 0);
;             const int c = h * 64 + ct * 16 + quad * 4;
;             const f32x4 mr = *(const f32x4*)(mu + c), mk = *(const f32x4*)(mu + COL_K + c), mv = *(const f32x4*)(mu + COL_V + c);
;             const f32x4 cr = ld_bf4(pt + c), ck = ld_bf4(pt + COL_K + c), cv = ld_bf4(pt + COL_V + c);
;             const f32x4 qr = ld_bf4(pp + c) * pm, qk = ld_bf4(pp + COL_K + c) * pm, qv = ld_bf4(pp + COL_V + c) * pm;
;             const f32x4 r = cr + (qr - cr) * mr, k = ck + (qk - ck) * mk, v = cv + (qv - cv) * mv;
;             const f32x4 w0v = *(const f32x4*)(w0 + c), a0v = *(const f32x4*)(a0 + c), kkv = *(const f32x4*)(kkp + c), kav = *(const f32x4*)(kap + c), rkv = *(const f32x4*)(rkp + c);
;             f32x4 dec, a, kk, k2;
; #pragma unroll
;             for (int j = 0; j < 4; ++j) {
;                 const float z = -(w0v[j] + aw[j]);
;                 const float sp = fmaxf(z, 0.f) + __logf(1.0f + __expf(-fabsf(z)));
;                 dec[j] = __expf(-__expf(-sp - 0.5f));
;                 a[j] = sigmoidf_(a0v[j] + aa[j]);
	v_mfma_f32_16x16x32_bf16 v[40:43], v[40:43], v[20:23], 0
	s_waitcnt vmcnt(6)
	v_mfma_f32_16x16x32_bf16 v[56:59], v[56:59], v[28:31], 0
	s_waitcnt vmcnt(5)
	v_mfma_f32_16x16x32_bf16 v[64:67], v[60:63], v[24:27], v[40:43]
	s_waitcnt vmcnt(4)
	v_mfma_f32_16x16x32_bf16 v[60:63], v[68:71], v[32:35], v[56:59]
	global_load_dwordx4 v[68:71], v158, s[8:9] offset:64
	s_nop 2
	global_load_dwordx4 v[56:59], v158, s[8:9] offset:3136
	global_load_dwordx4 v[40:43], v2, s[52:53]
	global_load_dwordx2 v[72:73], v[126:127], off offset:32
	global_load_dwordx2 v[136:137], v[126:127], off offset:1568
	global_load_dwordx2 v[76:77], v[126:127], off offset:3104
	s_waitcnt vmcnt(9)
	v_mfma_f32_16x16x32_bf16 v[52:55], v[52:55], v[4:7], 0
	global_load_dwordx2 v[80:81], v[124:125], off offset:1568
	s_waitcnt vmcnt(3)
	v_lshlrev_b32_e32 v74, 16, v72
	s_waitcnt vmcnt(1)
	v_lshlrev_b32_e32 v144, 16, v76
	v_and_b32_e32 v145, 0xffff0000, v76
	v_lshlrev_b32_e32 v146, 16, v77
	v_and_b32_e32 v147, 0xffff0000, v77
	global_load_dwordx2 v[76:77], v[124:125], off offset:32
	v_and_b32_e32 v75, 0xffff0000, v72
	v_xor_b32_e32 v85, 0x80000000, v75
	v_xor_b32_e32 v84, 0x80000000, v74
	v_lshlrev_b32_e32 v72, 16, v73
	v_and_b32_e32 v73, 0xffff0000, v73
	v_mfma_f32_16x16x32_bf16 v[48:51], v[48:51], v[8:11], v[52:55]
	s_waitcnt vmcnt(1)
	v_lshlrev_b32_e32 v138, 16, v80
	v_and_b32_e32 v139, 0xffff0000, v80
	v_lshlrev_b32_e32 v140, 16, v81
	v_and_b32_e32 v141, 0xffff0000, v81
	global_load_dwordx2 v[80:81], v[124:125], off offset:3104
	v_mfma_f32_16x16x32_bf16 v[44:47], v[44:47], v[12:15], v[48:51]
	s_waitcnt vmcnt(1)
	v_lshlrev_b32_e32 v78, 16, v76
	v_and_b32_e32 v79, 0xffff0000, v76
	v_pk_fma_f32 v[78:79], v[0:1], v[78:79], v[84:85]
	v_lshlrev_b32_e32 v76, 16, v77
	v_and_b32_e32 v77, 0xffff0000, v77
	v_xor_b32_e32 v85, 0x80000000, v73
	v_xor_b32_e32 v84, 0x80000000, v72
	v_pk_fma_f32 v[150:151], v[68:69], v[78:79], v[74:75]
	v_xor_b32_e32 v69, 0x80000000, v145
	v_xor_b32_e32 v68, 0x80000000, v144
	v_pk_fma_f32 v[76:77], v[100:101], v[76:77], v[84:85]
	v_mfma_f32_16x16x32_bf16 v[36:39], v[36:39], v[16:19], v[44:47]
	v_fma_f32 v148, v70, v76, v72
	v_fma_f32 v149, v71, v77, v73
	s_waitcnt vmcnt(0)
	v_lshlrev_b32_e32 v82, 16, v80
	v_and_b32_e32 v83, 0xffff0000, v80
	v_lshlrev_b32_e32 v80, 16, v81
	v_and_b32_e32 v81, 0xffff0000, v81
	v_lshl_add_u64 v[44:45], v[118:119], 0, v[106:107]
	v_cvt_pk_bf16_f32 v36, v36, v37
	v_cvt_pk_bf16_f32 v37, v38, v39
	v_pk_fma_f32 v[152:153], v[0:1], v[82:83], v[68:69]
	v_xor_b32_e32 v69, 0x80000000, v147
	v_xor_b32_e32 v68, 0x80000000, v146
	v_pk_fma_f32 v[154:155], v[100:101], v[80:81], v[68:69]
	global_load_dwordx4 v[84:87], v158, s[42:43] offset:64
	global_load_dwordx4 v[80:83], v158, s[44:45] offset:64
	global_load_dwordx4 v[72:75], v158, s[46:47] offset:64
	global_load_dwordx4 v[76:79], v158, s[48:49] offset:64
	global_load_dwordx4 v[68:71], v158, s[50:51] offset:64
	v_pk_fma_f32 v[40:41], v[40:41], v[152:153], v[144:145]
	v_pk_fma_f32 v[42:43], v[42:43], v[154:155], v[146:147]
	v_cvt_pk_bf16_f32 v40, v40, v41
	v_cvt_pk_bf16_f32 v41, v42, v43
	s_waitcnt vmcnt(4)
	v_add_f32_e32 v2, v64, v84
	v_max_f32_e64 v64, -v2, 0
	v_mul_f32_e64 v2, |v2|, s57
	v_exp_f32_e32 v2, v2
	s_nop 0
	v_add_f32_e32 v2, 1.0, v2
	v_cmp_gt_f32_e64 s[0:1], s75, v2
	s_nop 1
	v_cndmask_b32_e64 v84, 0, 32, s[0:1]
	v_ldexp_f32 v2, v2, v84
	v_log_f32_e32 v2, v2
	s_nop 0
	v_mul_f32_e32 v84, 0x3f317217, v2
	v_cmp_lt_f32_e64 s[4:5], |v2|, s59
	v_fma_f32 v84, v2, s58, -v84
	v_fmac_f32_e32 v84, 0x3377d1cf, v2
	v_fmac_f32_e32 v84, 0x3f317217, v2
	v_cndmask_b32_e64 v2, v2, v84, s[4:5]
	v_cndmask_b32_e64 v84, 0, v243, s[0:1]
	v_sub_f32_e32 v2, v2, v84
	v_add_f32_e32 v2, v64, v2
	v_sub_f32_e32 v2, -0.5, v2
	v_mul_f32_e32 v2, 0x3fb8aa3b, v2
	v_exp_f32_e32 v2, v2
	s_nop 0
	v_mul_f32_e32 v2, 0xbfb8aa3b, v2
	v_exp_f32_e32 v64, v2
	s_waitcnt vmcnt(3)
	v_add_f32_e32 v2, v60, v80
	v_mul_f32_e32 v2, 0xbfb8aa3b, v2
	v_exp_f32_e32 v2, v2
	s_nop 0
	v_add_f32_e32 v2, 1.0, v2
	v_rcp_f32_e32 v132, v2
	v_add_f32_e32 v2, v65, v85
	v_max_f32_e64 v60, -v2, 0
	v_mul_f32_e64 v2, |v2|, s57
	v_exp_f32_e32 v2, v2
	s_nop 0
	v_add_f32_e32 v2, 1.0, v2
	v_cmp_gt_f32_e64 s[0:1], s75, v2
	s_nop 1
	v_cndmask_b32_e64 v65, 0, 32, s[0:1]
	v_ldexp_f32 v2, v2, v65
	v_log_f32_e32 v2, v2
	s_nop 0
	v_mul_f32_e32 v65, 0x3f317217, v2
	v_cmp_lt_f32_e64 s[4:5], |v2|, s59
	v_fma_f32 v65, v2, s58, -v65
	v_fmac_f32_e32 v65, 0x3377d1cf, v2
	v_fmac_f32_e32 v65, 0x3f317217, v2
	v_cndmask_b32_e64 v2, v2, v65, s[4:5]
	v_cndmask_b32_e64 v65, 0, v243, s[0:1]
	v_sub_f32_e32 v2, v2, v65
	v_add_f32_e32 v2, v60, v2
	v_sub_f32_e32 v2, -0.5, v2
	v_mul_f32_e32 v2, 0x3fb8aa3b, v2
	v_exp_f32_e32 v2, v2
	s_nop 0
	v_mul_f32_e32 v2, 0xbfb8aa3b, v2
	v_exp_f32_e32 v65, v2
	v_add_f32_e32 v2, v61, v81
	v_mul_f32_e32 v2, 0xbfb8aa3b, v2
	v_exp_f32_e32 v2, v2
	s_nop 0
	v_add_f32_e32 v2, 1.0, v2
	v_rcp_f32_e32 v133, v2
	v_add_f32_e32 v2, v66, v86
	v_max_f32_e64 v60, -v2, 0
	v_mul_f32_e64 v2, |v2|, s57
	v_exp_f32_e32 v2, v2
	s_nop 0
	v_add_f32_e32 v2, 1.0, v2
	v_cmp_gt_f32_e64 s[0:1], s75, v2
	s_nop 1
	v_cndmask_b32_e64 v61, 0, 32, s[0:1]
	v_ldexp_f32 v2, v2, v61
	v_log_f32_e32 v2, v2
	s_nop 0
	v_mul_f32_e32 v61, 0x3f317217, v2
	v_cmp_lt_f32_e64 s[4:5], |v2|, s59
	v_fma_f32 v61, v2, s58, -v61
	v_fmac_f32_e32 v61, 0x3377d1cf, v2
	v_fmac_f32_e32 v61, 0x3f317217, v2
	v_cndmask_b32_e64 v2, v2, v61, s[4:5]
	v_cndmask_b32_e64 v61, 0, v243, s[0:1]
	v_sub_f32_e32 v2, v2, v61
	v_add_f32_e32 v2, v60, v2
	v_sub_f32_e32 v2, -0.5, v2
	v_mul_f32_e32 v2, 0x3fb8aa3b, v2
	v_exp_f32_e32 v2, v2
	s_nop 0
	v_mul_f32_e32 v2, 0xbfb8aa3b, v2
	v_exp_f32_e32 v66, v2
	v_add_f32_e32 v2, v62, v82
; __device__ __forceinline__ void rwkv_prep_item(const Params& p, const Lt& lt, int l, int item) {
;     ...
;         for (int ct = 0; ct < 4; ++ct) {
;             const int crow = h * 64 + ct * 16 + qi;
;             f32x4 aw = {0.f, 0.f, 0.f, 0.f}, aa = aw, ag = aw;
; #pragma unroll
;             for (int ks = 0; ks < 2; ++ks) {
;                 aw = __builtin_amdgcn_mfma_f32_16x16x32_bf16(*(const bf16x8*)(decT + crow * 64 + ks * 32 + quad * 8), fw[ks], aw, 0, 0, 0);
;                 aa = __builtin_amdgcn_mfma_f32_16x16x32_bf16(*(const bf16x8*)(aT + crow * 64 + ks * 32 + quad * 8), fa[ks], aa, 0, 0, 0);
;             }
; #pragma unroll
;             for (int ks = 0; ks < 4; ++ks) ag = __builtin_amdgcn_mfma_f32_16x16x32_bf16(*(const bf16x8*)(gT + crow * 128 + ks * 32 + quad * 8), fg[ks], ag, 0, 0, 0);
;             const int c = h * 64 + ct * 16 + quad * 4;
;             const f32x4 mr = *(const f32x4*)(mu + c), mk = *(const f32x4*)(mu + COL_K + c), mv = *(const f32x4*)(mu + COL_V + c);
;             const f32x4 cr = ld_bf4(pt + c), ck = ld_bf4(pt + COL_K + c), cv = ld_bf4(pt + COL_V + c);
;             const f32x4 qr = ld_bf4(pp + c) * pm, qk = ld_bf4(pp + COL_K + c) * pm, qv = ld_bf4(pp + COL_V + c) * pm;
;             const f32x4 r = cr + (qr - cr) * mr, k = ck + (qk - ck) * mk, v = cv + (qv - cv) * mv;
;             const f32x4 w0v = *(const f32x4*)(w0 + c), a0v = *(const f32x4*)(a0 + c), kkv = *(const f32x4*)(kkp + c), kav = *(const f32x4*)(kap + c), rkv = *(const f32x4*)(rkp + c);
;             f32x4 dec, a, kk, k2;
; #pragma unroll
;             for (int j = 0; j < 4; ++j) {
;                 const float z = -(w0v[j] + aw[j]);
;                 const float sp = fmaxf(z, 0.f) + __logf(1.0f + __expf(-fabsf(z)));
;                 dec[j] = __expf(-__expf(-sp - 0.5f));
;                 a[j] = sigmoidf_(a0v[j] + aa[j]);
;                 kk[j] = k[j] * kkv[j];
;                 nrm += kk[j] * kk[j];
;                 k2[j] = k[j] * (1.0f + (a[j] - 1.0f) * kav[j]);
;                 bon += r[j] * k2[j] * rkv[j];
;             }
;             va[ct] = a; vkk[ct] = kk;
;             { const int cc = ct * 16 + quad * 4; *(f32x4*)(ob + cc * 4) = dec; st_bf4(ob + 512 + cc * 2, k2); st_bf4(ob + 640 + cc * 2, v); st_bf4(ob + 768 + cc * 2, r); }
;             st_bf4((unsigned char*)((bf16_t*)gate + (size_t)t * RW + c), ag);
	v_lshlrev_b32_e32 v62, 16, v136
	v_mul_f32_e32 v2, 0xbfb8aa3b, v2
	v_xor_b32_e32 v82, 0x80000000, v62
	v_exp_f32_e32 v2, v2
	s_nop 0
	v_add_f32_e32 v2, 1.0, v2
	v_rcp_f32_e32 v134, v2
	v_add_f32_e32 v2, v67, v87
	v_max_f32_e64 v60, -v2, 0
	v_mul_f32_e64 v2, |v2|, s57
	v_exp_f32_e32 v2, v2
	s_nop 0
	v_add_f32_e32 v2, 1.0, v2
	v_cmp_gt_f32_e64 s[0:1], s75, v2
	s_nop 1
	v_cndmask_b32_e64 v61, 0, 32, s[0:1]
	v_ldexp_f32 v2, v2, v61
	v_log_f32_e32 v2, v2
	s_nop 0
	v_mul_f32_e32 v61, 0x3f317217, v2
	v_cmp_lt_f32_e64 s[4:5], |v2|, s59
	v_fma_f32 v61, v2, s58, -v61
	v_fmac_f32_e32 v61, 0x3377d1cf, v2
	v_fmac_f32_e32 v61, 0x3f317217, v2
	v_cndmask_b32_e64 v2, v2, v61, s[4:5]
	v_cndmask_b32_e64 v61, 0, v243, s[0:1]
	s_or_b32 s0, s10, 32
	v_sub_f32_e32 v2, v2, v61
	v_add_f32_e32 v2, v60, v2
	v_sub_f32_e32 v2, -0.5, v2
	v_mul_f32_e32 v2, 0x3fb8aa3b, v2
	v_exp_f32_e32 v2, v2
	v_lshlrev_b32_e32 v60, 16, v137
	v_and_b32_e32 v61, 0xffff0000, v137
	v_xor_b32_e32 v81, 0x80000000, v61
	v_mul_f32_e32 v2, 0xbfb8aa3b, v2
	v_exp_f32_e32 v67, v2
	v_add_f32_e32 v2, v63, v83
	v_mul_f32_e32 v2, 0xbfb8aa3b, v2
	v_exp_f32_e32 v2, v2
	v_and_b32_e32 v63, 0xffff0000, v136
	v_xor_b32_e32 v83, 0x80000000, v63
	v_pk_fma_f32 v[82:83], v[0:1], v[138:139], v[82:83]
	v_add_f32_e32 v2, 1.0, v2
	v_rcp_f32_e32 v135, v2
	v_xor_b32_e32 v80, 0x80000000, v60
	v_pk_fma_f32 v[56:57], v[56:57], v[82:83], v[62:63]
	v_pk_add_f32 v[62:63], v[132:133], -1.0 op_sel_hi:[1,0]
	v_pk_fma_f32 v[80:81], v[100:101], v[140:141], v[80:81]
	s_waitcnt vmcnt(1)
	v_pk_fma_f32 v[62:63], v[76:77], v[62:63], 1.0 op_sel_hi:[1,1,0]
	v_pk_mul_f32 v[136:137], v[72:73], v[56:57]
	v_pk_mul_f32 v[56:57], v[56:57], v[62:63]
	v_pk_fma_f32 v[58:59], v[58:59], v[80:81], v[60:61]
	v_pk_add_f32 v[60:61], v[134:135], -1.0 op_sel_hi:[1,0]
	v_mul_f32_e32 v2, v150, v56
	v_pk_fma_f32 v[60:61], v[78:79], v[60:61], 1.0 op_sel_hi:[1,1,0]
	s_waitcnt vmcnt(0)
	v_fmac_f32_e32 v159, v68, v2
	v_mul_f32_e32 v2, v151, v57
	v_pk_mul_f32 v[60:61], v[58:59], v[60:61]
	v_sub_u32_e32 v233, v44, v232
	ds_write_b128 v233, v[64:67]
	v_lshl_add_u64 v[44:45], v[118:119], 0, v[108:109]
	v_fmac_f32_e32 v159, v69, v2
	v_mul_f32_e32 v2, v148, v60
	v_cvt_pk_bf16_f32 v46, v56, v57
	v_cvt_pk_bf16_f32 v47, v60, v61
	v_sub_u32_e32 v233, v44, v232
	ds_write_b64 v233, v[40:41] offset:640
	v_cvt_pk_bf16_f32 v40, v150, v151
	v_cvt_pk_bf16_f32 v41, v148, v149
	v_fmac_f32_e32 v159, v70, v2
	v_mul_f32_e32 v2, v149, v61
	v_sub_u32_e32 v233, v44, v232
	ds_write_b64 v233, v[46:47] offset:512
	v_sub_u32_e32 v233, v44, v232
	ds_write_b64 v233, v[40:41] offset:768
	v_or_b32_e32 v44, s0, v180
	v_fmac_f32_e32 v159, v71, v2
	v_lshlrev_b32_e32 v2, 7, v44
	global_store_dwordx2 v[116:117], v[36:37], off offset:32
	v_lshl_add_u64 v[36:37], v[88:89], 0, v[2:3]
	v_pk_mul_f32 v[138:139], v[74:75], v[58:59]
	v_lshl_add_u64 v[38:39], v[92:93], 0, v[2:3]
	global_load_dwordx4 v[40:43], v[36:37], off
	global_load_dwordx4 v[56:59], v[38:39], off
	global_load_dwordx4 v[60:63], v[36:37], off offset:64
	global_load_dwordx4 v[68:71], v[38:39], off offset:64
	v_lshlrev_b32_e32 v2, 8, v44
	v_lshl_add_u64 v[36:37], v[94:95], 0, v[2:3]
	v_or_b32_e32 v2, s0, v181
	v_lshlrev_b32_e32 v2, 2, v2
	global_load_dwordx4 v[52:55], v[36:37], off
	global_load_dwordx4 v[48:51], v[36:37], off offset:64
	global_load_dwordx4 v[44:47], v[36:37], off offset:128
	s_nop 0
	global_load_dwordx4 v[36:39], v[36:37], off offset:192
	v_pk_mul_f32 v[140:141], v[136:137], v[136:137]
	v_pk_mul_f32 v[142:143], v[138:139], v[138:139]
	s_waitcnt vmcnt(7)
	v_mfma_f32_16x16x32_bf16 v[40:43], v[40:43], v[20:23], 0
	s_waitcnt vmcnt(6)
	v_mfma_f32_16x16x32_bf16 v[56:59], v[56:59], v[28:31], 0
	s_waitcnt vmcnt(5)
	v_mfma_f32_16x16x32_bf16 v[64:67], v[60:63], v[24:27], v[40:43]
	s_waitcnt vmcnt(4)
	v_mfma_f32_16x16x32_bf16 v[60:63], v[68:71], v[32:35], v[56:59]
	global_load_dwordx4 v[68:71], v158, s[8:9] offset:128
	s_nop 2
	global_load_dwordx4 v[56:59], v158, s[8:9] offset:3200
	global_load_dwordx4 v[40:43], v2, s[52:53]
	global_load_dwordx2 v[72:73], v[126:127], off offset:64
	global_load_dwordx2 v[152:153], v[126:127], off offset:1600
	global_load_dwordx2 v[76:77], v[126:127], off offset:3136
	s_waitcnt vmcnt(9)
	v_mfma_f32_16x16x32_bf16 v[52:55], v[52:55], v[4:7], 0
	global_load_dwordx2 v[80:81], v[124:125], off offset:1600
	s_waitcnt vmcnt(3)
	v_lshlrev_b32_e32 v74, 16, v72
	s_waitcnt vmcnt(1)
	v_lshlrev_b32_e32 v106, 16, v76
	v_and_b32_e32 v107, 0xffff0000, v76
	v_lshlrev_b32_e32 v108, 16, v77
	v_and_b32_e32 v109, 0xffff0000, v77
	global_load_dwordx2 v[76:77], v[124:125], off offset:64
	v_and_b32_e32 v75, 0xffff0000, v72
	v_xor_b32_e32 v85, 0x80000000, v75
	v_xor_b32_e32 v84, 0x80000000, v74
	v_lshlrev_b32_e32 v72, 16, v73
	v_and_b32_e32 v73, 0xffff0000, v73
	v_mfma_f32_16x16x32_bf16 v[48:51], v[48:51], v[8:11], v[52:55]
	s_waitcnt vmcnt(1)
	v_lshlrev_b32_e32 v154, 16, v80
	v_and_b32_e32 v155, 0xffff0000, v80
	v_lshlrev_b32_e32 v156, 16, v81
	v_and_b32_e32 v157, 0xffff0000, v81
	global_load_dwordx2 v[80:81], v[124:125], off offset:3136
	v_mfma_f32_16x16x32_bf16 v[44:47], v[44:47], v[12:15], v[48:51]
	s_waitcnt vmcnt(1)
	v_lshlrev_b32_e32 v78, 16, v76
	v_and_b32_e32 v79, 0xffff0000, v76
	v_pk_fma_f32 v[78:79], v[0:1], v[78:79], v[84:85]
	v_lshlrev_b32_e32 v76, 16, v77
	v_and_b32_e32 v77, 0xffff0000, v77
	v_xor_b32_e32 v85, 0x80000000, v73
	v_xor_b32_e32 v84, 0x80000000, v72
	v_pk_fma_f32 v[146:147], v[68:69], v[78:79], v[74:75]
	v_xor_b32_e32 v69, 0x80000000, v107
	v_xor_b32_e32 v68, 0x80000000, v106
	v_pk_fma_f32 v[76:77], v[100:101], v[76:77], v[84:85]
	v_mfma_f32_16x16x32_bf16 v[36:39], v[36:39], v[16:19], v[44:47]
	v_fma_f32 v144, v70, v76, v72
	v_fma_f32 v145, v71, v77, v73
	s_waitcnt vmcnt(0)
; __device__ __forceinline__ float sigmoidf_(float x) { return __builtin_amdgcn_rcpf(1.0f + __expf(-x)); }
; __device__ __forceinline__ f32x4 ld_bf4(const bf16_t* q) { const u32x2 u = *(const u32x2*)q; return (f32x4){bflo(u.x), bfhi(u.x), bflo(u.y), bfhi(u.y)}; }
; __device__ __forceinline__ void rwkv_prep_item(const Params& p, const Lt& lt, int l, int item) {
;     ...
;         for (int ct = 0; ct < 4; ++ct) {
;             const int crow = h * 64 + ct * 16 + qi;
;             f32x4 aw = {0.f, 0.f, 0.f, 0.f}, aa = aw, ag = aw;
; #pragma unroll
;             for (int ks = 0; ks < 2; ++ks) {
;                 aw = __builtin_amdgcn_mfma_f32_16x16x32_bf16(*(const bf16x8*)(decT + crow * 64 + ks * 32 + quad * 8), fw[ks], aw, 0, 0, 0);
;                 aa = __builtin_amdgcn_mfma_f32_16x16x32_bf16(*(const bf16x8*)(aT + crow * 64 + ks * 32 + quad * 8), fa[ks], aa, 0, 0, 0);
;             }
; #pragma unroll
;             for (int ks = 0; ks < 4; ++ks) ag = __builtin_amdgcn_mfma_f32_16x16x32_bf16(*(const bf16x8*)(gT + crow * 128 + ks * 32 + quad * 8), fg[ks], ag, 0, 0, 0);
;             const int c = h * 64 + ct * 16 + quad * 4;
;             const f32x4 mr = *(const f32x4*)(mu + c), mk = *(const f32x4*)(mu + COL_K + c), mv = *(const f32x4*)(mu + COL_V + c);
;             const f32x4 cr = ld_bf4(pt + c), ck = ld_bf4(pt + COL_K + c), cv = ld_bf4(pt + COL_V + c);
;             const f32x4 qr = ld_bf4(pp + c) * pm, qk = ld_bf4(pp + COL_K + c) * pm, qv = ld_bf4(pp + COL_V + c) * pm;
;             const f32x4 r = cr + (qr - cr) * mr, k = ck + (qk - ck) * mk, v = cv + (qv - cv) * mv;
;             const f32x4 w0v = *(const f32x4*)(w0 + c), a0v = *(const f32x4*)(a0 + c), kkv = *(const f32x4*)(kkp + c), kav = *(const f32x4*)(kap + c), rkv = *(const f32x4*)(rkp + c);
;             f32x4 dec, a, kk, k2;
; #pragma unroll
;             for (int j = 0; j < 4; ++j) {
;                 const float z = -(w0v[j] + aw[j]);
;                 const float sp = fmaxf(z, 0.f) + __logf(1.0f + __expf(-fabsf(z)));
;                 dec[j] = __expf(-__expf(-sp - 0.5f));
;                 a[j] = sigmoidf_(a0v[j] + aa[j]);
;                 kk[j] = k[j] * kkv[j];
;                 nrm += kk[j] * kk[j];
;                 k2[j] = k[j] * (1.0f + (a[j] - 1.0f) * kav[j]);
;                 bon += r[j] * k2[j] * rkv[j];
;             }
	v_lshlrev_b32_e32 v82, 16, v80
	v_and_b32_e32 v83, 0xffff0000, v80
	v_lshlrev_b32_e32 v80, 16, v81
	v_and_b32_e32 v81, 0xffff0000, v81
	v_lshl_add_u64 v[44:45], v[118:119], 0, v[102:103]
	v_cvt_pk_bf16_f32 v36, v36, v37
	v_cvt_pk_bf16_f32 v37, v38, v39
	v_pk_fma_f32 v[148:149], v[0:1], v[82:83], v[68:69]
	v_xor_b32_e32 v69, 0x80000000, v109
	v_xor_b32_e32 v68, 0x80000000, v108
	v_pk_fma_f32 v[150:151], v[100:101], v[80:81], v[68:69]
	global_load_dwordx4 v[84:87], v158, s[42:43] offset:128
	global_load_dwordx4 v[80:83], v158, s[44:45] offset:128
	global_load_dwordx4 v[72:75], v158, s[46:47] offset:128
	global_load_dwordx4 v[76:79], v158, s[48:49] offset:128
	global_load_dwordx4 v[68:71], v158, s[50:51] offset:128
	v_pk_fma_f32 v[40:41], v[40:41], v[148:149], v[106:107]
	v_pk_fma_f32 v[42:43], v[42:43], v[150:151], v[108:109]
	v_cvt_pk_bf16_f32 v40, v40, v41
	v_cvt_pk_bf16_f32 v41, v42, v43
	s_waitcnt vmcnt(4)
	v_add_f32_e32 v2, v64, v84
	v_max_f32_e64 v64, -v2, 0
	v_mul_f32_e64 v2, |v2|, s57
	v_exp_f32_e32 v2, v2
	s_nop 0
	v_add_f32_e32 v2, 1.0, v2
	v_cmp_gt_f32_e64 s[0:1], s75, v2
	s_nop 1
	v_cndmask_b32_e64 v84, 0, 32, s[0:1]
	v_ldexp_f32 v2, v2, v84
	v_log_f32_e32 v2, v2
	s_nop 0
	v_mul_f32_e32 v84, 0x3f317217, v2
	v_cmp_lt_f32_e64 s[4:5], |v2|, s59
	v_fma_f32 v84, v2, s58, -v84
	v_fmac_f32_e32 v84, 0x3377d1cf, v2
	v_fmac_f32_e32 v84, 0x3f317217, v2
	v_cndmask_b32_e64 v2, v2, v84, s[4:5]
	v_cndmask_b32_e64 v84, 0, v243, s[0:1]
	v_sub_f32_e32 v2, v2, v84
	v_add_f32_e32 v2, v64, v2
	v_sub_f32_e32 v2, -0.5, v2
	v_mul_f32_e32 v2, 0x3fb8aa3b, v2
	v_exp_f32_e32 v2, v2
	s_nop 0
	v_mul_f32_e32 v2, 0xbfb8aa3b, v2
	v_exp_f32_e32 v64, v2
	s_waitcnt vmcnt(3)
	v_add_f32_e32 v2, v60, v80
	v_mul_f32_e32 v2, 0xbfb8aa3b, v2
	v_exp_f32_e32 v2, v2
	s_nop 0
	v_add_f32_e32 v2, 1.0, v2
	v_rcp_f32_e32 v80, v2
	v_add_f32_e32 v2, v65, v85
	v_max_f32_e64 v60, -v2, 0
	v_mul_f32_e64 v2, |v2|, s57
	v_exp_f32_e32 v2, v2
	s_nop 0
	v_add_f32_e32 v2, 1.0, v2
	v_cmp_gt_f32_e64 s[0:1], s75, v2
	s_nop 1
	v_cndmask_b32_e64 v65, 0, 32, s[0:1]
	v_ldexp_f32 v2, v2, v65
	v_log_f32_e32 v2, v2
	s_nop 0
	v_mul_f32_e32 v65, 0x3f317217, v2
	v_cmp_lt_f32_e64 s[4:5], |v2|, s59
	v_fma_f32 v65, v2, s58, -v65
	v_fmac_f32_e32 v65, 0x3377d1cf, v2
	v_fmac_f32_e32 v65, 0x3f317217, v2
	v_cndmask_b32_e64 v2, v2, v65, s[4:5]
	v_cndmask_b32_e64 v65, 0, v243, s[0:1]
	v_sub_f32_e32 v2, v2, v65
	v_add_f32_e32 v2, v60, v2
	v_sub_f32_e32 v2, -0.5, v2
	v_mul_f32_e32 v2, 0x3fb8aa3b, v2
	v_exp_f32_e32 v2, v2
	s_nop 0
	v_mul_f32_e32 v2, 0xbfb8aa3b, v2
	v_exp_f32_e32 v65, v2
	v_add_f32_e32 v2, v61, v81
	v_mul_f32_e32 v2, 0xbfb8aa3b, v2
	v_exp_f32_e32 v2, v2
	s_nop 0
	v_add_f32_e32 v2, 1.0, v2
	v_rcp_f32_e32 v81, v2
	v_add_f32_e32 v2, v66, v86
	v_max_f32_e64 v60, -v2, 0
	v_mul_f32_e64 v2, |v2|, s57
	v_exp_f32_e32 v2, v2
	s_nop 0
	v_add_f32_e32 v2, 1.0, v2
	v_cmp_gt_f32_e64 s[0:1], s75, v2
	s_nop 1
	v_cndmask_b32_e64 v61, 0, 32, s[0:1]
	v_ldexp_f32 v2, v2, v61
	v_log_f32_e32 v2, v2
	s_nop 0
	v_mul_f32_e32 v61, 0x3f317217, v2
	v_cmp_lt_f32_e64 s[4:5], |v2|, s59
	v_fma_f32 v61, v2, s58, -v61
	v_fmac_f32_e32 v61, 0x3377d1cf, v2
	v_fmac_f32_e32 v61, 0x3f317217, v2
	v_cndmask_b32_e64 v2, v2, v61, s[4:5]
	v_cndmask_b32_e64 v61, 0, v243, s[0:1]
	v_sub_f32_e32 v2, v2, v61
	v_add_f32_e32 v2, v60, v2
	v_sub_f32_e32 v2, -0.5, v2
	v_mul_f32_e32 v2, 0x3fb8aa3b, v2
	v_exp_f32_e32 v2, v2
	s_nop 0
	v_mul_f32_e32 v2, 0xbfb8aa3b, v2
	v_exp_f32_e32 v66, v2
	v_add_f32_e32 v2, v62, v82
	v_mul_f32_e32 v2, 0xbfb8aa3b, v2
	v_exp_f32_e32 v2, v2
	v_lshlrev_b32_e32 v62, 16, v152
	v_add_f32_e32 v2, 1.0, v2
	v_rcp_f32_e32 v82, v2
	v_add_f32_e32 v2, v67, v87
	v_max_f32_e64 v60, -v2, 0
	v_mul_f32_e64 v2, |v2|, s57
	v_exp_f32_e32 v2, v2
	s_nop 0
	v_add_f32_e32 v2, 1.0, v2
	v_cmp_gt_f32_e64 s[0:1], s75, v2
	s_nop 1
	v_cndmask_b32_e64 v61, 0, 32, s[0:1]
	v_ldexp_f32 v2, v2, v61
	v_log_f32_e32 v2, v2
	s_nop 0
	v_mul_f32_e32 v61, 0x3f317217, v2
	v_fma_f32 v61, v2, s58, -v61
	v_fmac_f32_e32 v61, 0x3377d1cf, v2
	v_fmac_f32_e32 v61, 0x3f317217, v2
	v_cmp_lt_f32_e64 s[4:5], |v2|, s59
	s_nop 1
	v_cndmask_b32_e64 v2, v2, v61, s[4:5]
	v_cndmask_b32_e64 v61, 0, v243, s[0:1]
	v_sub_f32_e32 v2, v2, v61
	v_add_f32_e32 v2, v60, v2
	v_sub_f32_e32 v2, -0.5, v2
	v_mul_f32_e32 v2, 0x3fb8aa3b, v2
	v_exp_f32_e32 v2, v2
	v_lshlrev_b32_e32 v60, 16, v153
	v_and_b32_e32 v61, 0xffff0000, v153
	v_xor_b32_e32 v85, 0x80000000, v61
	v_mul_f32_e32 v2, 0xbfb8aa3b, v2
	v_exp_f32_e32 v67, v2
	v_add_f32_e32 v2, v63, v83
	v_mul_f32_e32 v2, 0xbfb8aa3b, v2
	v_exp_f32_e32 v2, v2
	v_and_b32_e32 v63, 0xffff0000, v152
	v_xor_b32_e32 v84, 0x80000000, v60
	v_pk_fma_f32 v[86:87], v[100:101], v[156:157], v[84:85]
	v_add_f32_e32 v2, 1.0, v2
	v_rcp_f32_e32 v83, v2
	v_xor_b32_e32 v85, 0x80000000, v63
	v_xor_b32_e32 v84, 0x80000000, v62
	v_pk_fma_f32 v[84:85], v[0:1], v[154:155], v[84:85]
	v_pk_fma_f32 v[58:59], v[58:59], v[86:87], v[60:61]
	v_pk_fma_f32 v[56:57], v[56:57], v[84:85], v[62:63]
	v_pk_add_f32 v[62:63], v[80:81], -1.0 op_sel_hi:[1,0]
	s_waitcnt vmcnt(2)
	v_pk_mul_f32 v[72:73], v[72:73], v[56:57]
	s_waitcnt vmcnt(1)
	v_pk_fma_f32 v[62:63], v[76:77], v[62:63], 1.0 op_sel_hi:[1,1,0]
	v_pk_add_f32 v[60:61], v[82:83], -1.0 op_sel_hi:[1,0]
	v_pk_mul_f32 v[56:57], v[56:57], v[62:63]
	v_pk_fma_f32 v[60:61], v[78:79], v[60:61], 1.0 op_sel_hi:[1,1,0]
	v_mul_f32_e32 v2, v146, v56
	s_waitcnt vmcnt(0)
; __device__ __forceinline__ void rwkv_prep_item(const Params& p, const Lt& lt, int l, int item) {
;     ...
;         for (int ct = 0; ct < 4; ++ct) {
;             const int crow = h * 64 + ct * 16 + qi;
;             f32x4 aw = {0.f, 0.f, 0.f, 0.f}, aa = aw, ag = aw;
; #pragma unroll
;             for (int ks = 0; ks < 2; ++ks) {
;                 aw = __builtin_amdgcn_mfma_f32_16x16x32_bf16(*(const bf16x8*)(decT + crow * 64 + ks * 32 + quad * 8), fw[ks], aw, 0, 0, 0);
;                 aa = __builtin_amdgcn_mfma_f32_16x16x32_bf16(*(const bf16x8*)(aT + crow * 64 + ks * 32 + quad * 8), fa[ks], aa, 0, 0, 0);
;             }
; #pragma unroll
;             for (int ks = 0; ks < 4; ++ks) ag = __builtin_amdgcn_mfma_f32_16x16x32_bf16(*(const bf16x8*)(gT + crow * 128 + ks * 32 + quad * 8), fg[ks], ag, 0, 0, 0);
;             const int c = h * 64 + ct * 16 + quad * 4;
;             const f32x4 mr = *(const f32x4*)(mu + c), mk = *(const f32x4*)(mu + COL_K + c), mv = *(const f32x4*)(mu + COL_V + c);
;             const f32x4 cr = ld_bf4(pt + c), ck = ld_bf4(pt + COL_K + c), cv = ld_bf4(pt + COL_V + c);
;             const f32x4 qr = ld_bf4(pp + c) * pm, qk = ld_bf4(pp + COL_K + c) * pm, qv = ld_bf4(pp + COL_V + c) * pm;
;             const f32x4 r = cr + (qr - cr) * mr, k = ck + (qk - ck) * mk, v = cv + (qv - cv) * mv;
;             const f32x4 w0v = *(const f32x4*)(w0 + c), a0v = *(const f32x4*)(a0 + c), kkv = *(const f32x4*)(kkp + c), kav = *(const f32x4*)(kap + c), rkv = *(const f32x4*)(rkp + c);
;             f32x4 dec, a, kk, k2;
; #pragma unroll
;             for (int j = 0; j < 4; ++j) {
;                 const float z = -(w0v[j] + aw[j]);
;                 const float sp = fmaxf(z, 0.f) + __logf(1.0f + __expf(-fabsf(z)));
;                 dec[j] = __expf(-__expf(-sp - 0.5f));
;                 a[j] = sigmoidf_(a0v[j] + aa[j]);
;                 kk[j] = k[j] * kkv[j];
;                 nrm += kk[j] * kk[j];
;                 k2[j] = k[j] * (1.0f + (a[j] - 1.0f) * kav[j]);
;                 bon += r[j] * k2[j] * rkv[j];
;             }
;             va[ct] = a; vkk[ct] = kk;
;             { const int cc = ct * 16 + quad * 4; *(f32x4*)(ob + cc * 4) = dec; st_bf4(ob + 512 + cc * 2, k2); st_bf4(ob + 640 + cc * 2, v); st_bf4(ob + 768 + cc * 2, r); }
;             st_bf4((unsigned char*)((bf16_t*)gate + (size_t)t * RW + c), ag);
	v_fmac_f32_e32 v159, v68, v2
	v_mul_f32_e32 v2, v147, v57
	v_pk_mul_f32 v[60:61], v[58:59], v[60:61]
	v_sub_u32_e32 v233, v44, v232
	ds_write_b128 v233, v[64:67]
	v_lshl_add_u64 v[44:45], v[118:119], 0, v[104:105]
	v_fmac_f32_e32 v159, v69, v2
	v_mul_f32_e32 v2, v144, v60
	v_sub_u32_e32 v233, v44, v232
	ds_write_b64 v233, v[40:41] offset:640
	v_cvt_pk_bf16_f32 v40, v146, v147
	v_cvt_pk_bf16_f32 v41, v144, v145
	s_or_b32 s0, s10, 48
	v_fmac_f32_e32 v159, v70, v2
	v_mul_f32_e32 v2, v145, v61
	v_sub_u32_e32 v233, v44, v232
	ds_write_b64 v233, v[40:41] offset:768
	v_or_b32_e32 v40, s0, v180
	v_fmac_f32_e32 v159, v71, v2
	v_cvt_pk_bf16_f32 v46, v56, v57
	v_cvt_pk_bf16_f32 v47, v60, v61
	v_lshlrev_b32_e32 v2, 7, v40
	v_sub_u32_e32 v233, v44, v232
	ds_write_b64 v233, v[46:47] offset:512
	global_store_dwordx2 v[116:117], v[36:37], off offset:64
	v_lshl_add_u64 v[36:37], v[88:89], 0, v[2:3]
	v_pk_mul_f32 v[74:75], v[74:75], v[58:59]
	v_lshl_add_u64 v[38:39], v[92:93], 0, v[2:3]
	global_load_dwordx4 v[52:55], v[36:37], off
	global_load_dwordx4 v[56:59], v[38:39], off
	global_load_dwordx4 v[60:63], v[36:37], off offset:64
	global_load_dwordx4 v[64:67], v[38:39], off offset:64
	v_lshlrev_b32_e32 v2, 8, v40
	v_lshl_add_u64 v[36:37], v[94:95], 0, v[2:3]
	v_or_b32_e32 v2, s0, v181
	v_lshlrev_b32_e32 v2, 2, v2
	global_load_dwordx4 v[48:51], v[36:37], off
	global_load_dwordx4 v[44:47], v[36:37], off offset:64
	global_load_dwordx4 v[40:43], v[36:37], off offset:128
	s_nop 0
	global_load_dwordx4 v[36:39], v[36:37], off offset:192
	v_pk_mul_f32 v[84:85], v[72:73], v[72:73]
	v_pk_mul_f32 v[76:77], v[74:75], v[74:75]
	s_waitcnt vmcnt(7)
	v_mfma_f32_16x16x32_bf16 v[20:23], v[52:55], v[20:23], 0
	s_waitcnt vmcnt(6)
	v_mfma_f32_16x16x32_bf16 v[28:31], v[56:59], v[28:31], 0
	s_waitcnt vmcnt(5)
	v_mfma_f32_16x16x32_bf16 v[52:55], v[60:63], v[24:27], v[20:23]
	s_waitcnt vmcnt(4)
	v_mfma_f32_16x16x32_bf16 v[28:31], v[64:67], v[32:35], v[28:31]
	global_load_dwordx4 v[32:35], v158, s[8:9] offset:192
	global_load_dwordx4 v[24:27], v158, s[8:9] offset:3264
	global_load_dwordx4 v[20:23], v2, s[52:53]
	global_load_dwordx2 v[56:57], v[126:127], off offset:96
	global_load_dwordx2 v[104:105], v[126:127], off offset:1632
	global_load_dwordx2 v[60:61], v[126:127], off offset:3168
	s_waitcnt vmcnt(9)
	v_mfma_f32_16x16x32_bf16 v[4:7], v[48:51], v[4:7], 0
	global_load_dwordx2 v[64:65], v[124:125], off offset:1632
	s_waitcnt vmcnt(3)
	v_lshlrev_b32_e32 v58, 16, v56
	s_waitcnt vmcnt(1)
	v_lshlrev_b32_e32 v78, 16, v60
	v_and_b32_e32 v79, 0xffff0000, v60
	v_lshlrev_b32_e32 v86, 16, v61
	v_and_b32_e32 v87, 0xffff0000, v61
	global_load_dwordx2 v[60:61], v[124:125], off offset:96
	v_and_b32_e32 v59, 0xffff0000, v56
	v_xor_b32_e32 v69, 0x80000000, v59
	v_xor_b32_e32 v68, 0x80000000, v58
	v_lshlrev_b32_e32 v56, 16, v57
	v_and_b32_e32 v57, 0xffff0000, v57
	v_mfma_f32_16x16x32_bf16 v[4:7], v[44:47], v[8:11], v[4:7]
	s_waitcnt vmcnt(1)
	v_lshlrev_b32_e32 v106, 16, v64
	v_and_b32_e32 v107, 0xffff0000, v64
	v_lshlrev_b32_e32 v108, 16, v65
	v_and_b32_e32 v109, 0xffff0000, v65
	global_load_dwordx2 v[64:65], v[124:125], off offset:3168
	v_mfma_f32_16x16x32_bf16 v[4:7], v[40:43], v[12:15], v[4:7]
	v_lshl_add_u64 v[12:13], v[118:119], 0, v[96:97]
	s_waitcnt vmcnt(1)
	v_lshlrev_b32_e32 v62, 16, v60
	v_and_b32_e32 v63, 0xffff0000, v60
	v_pk_fma_f32 v[62:63], v[0:1], v[62:63], v[68:69]
	v_lshlrev_b32_e32 v60, 16, v61
	v_and_b32_e32 v61, 0xffff0000, v61
	v_xor_b32_e32 v69, 0x80000000, v57
	v_xor_b32_e32 v68, 0x80000000, v56
	v_pk_fma_f32 v[92:93], v[32:33], v[62:63], v[58:59]
	v_xor_b32_e32 v33, 0x80000000, v79
	v_xor_b32_e32 v32, 0x80000000, v78
	v_pk_fma_f32 v[60:61], v[100:101], v[60:61], v[68:69]
	v_mfma_f32_16x16x32_bf16 v[4:7], v[36:39], v[16:19], v[4:7]
	v_fma_f32 v88, v34, v60, v56
	v_fma_f32 v89, v35, v61, v57
	s_waitcnt vmcnt(0)
	v_lshlrev_b32_e32 v66, 16, v64
	v_and_b32_e32 v67, 0xffff0000, v64
	v_lshlrev_b32_e32 v64, 16, v65
	v_and_b32_e32 v65, 0xffff0000, v65
	s_nop 0
	v_cvt_pk_bf16_f32 v4, v4, v5
	v_cvt_pk_bf16_f32 v5, v6, v7
	v_pk_fma_f32 v[94:95], v[0:1], v[66:67], v[32:33]
	v_xor_b32_e32 v33, 0x80000000, v87
	v_xor_b32_e32 v32, 0x80000000, v86
	v_pk_fma_f32 v[102:103], v[100:101], v[64:65], v[32:33]
	global_load_dwordx4 v[60:63], v158, s[42:43] offset:192
	global_load_dwordx4 v[68:71], v158, s[44:45] offset:192
	global_load_dwordx4 v[56:59], v158, s[46:47] offset:192
	global_load_dwordx4 v[64:67], v158, s[48:49] offset:192
	global_load_dwordx4 v[32:35], v158, s[50:51] offset:192
	v_pk_fma_f32 v[10:11], v[20:21], v[94:95], v[78:79]
	v_pk_fma_f32 v[8:9], v[22:23], v[102:103], v[86:87]
	v_cvt_pk_bf16_f32 v10, v10, v11
	v_cvt_pk_bf16_f32 v11, v8, v9
	v_cvt_pk_bf16_f32 v8, v92, v93
	v_cvt_pk_bf16_f32 v9, v88, v89
	s_waitcnt vmcnt(4)
	v_add_f32_e32 v2, v52, v60
	v_max_f32_e64 v52, -v2, 0
	v_mul_f32_e64 v2, |v2|, s57
	v_exp_f32_e32 v2, v2
	s_nop 0
	v_add_f32_e32 v2, 1.0, v2
	v_cmp_gt_f32_e64 s[0:1], s75, v2
	s_nop 1
	v_cndmask_b32_e64 v60, 0, 32, s[0:1]
	v_ldexp_f32 v2, v2, v60
	v_log_f32_e32 v2, v2
	s_nop 0
	v_mul_f32_e32 v60, 0x3f317217, v2
	v_cmp_lt_f32_e64 s[4:5], |v2|, s59
	v_fma_f32 v60, v2, s58, -v60
	v_fmac_f32_e32 v60, 0x3377d1cf, v2
	v_fmac_f32_e32 v60, 0x3f317217, v2
	v_cndmask_b32_e64 v2, v2, v60, s[4:5]
	v_cndmask_b32_e64 v60, 0, v243, s[0:1]
	v_sub_f32_e32 v2, v2, v60
	v_add_f32_e32 v2, v52, v2
	v_sub_f32_e32 v2, -0.5, v2
	v_mul_f32_e32 v2, 0x3fb8aa3b, v2
	v_exp_f32_e32 v2, v2
	s_nop 0
	v_mul_f32_e32 v2, 0xbfb8aa3b, v2
	v_exp_f32_e32 v52, v2
	s_waitcnt vmcnt(3)
; __device__ __forceinline__ float quad_sum(float v) { v += xor16(v); v += xor32(v); return v; }
; __device__ __forceinline__ float sigmoidf_(float x) { return __builtin_amdgcn_rcpf(1.0f + __expf(-x)); }
; __device__ __forceinline__ void st_bf4(unsigned char* q, f32x4 v) { u32x2 w; w.x = cvt_pk_bf16(v[0], v[1]); w.y = cvt_pk_bf16(v[2], v[3]); *(u32x2*)q = w; }
; __device__ __forceinline__ void rwkv_prep_item(const Params& p, const Lt& lt, int l, int item) {
;     ...
; #pragma unroll
;             for (int j = 0; j < 4; ++j) {
;                 const float z = -(w0v[j] + aw[j]);
;                 const float sp = fmaxf(z, 0.f) + __logf(1.0f + __expf(-fabsf(z)));
;                 dec[j] = __expf(-__expf(-sp - 0.5f));
;                 a[j] = sigmoidf_(a0v[j] + aa[j]);
;                 kk[j] = k[j] * kkv[j];
;                 nrm += kk[j] * kk[j];
;                 k2[j] = k[j] * (1.0f + (a[j] - 1.0f) * kav[j]);
;                 bon += r[j] * k2[j] * rkv[j];
;             }
;             va[ct] = a; vkk[ct] = kk;
;             { const int cc = ct * 16 + quad * 4; *(f32x4*)(ob + cc * 4) = dec; st_bf4(ob + 512 + cc * 2, k2); st_bf4(ob + 640 + cc * 2, v); st_bf4(ob + 768 + cc * 2, r); }
;             st_bf4((unsigned char*)((bf16_t*)gate + (size_t)t * RW + c), ag);
;         }
;         nrm = quad_sum(nrm); bon = quad_sum(bon);
	v_add_f32_e32 v2, v28, v68
	v_mul_f32_e32 v2, 0xbfb8aa3b, v2
	v_exp_f32_e32 v2, v2
	s_nop 0
	v_add_f32_e32 v2, 1.0, v2
	v_rcp_f32_e32 v28, v2
	v_add_f32_e32 v2, v53, v61
	v_and_b32_e32 v61, 0xffff0000, v105
	v_max_f32_e64 v53, -v2, 0
	v_mul_f32_e64 v2, |v2|, s57
	v_exp_f32_e32 v2, v2
	s_nop 0
	v_add_f32_e32 v2, 1.0, v2
	v_cmp_gt_f32_e64 s[0:1], s75, v2
	s_nop 1
	v_cndmask_b32_e64 v60, 0, 32, s[0:1]
	v_ldexp_f32 v2, v2, v60
	v_log_f32_e32 v2, v2
	s_nop 0
	v_mul_f32_e32 v60, 0x3f317217, v2
	v_fma_f32 v60, v2, s58, -v60
	v_fmac_f32_e32 v60, 0x3377d1cf, v2
	v_fmac_f32_e32 v60, 0x3f317217, v2
	v_cmp_lt_f32_e64 s[4:5], |v2|, s59
	s_nop 1
	v_cndmask_b32_e64 v2, v2, v60, s[4:5]
	v_cndmask_b32_e64 v60, 0, v243, s[0:1]
	v_sub_f32_e32 v2, v2, v60
	v_add_f32_e32 v2, v53, v2
	v_sub_f32_e32 v2, -0.5, v2
	v_mul_f32_e32 v2, 0x3fb8aa3b, v2
	v_exp_f32_e32 v2, v2
	s_nop 0
	v_mul_f32_e32 v2, 0xbfb8aa3b, v2
	v_exp_f32_e32 v53, v2
	v_add_f32_e32 v2, v29, v69
	v_mul_f32_e32 v2, 0xbfb8aa3b, v2
	v_exp_f32_e32 v2, v2
	v_xor_b32_e32 v69, 0x80000000, v61
	v_add_f32_e32 v2, 1.0, v2
	v_rcp_f32_e32 v29, v2
	v_add_f32_e32 v2, v54, v62
	v_max_f32_e64 v54, -v2, 0
	v_mul_f32_e64 v2, |v2|, s57
	v_exp_f32_e32 v2, v2
	v_lshlrev_b32_e32 v62, 16, v104
	v_add_f32_e32 v2, 1.0, v2
	v_cmp_gt_f32_e64 s[0:1], s75, v2
	s_nop 1
	v_cndmask_b32_e64 v60, 0, 32, s[0:1]
	v_ldexp_f32 v2, v2, v60
	v_log_f32_e32 v2, v2
	s_nop 0
	v_mul_f32_e32 v60, 0x3f317217, v2
	v_fma_f32 v60, v2, s58, -v60
	v_fmac_f32_e32 v60, 0x3377d1cf, v2
	v_fmac_f32_e32 v60, 0x3f317217, v2
	v_cmp_lt_f32_e64 s[4:5], |v2|, s59
	s_nop 1
	v_cndmask_b32_e64 v2, v2, v60, s[4:5]
	v_cndmask_b32_e64 v60, 0, v243, s[0:1]
	v_sub_f32_e32 v2, v2, v60
	v_add_f32_e32 v2, v54, v2
	v_sub_f32_e32 v2, -0.5, v2
	v_mul_f32_e32 v2, 0x3fb8aa3b, v2
	v_exp_f32_e32 v2, v2
	s_nop 0
	v_mul_f32_e32 v2, 0xbfb8aa3b, v2
	v_exp_f32_e32 v54, v2
	v_add_f32_e32 v2, v30, v70
	v_mul_f32_e32 v2, 0xbfb8aa3b, v2
	v_exp_f32_e32 v2, v2
	v_xor_b32_e32 v70, 0x80000000, v62
	v_add_f32_e32 v2, 1.0, v2
	v_rcp_f32_e32 v30, v2
	v_add_f32_e32 v2, v55, v63
	v_max_f32_e64 v55, -v2, 0
	v_mul_f32_e64 v2, |v2|, s57
	v_exp_f32_e32 v2, v2
	v_and_b32_e32 v63, 0xffff0000, v104
	v_add_f32_e32 v2, 1.0, v2
	v_cmp_gt_f32_e64 s[0:1], s75, v2
	s_nop 1
	v_cndmask_b32_e64 v60, 0, 32, s[0:1]
	v_ldexp_f32 v2, v2, v60
	v_log_f32_e32 v2, v2
	s_nop 0
	v_mul_f32_e32 v60, 0x3f317217, v2
	v_fma_f32 v60, v2, s58, -v60
	v_fmac_f32_e32 v60, 0x3377d1cf, v2
	v_fmac_f32_e32 v60, 0x3f317217, v2
	v_cmp_lt_f32_e64 s[4:5], |v2|, s59
	s_nop 1
	v_cndmask_b32_e64 v2, v2, v60, s[4:5]
	v_cndmask_b32_e64 v60, 0, v243, s[0:1]
	v_sub_f32_e32 v2, v2, v60
	v_add_f32_e32 v2, v55, v2
	v_sub_f32_e32 v2, -0.5, v2
	v_mul_f32_e32 v2, 0x3fb8aa3b, v2
	v_exp_f32_e32 v2, v2
	v_lshlrev_b32_e32 v60, 16, v105
	v_xor_b32_e32 v68, 0x80000000, v60
	v_pk_fma_f32 v[68:69], v[100:101], v[108:109], v[68:69]
	v_mul_f32_e32 v2, 0xbfb8aa3b, v2
	v_exp_f32_e32 v55, v2
	v_add_f32_e32 v2, v31, v71
	v_mul_f32_e32 v2, 0xbfb8aa3b, v2
	v_exp_f32_e32 v2, v2
	v_xor_b32_e32 v71, 0x80000000, v63
	v_pk_fma_f32 v[0:1], v[0:1], v[106:107], v[70:71]
	v_sub_u32_e32 v233, v12, v232
	ds_write_b128 v233, v[52:55]
	v_add_f32_e32 v2, 1.0, v2
	v_rcp_f32_e32 v31, v2
	v_pk_fma_f32 v[24:25], v[24:25], v[0:1], v[62:63]
	v_pk_add_f32 v[62:63], v[28:29], -1.0 op_sel_hi:[1,0]
	s_waitcnt vmcnt(2)
	v_pk_mul_f32 v[0:1], v[56:57], v[24:25]
	s_waitcnt vmcnt(1)
	v_pk_fma_f32 v[62:63], v[64:65], v[62:63], 1.0 op_sel_hi:[1,1,0]
	v_pk_mul_f32 v[56:57], v[0:1], v[0:1]
	v_pk_mul_f32 v[62:63], v[24:25], v[62:63]
	v_pk_fma_f32 v[24:25], v[26:27], v[68:69], v[60:61]
	v_pk_add_f32 v[26:27], v[30:31], -1.0 op_sel_hi:[1,0]
	v_mul_f32_e32 v2, v92, v62
	v_pk_fma_f32 v[26:27], v[66:67], v[26:27], 1.0 op_sel_hi:[1,1,0]
	s_waitcnt vmcnt(0)
	v_fmac_f32_e32 v159, v32, v2
	v_mul_f32_e32 v2, v93, v63
	v_pk_mul_f32 v[26:27], v[24:25], v[26:27]
	v_fmac_f32_e32 v159, v33, v2
	v_mul_f32_e32 v2, v88, v26
	v_fmac_f32_e32 v159, v34, v2
	v_add_f32_e32 v2, v128, v129
	v_add_f32_e32 v2, v130, v2
	v_add_f32_e32 v2, v131, v2
	v_add_f32_e32 v2, v2, v140
	v_add_f32_e32 v2, v141, v2
	v_add_f32_e32 v2, v142, v2
	v_add_f32_e32 v2, v143, v2
	v_add_f32_e32 v2, v2, v84
	v_add_f32_e32 v2, v85, v2
	v_add_f32_e32 v2, v76, v2
	v_add_f32_e32 v2, v77, v2
	v_pk_mul_f32 v[24:25], v[58:59], v[24:25]
	v_add_f32_e32 v2, v2, v56
	v_pk_mul_f32 v[32:33], v[24:25], v[24:25]
	v_add_f32_e32 v2, v57, v2
	v_add_f32_e32 v2, v32, v2
	v_add_f32_e32 v2, v33, v2
	v_lshl_add_u64 v[12:13], v[118:119], 0, v[98:99]
	v_cvt_pk_bf16_f32 v14, v62, v63
	v_cvt_pk_bf16_f32 v15, v26, v27
	v_sub_u32_e32 v233, v12, v232
	ds_write_b64 v233, v[14:15] offset:512
	v_sub_u32_e32 v233, v12, v232
	ds_write_b64 v233, v[10:11] offset:640
	v_sub_u32_e32 v233, v12, v232
	ds_write_b64 v233, v[8:9] offset:768
	global_store_dwordx2 v[116:117], v[4:5], off offset:96
	ds_bpermute_b32 v4, v182, v2
	v_mul_f32_e32 v32, v89, v27
	v_fmac_f32_e32 v159, v35, v32
	s_waitcnt lgkmcnt(0)
	v_add_f32_e32 v2, v2, v4
	ds_bpermute_b32 v4, v183, v2
	s_waitcnt lgkmcnt(0)
; __device__ __forceinline__ float quad_sum(float v) { v += xor16(v); v += xor32(v); return v; }
; __device__ __forceinline__ void st_bf4(unsigned char* q, f32x4 v) { u32x2 w; w.x = cvt_pk_bf16(v[0], v[1]); w.y = cvt_pk_bf16(v[2], v[3]); *(u32x2*)q = w; }
; __device__ __forceinline__ void rwkv_prep_item(const Params& p, const Lt& lt, int l, int item) {
;     ...
;         nrm = quad_sum(nrm); bon = quad_sum(bon);
;         const float inv = rsqrtf(fmaxf(nrm, 1e-24f));
; #pragma unroll
;         for (int ct = 0; ct < 4; ++ct) {
;             const int cc = ct * 16 + quad * 4;
;             const f32x4 kkn = vkk[ct] * inv;
;             st_bf4(ob + 256 + cc * 2, -kkn);
;             st_bf4(ob + 384 + cc * 2, kkn * va[ct]);
;         }
;         if (quad == 0) bonus[(size_t)t * 16 + h] = bon;
	v_add_f32_e32 v5, v2, v4
	v_max_f32_e32 v5, 0x179abe15, v5
	v_rsq_f32_e32 v6, v5
	ds_bpermute_b32 v2, v182, v159
	v_pk_mul_f32 v[8:9], v[120:121], v[6:7] op_sel_hi:[1,0]
	v_pk_mul_f32 v[10:11], v[122:123], v[6:7] op_sel_hi:[1,0]
	v_xor_b32_e32 v12, 0x80000000, v9
	v_xor_b32_e32 v5, 0x80000000, v11
	v_xor_b32_e32 v7, 0x80000000, v10
	v_xor_b32_e32 v13, 0x80000000, v8
	v_pk_mul_f32 v[10:11], v[114:115], v[10:11]
	v_pk_mul_f32 v[8:9], v[110:111], v[8:9]
	v_cvt_pk_bf16_f32 v12, v13, v12
	v_cvt_pk_bf16_f32 v8, v8, v9
	v_cvt_pk_bf16_f32 v9, v10, v11
	v_cvt_pk_bf16_f32 v13, v7, v5
	v_sub_u32_e32 v233, v112, v232
	ds_write_b64 v233, v[8:9] offset:384
	v_pk_mul_f32 v[8:9], v[136:137], v[6:7] op_sel_hi:[1,0]
	v_pk_mul_f32 v[10:11], v[138:139], v[6:7] op_sel_hi:[1,0]
	v_sub_u32_e32 v233, v112, v232
	ds_write_b64 v233, v[12:13] offset:256
	v_xor_b32_e32 v5, 0x80000000, v11
	v_xor_b32_e32 v7, 0x80000000, v10
	v_xor_b32_e32 v12, 0x80000000, v9
	v_xor_b32_e32 v13, 0x80000000, v8
	v_pk_mul_f32 v[10:11], v[134:135], v[10:11]
	v_pk_mul_f32 v[8:9], v[132:133], v[8:9]
	s_waitcnt lgkmcnt(0)
	v_add_f32_e32 v2, v159, v2
	v_cvt_pk_bf16_f32 v8, v8, v9
	v_cvt_pk_bf16_f32 v9, v10, v11
	ds_bpermute_b32 v4, v183, v2
	v_cvt_pk_bf16_f32 v12, v13, v12
	v_cvt_pk_bf16_f32 v13, v7, v5
	v_sub_u32_e32 v233, v112, v232
	ds_write_b64 v233, v[8:9] offset:416
	v_pk_mul_f32 v[8:9], v[72:73], v[6:7] op_sel_hi:[1,0]
	v_pk_mul_f32 v[10:11], v[74:75], v[6:7] op_sel_hi:[1,0]
	v_sub_u32_e32 v233, v112, v232
	ds_write_b64 v233, v[12:13] offset:288
	v_xor_b32_e32 v5, 0x80000000, v11
	v_xor_b32_e32 v7, 0x80000000, v10
	v_xor_b32_e32 v12, 0x80000000, v9
	v_xor_b32_e32 v13, 0x80000000, v8
	v_pk_mul_f32 v[10:11], v[82:83], v[10:11]
	v_pk_mul_f32 v[8:9], v[80:81], v[8:9]
	v_cvt_pk_bf16_f32 v12, v13, v12
	v_cvt_pk_bf16_f32 v13, v7, v5
	v_cvt_pk_bf16_f32 v8, v8, v9
	v_cvt_pk_bf16_f32 v9, v10, v11
	v_pk_mul_f32 v[0:1], v[0:1], v[6:7] op_sel_hi:[1,0]
	v_pk_mul_f32 v[6:7], v[24:25], v[6:7] op_sel_hi:[1,0]
	v_sub_u32_e32 v233, v112, v232
	ds_write_b64 v233, v[8:9] offset:448
	v_xor_b32_e32 v5, 0x80000000, v7
	v_xor_b32_e32 v9, 0x80000000, v6
	v_xor_b32_e32 v8, 0x80000000, v1
	v_xor_b32_e32 v10, 0x80000000, v0
	v_pk_mul_f32 v[6:7], v[30:31], v[6:7]
	v_pk_mul_f32 v[0:1], v[28:29], v[0:1]
	v_cvt_pk_bf16_f32 v8, v10, v8
	v_cvt_pk_bf16_f32 v9, v9, v5
	v_cvt_pk_bf16_f32 v0, v0, v1
	v_cvt_pk_bf16_f32 v1, v6, v7
	v_sub_u32_e32 v233, v112, v232
	ds_write_b64 v233, v[12:13] offset:320
	v_sub_u32_e32 v233, v112, v232
	ds_write_b64 v233, v[8:9] offset:352
	v_sub_u32_e32 v233, v112, v232
	ds_write_b64 v233, v[0:1] offset:480
	s_waitcnt lgkmcnt(0)
	s_mov_b32 s98, -1
	s_mov_b32 s99, 0xffffff
	s_mov_b64 exec, s[98:99]
	s_movk_i32 s98, 1792
	s_mov_b32 s99, 0
	v_lshl_add_u64 v[228:229], v[234:235], 0, s[98:99]
	s_movk_i32 s98, 0x2a00
	ds_read_b128 v[210:213], v226 offset:0
	ds_read_b128 v[214:217], v226 offset:912
	ds_read_b128 v[218:221], v226 offset:1824
	ds_read_b128 v[222:225], v226 offset:2736
	s_waitcnt lgkmcnt(3)
	global_store_dwordx4 v[228:229], v[210:213], off
	v_lshl_add_u64 v[228:229], v[228:229], 0, s[98:99]
	s_waitcnt lgkmcnt(2)
	global_store_dwordx4 v[228:229], v[214:217], off
	v_lshl_add_u64 v[228:229], v[228:229], 0, s[98:99]
	s_waitcnt lgkmcnt(1)
	global_store_dwordx4 v[228:229], v[218:221], off
	v_lshl_add_u64 v[228:229], v[228:229], 0, s[98:99]
	s_waitcnt lgkmcnt(0)
	global_store_dwordx4 v[228:229], v[222:225], off
	v_lshl_add_u64 v[228:229], v[228:229], 0, s[98:99]
	ds_read_b128 v[210:213], v226 offset:3648
	ds_read_b128 v[214:217], v226 offset:4560
	ds_read_b128 v[218:221], v226 offset:5472
	ds_read_b128 v[222:225], v226 offset:6384
	s_waitcnt lgkmcnt(3)
	global_store_dwordx4 v[228:229], v[210:213], off
	v_lshl_add_u64 v[228:229], v[228:229], 0, s[98:99]
	s_waitcnt lgkmcnt(2)
	global_store_dwordx4 v[228:229], v[214:217], off
	v_lshl_add_u64 v[228:229], v[228:229], 0, s[98:99]
	s_waitcnt lgkmcnt(1)
	global_store_dwordx4 v[228:229], v[218:221], off
	v_lshl_add_u64 v[228:229], v[228:229], 0, s[98:99]
	s_waitcnt lgkmcnt(0)
	global_store_dwordx4 v[228:229], v[222:225], off
	v_lshl_add_u64 v[228:229], v[228:229], 0, s[98:99]
	ds_read_b128 v[210:213], v226 offset:7296
	ds_read_b128 v[214:217], v226 offset:8208
	ds_read_b128 v[218:221], v226 offset:9120
	ds_read_b128 v[222:225], v226 offset:10032
	s_waitcnt lgkmcnt(3)
	global_store_dwordx4 v[228:229], v[210:213], off
	v_lshl_add_u64 v[228:229], v[228:229], 0, s[98:99]
	s_waitcnt lgkmcnt(2)
	global_store_dwordx4 v[228:229], v[214:217], off
	v_lshl_add_u64 v[228:229], v[228:229], 0, s[98:99]
	s_waitcnt lgkmcnt(1)
	global_store_dwordx4 v[228:229], v[218:221], off
	v_lshl_add_u64 v[228:229], v[228:229], 0, s[98:99]
	s_waitcnt lgkmcnt(0)
	global_store_dwordx4 v[228:229], v[222:225], off
	v_lshl_add_u64 v[228:229], v[228:229], 0, s[98:99]
	ds_read_b128 v[210:213], v226 offset:10944
	ds_read_b128 v[214:217], v226 offset:11856
	ds_read_b128 v[218:221], v226 offset:12768
	ds_read_b128 v[222:225], v226 offset:13680
	s_waitcnt lgkmcnt(3)
	global_store_dwordx4 v[228:229], v[210:213], off
	v_lshl_add_u64 v[228:229], v[228:229], 0, s[98:99]
	s_waitcnt lgkmcnt(2)
	global_store_dwordx4 v[228:229], v[214:217], off
	v_lshl_add_u64 v[228:229], v[228:229], 0, s[98:99]
	s_waitcnt lgkmcnt(1)
	global_store_dwordx4 v[228:229], v[218:221], off
	v_lshl_add_u64 v[228:229], v[228:229], 0, s[98:99]
	s_waitcnt lgkmcnt(0)
	global_store_dwordx4 v[228:229], v[222:225], off
	v_lshl_add_u64 v[228:229], v[228:229], 0, s[98:99]
	s_mov_b64 exec, -1
	s_and_saveexec_b64 s[0:1], vcc
	s_cbranch_execz .LBB0_342
	s_lshl_b32 s10, s56, 2
	v_lshl_add_u64 v[0:1], v[90:91], 0, s[10:11]
	s_waitcnt lgkmcnt(0)
	v_add_f32_e32 v2, v2, v4
	global_store_dword v[0:1], v2, off offset:8
	s_branch .LBB0_342
